# baseline (speedup 1.0000x reference)
; __device__ __forceinline__ int tid_fresh() { int t = (int)threadIdx.x; asm volatile("" : "+v"(t)); return t; }
; __device__ __forceinline__ void conv_phase(const bf16_t* Z, bf16_t* UA, const float* cw, const float* cb, int nrows, int rowoff) {
;     const int gtid = blockIdx.x * 512 + tid_fresh(), NT = gridDim.x * 512; const int total = (nrows / 16) * 352;
;     for (int idx = gtid; idx < total; idx += NT) {
;         const int cgp = idx % 352, rb = idx / 352, c0 = cgp * 8, r0 = rb * 16, grow0 = rowoff + r0;
;         const int seg = grow0 < MLAT ? SEQ : CTXL; const bool has_left = (grow0 & (seg - 1)) != 0, has_right = ((grow0 + 16) & (seg - 1)) != 0;
;         float wa[3][8], wg[3][8], ba[8], bg[8];
; #pragma unroll
;         for (int j = 0; j < 3; ++j)
; #pragma unroll
;             for (int h = 0; h < 2; ++h) { const f32x4 x = *(const f32x4*)(cw + j * FFN2 + c0 + 4 * h), y = *(const f32x4*)(cw + j * FFN2 + FFN + c0 + 4 * h);
; #pragma unroll
;                 for (int e = 0; e < 4; ++e) { wa[j][4 * h + e] = x[e]; wg[j][4 * h + e] = y[e]; } }
; #pragma unroll
;         for (int h = 0; h < 2; ++h) { const f32x4 x = *(const f32x4*)(cb + c0 + 4 * h), y = *(const f32x4*)(cb + FFN + c0 + 4 * h);
; #pragma unroll
;             for (int e = 0; e < 4; ++e) { ba[4 * h + e] = x[e]; bg[4 * h + e] = y[e]; } }
;         const bf16_t* zp = Z + (size_t)r0 * FFN2 + c0; const u32x4 zero = (u32x4){0u, 0u, 0u, 0u};
;         u32x4 pa = zero, pg = zero; if (has_left) { pa = *(const u32x4*)(zp - FFN2); pg = *(const u32x4*)(zp - FFN2 + FFN); }
;         u32x4 ca = *(const u32x4*)(zp), cgv = *(const u32x4*)(zp + FFN);
; #pragma unroll 4
;         for (int rr = 0; rr < 16; ++rr) {
;             u32x4 na = zero, ng = zero; if (rr < 15 || has_right) { na = *(const u32x4*)(zp + (size_t)(rr + 1) * FFN2); ng = *(const u32x4*)(zp + (size_t)(rr + 1) * FFN2 + FFN); }
.LBB0_459:
	s_or_b64 exec, exec, s[2:3]
	v_mov_b32_e32 v1, v204
	v_readlane_b32 s2, v255, 17
	s_lshr_b32 s12, s45, 4
	s_waitcnt lgkmcnt(0)
	s_barrier
	s_mulk_i32 s12, 0x160
	s_xor_b64 s[88:89], s[40:41], -1
	s_lshr_b32 s13, s45, 4
	v_readlane_b32 s2, v254, 21
	v_readlane_b32 s3, v254, 22
	v_readlane_b32 s98, v255, 17
	s_load_dwordx2 s[38:39], s[2:3], 0x98
	s_load_dwordx2 s[40:41], s[2:3], 0xa0
	s_add_u32 s36, s54, 0x23a00000
	s_addc_u32 s37, s55, 0
	v_mov_b32_e32 v180, 0xbfb8aa3b
	v_mov_b32_e32 v181, 0xbfb8aa3b
	v_mov_b32_e32 v144, 1.0
	v_mov_b32_e32 v145, 1.0
	v_add_u32_e32 v1, s98, v204
	s_mov_b32 s99, 0x2e8ba2e9
	v_mul_hi_u32 v2, v1, s99
	v_lshrrev_b32_e32 v2, 6, v2
	v_mul_u32_u24_e32 v3, 0x160, v2
	v_sub_u32_e32 v3, v1, v3
	v_lshlrev_b32_e32 v4, 5, v3
	v_mul_u32_u24_e32 v5, 180224, v2
	v_lshl_add_u32 v5, v3, 4, v5
	v_mul_u32_u24_e32 v6, 90112, v2
	v_lshl_add_u32 v6, v3, 4, v6
	s_lshr_b32 s99, s43, 4
	v_add_u32_e32 v7, s99, v2
	s_waitcnt lgkmcnt(0)
	s_sub_u32 s2, s64, 0x4000
	s_subb_u32 s3, s65, 0
	s_mov_b32 s98, 0
	s_mov_b32 s99, 0xffff0000
	global_load_dwordx4 v[152:155], v4, s[38:39]
	global_load_dwordx4 v[156:159], v4, s[38:39] offset:16
	v_add_u32_e32 v10, 11264, v4
	global_load_dwordx4 v[212:215], v10, s[38:39]
	global_load_dwordx4 v[216:219], v10, s[38:39] offset:16
	v_add_u32_e32 v11, 22528, v4
	global_load_dwordx4 v[160:163], v11, s[38:39]
	global_load_dwordx4 v[164:167], v11, s[38:39] offset:16
	v_add_u32_e32 v10, 33792, v4
	global_load_dwordx4 v[220:223], v10, s[38:39]
	global_load_dwordx4 v[224:227], v10, s[38:39] offset:16
	v_add_u32_e32 v11, 45056, v4
	global_load_dwordx4 v[168:171], v11, s[38:39]
	global_load_dwordx4 v[172:175], v11, s[38:39] offset:16
	v_add_u32_e32 v10, 56320, v4
	global_load_dwordx4 v[228:231], v10, s[38:39]
	global_load_dwordx4 v[232:235], v10, s[38:39] offset:16
	global_load_dwordx4 v[236:239], v4, s[40:41]
	global_load_dwordx4 v[240:243], v4, s[40:41] offset:16
	v_add_u32_e32 v11, 11264, v4
	global_load_dwordx4 v[244:247], v11, s[40:41]
	global_load_dwordx4 v[248:251], v11, s[40:41] offset:16
	v_add_u32_e32 v10, 7936, v5
	global_load_dwordx4 v[64:67], v10, s[2:3] offset:-2816
	global_load_dwordx4 v[68:71], v10, s[2:3] offset:2816
	global_load_dword v252, v4, s[40:41]
	v_add_u32_e32 v11, 19200, v5
	global_load_dwordx4 v[72:75], v11, s[2:3] offset:-2816
	global_load_dwordx4 v[76:79], v11, s[2:3] offset:2816
	global_load_dword v252, v4, s[40:41]
	v_add_u32_e32 v10, 30464, v5
	global_load_dwordx4 v[80:83], v10, s[2:3] offset:-2816
	global_load_dwordx4 v[84:87], v10, s[2:3] offset:2816
	global_load_dword v252, v4, s[40:41]
	v_add_u32_e32 v11, 41728, v5
	global_load_dwordx4 v[88:91], v11, s[2:3] offset:-2816
	global_load_dwordx4 v[92:95], v11, s[2:3] offset:2816
	global_load_dword v252, v4, s[40:41]
	v_add_u32_e32 v10, 52992, v5
	global_load_dwordx4 v[96:99], v10, s[2:3] offset:-2816
	global_load_dwordx4 v[100:103], v10, s[2:3] offset:2816
	global_load_dword v252, v4, s[40:41]
	v_add_u32_e32 v11, 64256, v5
	global_load_dwordx4 v[104:107], v11, s[2:3] offset:-2816
	global_load_dwordx4 v[108:111], v11, s[2:3] offset:2816
	global_load_dword v252, v4, s[40:41]
	v_add_u32_e32 v10, 75520, v5
	global_load_dwordx4 v[112:115], v10, s[2:3] offset:-2816
	global_load_dwordx4 v[116:119], v10, s[2:3] offset:2816
	global_load_dword v252, v4, s[40:41]
	v_add_u32_e32 v11, 86784, v5
	global_load_dwordx4 v[120:123], v11, s[2:3] offset:-2816
	global_load_dwordx4 v[124:127], v11, s[2:3] offset:2816
	global_load_dword v252, v4, s[40:41]
	v_add_u32_e32 v10, 98048, v5
	global_load_dwordx4 v[128:131], v10, s[2:3] offset:-2816
	global_load_dwordx4 v[132:135], v10, s[2:3] offset:2816
	global_load_dword v252, v4, s[40:41]
.Lconv_item_l0:
	v_cmp_gt_u32_e32 vcc, s13, v2
	s_nop 4
	s_cbranch_vccz .Lconv_done_l0
	v_mov_b32_e32 v9, 0x1ff
	v_cmp_gt_u32_e32 vcc, 0x1000, v7
	s_nop 1
	v_cndmask_b32_e32 v8, 15, v9, vcc
	v_and_b32_e32 v9, v7, v8
	v_cmp_ne_u32_e64 s[60:61], 0, v9
	v_add_u32_e32 v9, 1, v7
	v_and_b32_e32 v9, v9, v8
	v_cmp_ne_u32_e64 s[100:101], 0, v9
	s_waitcnt vmcnt(25)
	v_cndmask_b32_e64 v64, 0, v64, s[60:61]
	v_cndmask_b32_e64 v65, 0, v65, s[60:61]
	v_cndmask_b32_e64 v66, 0, v66, s[60:61]
	v_cndmask_b32_e64 v67, 0, v67, s[60:61]
	v_cndmask_b32_e64 v68, 0, v68, s[60:61]
	v_cndmask_b32_e64 v69, 0, v69, s[60:61]
	v_cndmask_b32_e64 v70, 0, v70, s[60:61]
	v_cndmask_b32_e64 v71, 0, v71, s[60:61]
	v_lshlrev_b32_e32 v16, 16, v64
	v_and_b32_e32 v17, s99, v64
	v_lshlrev_b32_e32 v18, 16, v65
	v_and_b32_e32 v19, s99, v65
	v_lshlrev_b32_e32 v20, 16, v66
	v_and_b32_e32 v21, s99, v66
	v_lshlrev_b32_e32 v22, 16, v67
	v_and_b32_e32 v23, s99, v67
	v_lshlrev_b32_e32 v24, 16, v68
	v_and_b32_e32 v25, s99, v68
	v_lshlrev_b32_e32 v26, 16, v69
	v_and_b32_e32 v27, s99, v69
	v_lshlrev_b32_e32 v28, 16, v70
	v_and_b32_e32 v29, s99, v70
	v_lshlrev_b32_e32 v30, 16, v71
	v_and_b32_e32 v31, s99, v71
	v_add_u32_e32 v11, 109312, v5
	global_load_dwordx4 v[64:67], v11, s[2:3] offset:-2816
	global_load_dwordx4 v[68:71], v11, s[2:3] offset:2816
	s_waitcnt vmcnt(24)
	v_lshlrev_b32_e32 v32, 16, v72
	v_and_b32_e32 v33, s99, v72
	v_lshlrev_b32_e32 v34, 16, v73
	v_and_b32_e32 v35, s99, v73
	v_lshlrev_b32_e32 v36, 16, v74
	v_and_b32_e32 v37, s99, v74
	v_lshlrev_b32_e32 v38, 16, v75
	v_and_b32_e32 v39, s99, v75
	v_lshlrev_b32_e32 v40, 16, v76
	v_and_b32_e32 v41, s99, v76
	v_lshlrev_b32_e32 v42, 16, v77
	v_and_b32_e32 v43, s99, v77
	v_lshlrev_b32_e32 v44, 16, v78
	v_and_b32_e32 v45, s99, v78
	v_lshlrev_b32_e32 v46, 16, v79
	v_and_b32_e32 v47, s99, v79
	v_add_u32_e32 v10, 120576, v5
	global_load_dwordx4 v[72:75], v10, s[2:3] offset:-2816
	global_load_dwordx4 v[76:79], v10, s[2:3] offset:2816
	s_waitcnt vmcnt(23)
; __device__ __forceinline__ unsigned cvt_pk_bf16(float lo, float hi) { unsigned r; asm volatile("v_cvt_pk_bf16_f32 %0, %1, %2" : "=v"(r) : "v"(lo), "v"(hi)); return r; }
; __device__ __forceinline__ float silu_f(float x) { return x * __builtin_amdgcn_rcpf(1.0f + __builtin_amdgcn_exp2f(-LOG2E * x)); }
; __device__ __forceinline__ float bflo(unsigned w) { return __uint_as_float(w << 16); }
; __device__ __forceinline__ float bfhi(unsigned w) { return __uint_as_float(w & 0xffff0000u); }
; __device__ __forceinline__ void conv_phase(const bf16_t* Z, bf16_t* UA, const float* cw, const float* cb, int nrows, int rowoff) {
;     ...
;         for (int rr = 0; rr < 16; ++rr) {
;             u32x4 na = zero, ng = zero; if (rr < 15 || has_right) { na = *(const u32x4*)(zp + (size_t)(rr + 1) * FFN2); ng = *(const u32x4*)(zp + (size_t)(rr + 1) * FFN2 + FFN); }
;             u32x4 o;
; #pragma unroll
;             for (int e2 = 0; e2 < 4; ++e2) {
;                 const float a0 = bflo(pa[e2]) * wa[0][2 * e2] + bflo(ca[e2]) * wa[1][2 * e2] + bflo(na[e2]) * wa[2][2 * e2] + ba[2 * e2];
;                 const float a1 = bfhi(pa[e2]) * wa[0][2 * e2 + 1] + bfhi(ca[e2]) * wa[1][2 * e2 + 1] + bfhi(na[e2]) * wa[2][2 * e2 + 1] + ba[2 * e2 + 1];
;                 const float g0 = bflo(pg[e2]) * wg[0][2 * e2] + bflo(cgv[e2]) * wg[1][2 * e2] + bflo(ng[e2]) * wg[2][2 * e2] + bg[2 * e2];
;                 const float g1 = bfhi(pg[e2]) * wg[0][2 * e2 + 1] + bfhi(cgv[e2]) * wg[1][2 * e2 + 1] + bfhi(ng[e2]) * wg[2][2 * e2 + 1] + bg[2 * e2 + 1];
;                 o[e2] = cvt_pk_bf16(silu_f(a0) * g0, silu_f(a1) * g1); }
;             *(u32x4*)(UA + (size_t)(r0 + rr) * FFN + c0) = o;
;             pa = ca; pg = cgv; ca = na; cgv = ng;
	v_lshlrev_b32_e32 v48, 16, v80
	v_and_b32_e32 v49, s99, v80
	v_lshlrev_b32_e32 v50, 16, v81
	v_and_b32_e32 v51, s99, v81
	v_lshlrev_b32_e32 v52, 16, v82
	v_and_b32_e32 v53, s99, v82
	v_lshlrev_b32_e32 v54, 16, v83
	v_and_b32_e32 v55, s99, v83
	v_lshlrev_b32_e32 v56, 16, v84
	v_and_b32_e32 v57, s99, v84
	v_lshlrev_b32_e32 v58, 16, v85
	v_and_b32_e32 v59, s99, v85
	v_lshlrev_b32_e32 v60, 16, v86
	v_and_b32_e32 v61, s99, v86
	v_lshlrev_b32_e32 v62, 16, v87
	v_and_b32_e32 v63, s99, v87
	v_add_u32_e32 v11, 131840, v5
	global_load_dwordx4 v[80:83], v11, s[2:3] offset:-2816
	global_load_dwordx4 v[84:87], v11, s[2:3] offset:2816
	v_pk_fma_f32 v[136:137], v[16:17], v[152:153], v[236:237]
	v_pk_fma_f32 v[196:197], v[24:25], v[212:213], v[244:245]
	v_pk_fma_f32 v[138:139], v[18:19], v[154:155], v[238:239]
	v_pk_fma_f32 v[198:199], v[26:27], v[214:215], v[246:247]
	v_pk_fma_f32 v[140:141], v[20:21], v[156:157], v[240:241]
	v_pk_fma_f32 v[200:201], v[28:29], v[216:217], v[248:249]
	v_pk_fma_f32 v[142:143], v[22:23], v[158:159], v[242:243]
	v_pk_fma_f32 v[202:203], v[30:31], v[218:219], v[250:251]
	v_pk_fma_f32 v[136:137], v[32:33], v[160:161], v[136:137]
	v_pk_fma_f32 v[196:197], v[40:41], v[220:221], v[196:197]
	v_pk_fma_f32 v[138:139], v[34:35], v[162:163], v[138:139]
	v_pk_fma_f32 v[198:199], v[42:43], v[222:223], v[198:199]
	v_pk_fma_f32 v[140:141], v[36:37], v[164:165], v[140:141]
	v_pk_fma_f32 v[200:201], v[44:45], v[224:225], v[200:201]
	v_pk_fma_f32 v[142:143], v[38:39], v[166:167], v[142:143]
	v_pk_fma_f32 v[202:203], v[46:47], v[226:227], v[202:203]
	v_pk_fma_f32 v[136:137], v[48:49], v[168:169], v[136:137]
	v_pk_fma_f32 v[196:197], v[56:57], v[228:229], v[196:197]
	v_pk_fma_f32 v[138:139], v[50:51], v[170:171], v[138:139]
	v_pk_fma_f32 v[198:199], v[58:59], v[230:231], v[198:199]
	v_pk_fma_f32 v[140:141], v[52:53], v[172:173], v[140:141]
	v_pk_fma_f32 v[200:201], v[60:61], v[232:233], v[200:201]
	v_pk_fma_f32 v[142:143], v[54:55], v[174:175], v[142:143]
	v_pk_fma_f32 v[202:203], v[62:63], v[234:235], v[202:203]
	v_pk_mul_f32 v[184:185], v[136:137], v[180:181]
	v_pk_mul_f32 v[186:187], v[138:139], v[180:181]
	v_pk_mul_f32 v[188:189], v[140:141], v[180:181]
	v_pk_mul_f32 v[190:191], v[142:143], v[180:181]
	v_exp_f32_e32 v184, v184
	v_exp_f32_e32 v185, v185
	v_exp_f32_e32 v186, v186
	v_exp_f32_e32 v187, v187
	v_exp_f32_e32 v188, v188
	v_exp_f32_e32 v189, v189
	v_exp_f32_e32 v190, v190
	v_exp_f32_e32 v191, v191
	s_nop 0
	v_pk_add_f32 v[184:185], v[184:185], v[144:145]
	v_pk_add_f32 v[186:187], v[186:187], v[144:145]
	v_pk_add_f32 v[188:189], v[188:189], v[144:145]
	v_pk_add_f32 v[190:191], v[190:191], v[144:145]
	v_rcp_f32_e32 v184, v184
	v_rcp_f32_e32 v185, v185
	v_rcp_f32_e32 v186, v186
	v_rcp_f32_e32 v187, v187
	v_rcp_f32_e32 v188, v188
	v_rcp_f32_e32 v189, v189
	v_rcp_f32_e32 v190, v190
	v_rcp_f32_e32 v191, v191
	s_nop 0
	v_pk_mul_f32 v[136:137], v[136:137], v[184:185]
	v_pk_mul_f32 v[138:139], v[138:139], v[186:187]
	v_pk_mul_f32 v[140:141], v[140:141], v[188:189]
	v_pk_mul_f32 v[142:143], v[142:143], v[190:191]
	v_pk_mul_f32 v[136:137], v[136:137], v[196:197]
	v_pk_mul_f32 v[138:139], v[138:139], v[198:199]
	v_pk_mul_f32 v[140:141], v[140:141], v[200:201]
	v_pk_mul_f32 v[142:143], v[142:143], v[202:203]
	v_cvt_pk_bf16_f32 v12, v136, v137
	v_cvt_pk_bf16_f32 v13, v138, v139
	v_cvt_pk_bf16_f32 v14, v140, v141
	v_cvt_pk_bf16_f32 v15, v142, v143
	global_store_dwordx4 v6, v[12:15], s[36:37]
	v_add_u32_e32 v6, 5632, v6
	s_waitcnt vmcnt(23)
	v_lshlrev_b32_e32 v16, 16, v88
	v_and_b32_e32 v17, s99, v88
	v_lshlrev_b32_e32 v18, 16, v89
	v_and_b32_e32 v19, s99, v89
	v_lshlrev_b32_e32 v20, 16, v90
	v_and_b32_e32 v21, s99, v90
	v_lshlrev_b32_e32 v22, 16, v91
	v_and_b32_e32 v23, s99, v91
	v_lshlrev_b32_e32 v24, 16, v92
	v_and_b32_e32 v25, s99, v92
	v_lshlrev_b32_e32 v26, 16, v93
	v_and_b32_e32 v27, s99, v93
	v_lshlrev_b32_e32 v28, 16, v94
	v_and_b32_e32 v29, s99, v94
	v_lshlrev_b32_e32 v30, 16, v95
	v_and_b32_e32 v31, s99, v95
	v_add_u32_e32 v10, 143104, v5
	global_load_dwordx4 v[88:91], v10, s[2:3] offset:-2816
	global_load_dwordx4 v[92:95], v10, s[2:3] offset:2816
	v_pk_fma_f32 v[136:137], v[32:33], v[152:153], v[236:237]
	v_pk_fma_f32 v[196:197], v[40:41], v[212:213], v[244:245]
	v_pk_fma_f32 v[138:139], v[34:35], v[154:155], v[238:239]
	v_pk_fma_f32 v[198:199], v[42:43], v[214:215], v[246:247]
	v_pk_fma_f32 v[140:141], v[36:37], v[156:157], v[240:241]
	v_pk_fma_f32 v[200:201], v[44:45], v[216:217], v[248:249]
	v_pk_fma_f32 v[142:143], v[38:39], v[158:159], v[242:243]
	v_pk_fma_f32 v[202:203], v[46:47], v[218:219], v[250:251]
	v_pk_fma_f32 v[136:137], v[48:49], v[160:161], v[136:137]
	v_pk_fma_f32 v[196:197], v[56:57], v[220:221], v[196:197]
	v_pk_fma_f32 v[138:139], v[50:51], v[162:163], v[138:139]
	v_pk_fma_f32 v[198:199], v[58:59], v[222:223], v[198:199]
	v_pk_fma_f32 v[140:141], v[52:53], v[164:165], v[140:141]
	v_pk_fma_f32 v[200:201], v[60:61], v[224:225], v[200:201]
	v_pk_fma_f32 v[142:143], v[54:55], v[166:167], v[142:143]
	v_pk_fma_f32 v[202:203], v[62:63], v[226:227], v[202:203]
	v_pk_fma_f32 v[136:137], v[16:17], v[168:169], v[136:137]
	v_pk_fma_f32 v[196:197], v[24:25], v[228:229], v[196:197]
	v_pk_fma_f32 v[138:139], v[18:19], v[170:171], v[138:139]
	v_pk_fma_f32 v[198:199], v[26:27], v[230:231], v[198:199]
	v_pk_fma_f32 v[140:141], v[20:21], v[172:173], v[140:141]
	v_pk_fma_f32 v[200:201], v[28:29], v[232:233], v[200:201]
	v_pk_fma_f32 v[142:143], v[22:23], v[174:175], v[142:143]
	v_pk_fma_f32 v[202:203], v[30:31], v[234:235], v[202:203]
	v_pk_mul_f32 v[184:185], v[136:137], v[180:181]
	v_pk_mul_f32 v[186:187], v[138:139], v[180:181]
	v_pk_mul_f32 v[188:189], v[140:141], v[180:181]
	v_pk_mul_f32 v[190:191], v[142:143], v[180:181]
	v_exp_f32_e32 v184, v184
	v_exp_f32_e32 v185, v185
	v_exp_f32_e32 v186, v186
	v_exp_f32_e32 v187, v187
	v_exp_f32_e32 v188, v188
	v_exp_f32_e32 v189, v189
	v_exp_f32_e32 v190, v190
	v_exp_f32_e32 v191, v191
	s_nop 0
	v_pk_add_f32 v[184:185], v[184:185], v[144:145]
	v_pk_add_f32 v[186:187], v[186:187], v[144:145]
	v_pk_add_f32 v[188:189], v[188:189], v[144:145]
	v_pk_add_f32 v[190:191], v[190:191], v[144:145]
	v_rcp_f32_e32 v184, v184
	v_rcp_f32_e32 v185, v185
	v_rcp_f32_e32 v186, v186
	v_rcp_f32_e32 v187, v187
	v_rcp_f32_e32 v188, v188
	v_rcp_f32_e32 v189, v189
	v_rcp_f32_e32 v190, v190
	v_rcp_f32_e32 v191, v191
	s_nop 0
	v_pk_mul_f32 v[136:137], v[136:137], v[184:185]
	v_pk_mul_f32 v[138:139], v[138:139], v[186:187]
	v_pk_mul_f32 v[140:141], v[140:141], v[188:189]
	v_pk_mul_f32 v[142:143], v[142:143], v[190:191]
	v_pk_mul_f32 v[136:137], v[136:137], v[196:197]
	v_pk_mul_f32 v[138:139], v[138:139], v[198:199]
	v_pk_mul_f32 v[140:141], v[140:141], v[200:201]
	v_pk_mul_f32 v[142:143], v[142:143], v[202:203]
	v_cvt_pk_bf16_f32 v12, v136, v137
	v_cvt_pk_bf16_f32 v13, v138, v139
	v_cvt_pk_bf16_f32 v14, v140, v141
	v_cvt_pk_bf16_f32 v15, v142, v143
	global_store_dwordx4 v6, v[12:15], s[36:37]
	v_add_u32_e32 v6, 5632, v6
	s_waitcnt vmcnt(23)
; __device__ __forceinline__ unsigned cvt_pk_bf16(float lo, float hi) { unsigned r; asm volatile("v_cvt_pk_bf16_f32 %0, %1, %2" : "=v"(r) : "v"(lo), "v"(hi)); return r; }
; __device__ __forceinline__ float silu_f(float x) { return x * __builtin_amdgcn_rcpf(1.0f + __builtin_amdgcn_exp2f(-LOG2E * x)); }
; __device__ __forceinline__ float bflo(unsigned w) { return __uint_as_float(w << 16); }
; __device__ __forceinline__ float bfhi(unsigned w) { return __uint_as_float(w & 0xffff0000u); }
; __device__ __forceinline__ void conv_phase(const bf16_t* Z, bf16_t* UA, const float* cw, const float* cb, int nrows, int rowoff) {
;     ...
;         for (int rr = 0; rr < 16; ++rr) {
;             u32x4 na = zero, ng = zero; if (rr < 15 || has_right) { na = *(const u32x4*)(zp + (size_t)(rr + 1) * FFN2); ng = *(const u32x4*)(zp + (size_t)(rr + 1) * FFN2 + FFN); }
;             u32x4 o;
; #pragma unroll
;             for (int e2 = 0; e2 < 4; ++e2) {
;                 const float a0 = bflo(pa[e2]) * wa[0][2 * e2] + bflo(ca[e2]) * wa[1][2 * e2] + bflo(na[e2]) * wa[2][2 * e2] + ba[2 * e2];
;                 const float a1 = bfhi(pa[e2]) * wa[0][2 * e2 + 1] + bfhi(ca[e2]) * wa[1][2 * e2 + 1] + bfhi(na[e2]) * wa[2][2 * e2 + 1] + ba[2 * e2 + 1];
;                 const float g0 = bflo(pg[e2]) * wg[0][2 * e2] + bflo(cgv[e2]) * wg[1][2 * e2] + bflo(ng[e2]) * wg[2][2 * e2] + bg[2 * e2];
;                 const float g1 = bfhi(pg[e2]) * wg[0][2 * e2 + 1] + bfhi(cgv[e2]) * wg[1][2 * e2 + 1] + bfhi(ng[e2]) * wg[2][2 * e2 + 1] + bg[2 * e2 + 1];
;                 o[e2] = cvt_pk_bf16(silu_f(a0) * g0, silu_f(a1) * g1); }
;             *(u32x4*)(UA + (size_t)(r0 + rr) * FFN + c0) = o;
;             pa = ca; pg = cgv; ca = na; cgv = ng;
	v_lshlrev_b32_e32 v32, 16, v96
	v_and_b32_e32 v33, s99, v96
	v_lshlrev_b32_e32 v34, 16, v97
	v_and_b32_e32 v35, s99, v97
	v_lshlrev_b32_e32 v36, 16, v98
	v_and_b32_e32 v37, s99, v98
	v_lshlrev_b32_e32 v38, 16, v99
	v_and_b32_e32 v39, s99, v99
	v_lshlrev_b32_e32 v40, 16, v100
	v_and_b32_e32 v41, s99, v100
	v_lshlrev_b32_e32 v42, 16, v101
	v_and_b32_e32 v43, s99, v101
	v_lshlrev_b32_e32 v44, 16, v102
	v_and_b32_e32 v45, s99, v102
	v_lshlrev_b32_e32 v46, 16, v103
	v_and_b32_e32 v47, s99, v103
	v_add_u32_e32 v11, 154368, v5
	global_load_dwordx4 v[96:99], v11, s[2:3] offset:-2816
	global_load_dwordx4 v[100:103], v11, s[2:3] offset:2816
	v_pk_fma_f32 v[136:137], v[48:49], v[152:153], v[236:237]
	v_pk_fma_f32 v[196:197], v[56:57], v[212:213], v[244:245]
	v_pk_fma_f32 v[138:139], v[50:51], v[154:155], v[238:239]
	v_pk_fma_f32 v[198:199], v[58:59], v[214:215], v[246:247]
	v_pk_fma_f32 v[140:141], v[52:53], v[156:157], v[240:241]
	v_pk_fma_f32 v[200:201], v[60:61], v[216:217], v[248:249]
	v_pk_fma_f32 v[142:143], v[54:55], v[158:159], v[242:243]
	v_pk_fma_f32 v[202:203], v[62:63], v[218:219], v[250:251]
	v_pk_fma_f32 v[136:137], v[16:17], v[160:161], v[136:137]
	v_pk_fma_f32 v[196:197], v[24:25], v[220:221], v[196:197]
	v_pk_fma_f32 v[138:139], v[18:19], v[162:163], v[138:139]
	v_pk_fma_f32 v[198:199], v[26:27], v[222:223], v[198:199]
	v_pk_fma_f32 v[140:141], v[20:21], v[164:165], v[140:141]
	v_pk_fma_f32 v[200:201], v[28:29], v[224:225], v[200:201]
	v_pk_fma_f32 v[142:143], v[22:23], v[166:167], v[142:143]
	v_pk_fma_f32 v[202:203], v[30:31], v[226:227], v[202:203]
	v_pk_fma_f32 v[136:137], v[32:33], v[168:169], v[136:137]
	v_pk_fma_f32 v[196:197], v[40:41], v[228:229], v[196:197]
	v_pk_fma_f32 v[138:139], v[34:35], v[170:171], v[138:139]
	v_pk_fma_f32 v[198:199], v[42:43], v[230:231], v[198:199]
	v_pk_fma_f32 v[140:141], v[36:37], v[172:173], v[140:141]
	v_pk_fma_f32 v[200:201], v[44:45], v[232:233], v[200:201]
	v_pk_fma_f32 v[142:143], v[38:39], v[174:175], v[142:143]
	v_pk_fma_f32 v[202:203], v[46:47], v[234:235], v[202:203]
	v_pk_mul_f32 v[184:185], v[136:137], v[180:181]
	v_pk_mul_f32 v[186:187], v[138:139], v[180:181]
	v_pk_mul_f32 v[188:189], v[140:141], v[180:181]
	v_pk_mul_f32 v[190:191], v[142:143], v[180:181]
	v_exp_f32_e32 v184, v184
	v_exp_f32_e32 v185, v185
	v_exp_f32_e32 v186, v186
	v_exp_f32_e32 v187, v187
	v_exp_f32_e32 v188, v188
	v_exp_f32_e32 v189, v189
	v_exp_f32_e32 v190, v190
	v_exp_f32_e32 v191, v191
	s_nop 0
	v_pk_add_f32 v[184:185], v[184:185], v[144:145]
	v_pk_add_f32 v[186:187], v[186:187], v[144:145]
	v_pk_add_f32 v[188:189], v[188:189], v[144:145]
	v_pk_add_f32 v[190:191], v[190:191], v[144:145]
	v_rcp_f32_e32 v184, v184
	v_rcp_f32_e32 v185, v185
	v_rcp_f32_e32 v186, v186
	v_rcp_f32_e32 v187, v187
	v_rcp_f32_e32 v188, v188
	v_rcp_f32_e32 v189, v189
	v_rcp_f32_e32 v190, v190
	v_rcp_f32_e32 v191, v191
	s_nop 0
	v_pk_mul_f32 v[136:137], v[136:137], v[184:185]
	v_pk_mul_f32 v[138:139], v[138:139], v[186:187]
	v_pk_mul_f32 v[140:141], v[140:141], v[188:189]
	v_pk_mul_f32 v[142:143], v[142:143], v[190:191]
	v_pk_mul_f32 v[136:137], v[136:137], v[196:197]
	v_pk_mul_f32 v[138:139], v[138:139], v[198:199]
	v_pk_mul_f32 v[140:141], v[140:141], v[200:201]
	v_pk_mul_f32 v[142:143], v[142:143], v[202:203]
	v_cvt_pk_bf16_f32 v12, v136, v137
	v_cvt_pk_bf16_f32 v13, v138, v139
	v_cvt_pk_bf16_f32 v14, v140, v141
	v_cvt_pk_bf16_f32 v15, v142, v143
	global_store_dwordx4 v6, v[12:15], s[36:37]
	v_add_u32_e32 v6, 5632, v6
	s_waitcnt vmcnt(23)
	v_lshlrev_b32_e32 v48, 16, v104
	v_and_b32_e32 v49, s99, v104
	v_lshlrev_b32_e32 v50, 16, v105
	v_and_b32_e32 v51, s99, v105
	v_lshlrev_b32_e32 v52, 16, v106
	v_and_b32_e32 v53, s99, v106
	v_lshlrev_b32_e32 v54, 16, v107
	v_and_b32_e32 v55, s99, v107
	v_lshlrev_b32_e32 v56, 16, v108
	v_and_b32_e32 v57, s99, v108
	v_lshlrev_b32_e32 v58, 16, v109
	v_and_b32_e32 v59, s99, v109
	v_lshlrev_b32_e32 v60, 16, v110
	v_and_b32_e32 v61, s99, v110
	v_lshlrev_b32_e32 v62, 16, v111
	v_and_b32_e32 v63, s99, v111
	v_add_u32_e32 v10, 165632, v5
	global_load_dwordx4 v[104:107], v10, s[2:3] offset:-2816
	global_load_dwordx4 v[108:111], v10, s[2:3] offset:2816
	v_pk_fma_f32 v[136:137], v[16:17], v[152:153], v[236:237]
	v_pk_fma_f32 v[196:197], v[24:25], v[212:213], v[244:245]
	v_pk_fma_f32 v[138:139], v[18:19], v[154:155], v[238:239]
	v_pk_fma_f32 v[198:199], v[26:27], v[214:215], v[246:247]
	v_pk_fma_f32 v[140:141], v[20:21], v[156:157], v[240:241]
	v_pk_fma_f32 v[200:201], v[28:29], v[216:217], v[248:249]
	v_pk_fma_f32 v[142:143], v[22:23], v[158:159], v[242:243]
	v_pk_fma_f32 v[202:203], v[30:31], v[218:219], v[250:251]
	v_pk_fma_f32 v[136:137], v[32:33], v[160:161], v[136:137]
	v_pk_fma_f32 v[196:197], v[40:41], v[220:221], v[196:197]
	v_pk_fma_f32 v[138:139], v[34:35], v[162:163], v[138:139]
	v_pk_fma_f32 v[198:199], v[42:43], v[222:223], v[198:199]
	v_pk_fma_f32 v[140:141], v[36:37], v[164:165], v[140:141]
	v_pk_fma_f32 v[200:201], v[44:45], v[224:225], v[200:201]
	v_pk_fma_f32 v[142:143], v[38:39], v[166:167], v[142:143]
	v_pk_fma_f32 v[202:203], v[46:47], v[226:227], v[202:203]
	v_pk_fma_f32 v[136:137], v[48:49], v[168:169], v[136:137]
	v_pk_fma_f32 v[196:197], v[56:57], v[228:229], v[196:197]
	v_pk_fma_f32 v[138:139], v[50:51], v[170:171], v[138:139]
	v_pk_fma_f32 v[198:199], v[58:59], v[230:231], v[198:199]
	v_pk_fma_f32 v[140:141], v[52:53], v[172:173], v[140:141]
	v_pk_fma_f32 v[200:201], v[60:61], v[232:233], v[200:201]
	v_pk_fma_f32 v[142:143], v[54:55], v[174:175], v[142:143]
	v_pk_fma_f32 v[202:203], v[62:63], v[234:235], v[202:203]
	v_pk_mul_f32 v[184:185], v[136:137], v[180:181]
	v_pk_mul_f32 v[186:187], v[138:139], v[180:181]
	v_pk_mul_f32 v[188:189], v[140:141], v[180:181]
	v_pk_mul_f32 v[190:191], v[142:143], v[180:181]
	v_exp_f32_e32 v184, v184
	v_exp_f32_e32 v185, v185
	v_exp_f32_e32 v186, v186
	v_exp_f32_e32 v187, v187
	v_exp_f32_e32 v188, v188
	v_exp_f32_e32 v189, v189
	v_exp_f32_e32 v190, v190
	v_exp_f32_e32 v191, v191
	s_nop 0
	v_pk_add_f32 v[184:185], v[184:185], v[144:145]
	v_pk_add_f32 v[186:187], v[186:187], v[144:145]
	v_pk_add_f32 v[188:189], v[188:189], v[144:145]
	v_pk_add_f32 v[190:191], v[190:191], v[144:145]
	v_rcp_f32_e32 v184, v184
	v_rcp_f32_e32 v185, v185
	v_rcp_f32_e32 v186, v186
	v_rcp_f32_e32 v187, v187
	v_rcp_f32_e32 v188, v188
	v_rcp_f32_e32 v189, v189
	v_rcp_f32_e32 v190, v190
	v_rcp_f32_e32 v191, v191
	s_nop 0
	v_pk_mul_f32 v[136:137], v[136:137], v[184:185]
	v_pk_mul_f32 v[138:139], v[138:139], v[186:187]
	v_pk_mul_f32 v[140:141], v[140:141], v[188:189]
	v_pk_mul_f32 v[142:143], v[142:143], v[190:191]
	v_pk_mul_f32 v[136:137], v[136:137], v[196:197]
	v_pk_mul_f32 v[138:139], v[138:139], v[198:199]
	v_pk_mul_f32 v[140:141], v[140:141], v[200:201]
	v_pk_mul_f32 v[142:143], v[142:143], v[202:203]
	v_cvt_pk_bf16_f32 v12, v136, v137
	v_cvt_pk_bf16_f32 v13, v138, v139
	v_cvt_pk_bf16_f32 v14, v140, v141
	v_cvt_pk_bf16_f32 v15, v142, v143
	global_store_dwordx4 v6, v[12:15], s[36:37]
	v_add_u32_e32 v6, 5632, v6
	s_waitcnt vmcnt(23)
; __device__ __forceinline__ unsigned cvt_pk_bf16(float lo, float hi) { unsigned r; asm volatile("v_cvt_pk_bf16_f32 %0, %1, %2" : "=v"(r) : "v"(lo), "v"(hi)); return r; }
; __device__ __forceinline__ float silu_f(float x) { return x * __builtin_amdgcn_rcpf(1.0f + __builtin_amdgcn_exp2f(-LOG2E * x)); }
; __device__ __forceinline__ float bflo(unsigned w) { return __uint_as_float(w << 16); }
; __device__ __forceinline__ float bfhi(unsigned w) { return __uint_as_float(w & 0xffff0000u); }
; __device__ __forceinline__ void conv_phase(const bf16_t* Z, bf16_t* UA, const float* cw, const float* cb, int nrows, int rowoff) {
;     ...
;         for (int rr = 0; rr < 16; ++rr) {
;             u32x4 na = zero, ng = zero; if (rr < 15 || has_right) { na = *(const u32x4*)(zp + (size_t)(rr + 1) * FFN2); ng = *(const u32x4*)(zp + (size_t)(rr + 1) * FFN2 + FFN); }
;             u32x4 o;
; #pragma unroll
;             for (int e2 = 0; e2 < 4; ++e2) {
;                 const float a0 = bflo(pa[e2]) * wa[0][2 * e2] + bflo(ca[e2]) * wa[1][2 * e2] + bflo(na[e2]) * wa[2][2 * e2] + ba[2 * e2];
;                 const float a1 = bfhi(pa[e2]) * wa[0][2 * e2 + 1] + bfhi(ca[e2]) * wa[1][2 * e2 + 1] + bfhi(na[e2]) * wa[2][2 * e2 + 1] + ba[2 * e2 + 1];
;                 const float g0 = bflo(pg[e2]) * wg[0][2 * e2] + bflo(cgv[e2]) * wg[1][2 * e2] + bflo(ng[e2]) * wg[2][2 * e2] + bg[2 * e2];
;                 const float g1 = bfhi(pg[e2]) * wg[0][2 * e2 + 1] + bfhi(cgv[e2]) * wg[1][2 * e2 + 1] + bfhi(ng[e2]) * wg[2][2 * e2 + 1] + bg[2 * e2 + 1];
;                 o[e2] = cvt_pk_bf16(silu_f(a0) * g0, silu_f(a1) * g1); }
;             *(u32x4*)(UA + (size_t)(r0 + rr) * FFN + c0) = o;
;             pa = ca; pg = cgv; ca = na; cgv = ng;
	v_lshlrev_b32_e32 v16, 16, v112
	v_and_b32_e32 v17, s99, v112
	v_lshlrev_b32_e32 v18, 16, v113
	v_and_b32_e32 v19, s99, v113
	v_lshlrev_b32_e32 v20, 16, v114
	v_and_b32_e32 v21, s99, v114
	v_lshlrev_b32_e32 v22, 16, v115
	v_and_b32_e32 v23, s99, v115
	v_lshlrev_b32_e32 v24, 16, v116
	v_and_b32_e32 v25, s99, v116
	v_lshlrev_b32_e32 v26, 16, v117
	v_and_b32_e32 v27, s99, v117
	v_lshlrev_b32_e32 v28, 16, v118
	v_and_b32_e32 v29, s99, v118
	v_lshlrev_b32_e32 v30, 16, v119
	v_and_b32_e32 v31, s99, v119
	v_add_u32_e32 v11, 176896, v5
	global_load_dwordx4 v[112:115], v11, s[2:3] offset:-2816
	global_load_dwordx4 v[116:119], v11, s[2:3] offset:2816
	v_pk_fma_f32 v[136:137], v[32:33], v[152:153], v[236:237]
	v_pk_fma_f32 v[196:197], v[40:41], v[212:213], v[244:245]
	v_pk_fma_f32 v[138:139], v[34:35], v[154:155], v[238:239]
	v_pk_fma_f32 v[198:199], v[42:43], v[214:215], v[246:247]
	v_pk_fma_f32 v[140:141], v[36:37], v[156:157], v[240:241]
	v_pk_fma_f32 v[200:201], v[44:45], v[216:217], v[248:249]
	v_pk_fma_f32 v[142:143], v[38:39], v[158:159], v[242:243]
	v_pk_fma_f32 v[202:203], v[46:47], v[218:219], v[250:251]
	v_pk_fma_f32 v[136:137], v[48:49], v[160:161], v[136:137]
	v_pk_fma_f32 v[196:197], v[56:57], v[220:221], v[196:197]
	v_pk_fma_f32 v[138:139], v[50:51], v[162:163], v[138:139]
	v_pk_fma_f32 v[198:199], v[58:59], v[222:223], v[198:199]
	v_pk_fma_f32 v[140:141], v[52:53], v[164:165], v[140:141]
	v_pk_fma_f32 v[200:201], v[60:61], v[224:225], v[200:201]
	v_pk_fma_f32 v[142:143], v[54:55], v[166:167], v[142:143]
	v_pk_fma_f32 v[202:203], v[62:63], v[226:227], v[202:203]
	v_pk_fma_f32 v[136:137], v[16:17], v[168:169], v[136:137]
	v_pk_fma_f32 v[196:197], v[24:25], v[228:229], v[196:197]
	v_pk_fma_f32 v[138:139], v[18:19], v[170:171], v[138:139]
	v_pk_fma_f32 v[198:199], v[26:27], v[230:231], v[198:199]
	v_pk_fma_f32 v[140:141], v[20:21], v[172:173], v[140:141]
	v_pk_fma_f32 v[200:201], v[28:29], v[232:233], v[200:201]
	v_pk_fma_f32 v[142:143], v[22:23], v[174:175], v[142:143]
	v_pk_fma_f32 v[202:203], v[30:31], v[234:235], v[202:203]
	v_pk_mul_f32 v[184:185], v[136:137], v[180:181]
	v_pk_mul_f32 v[186:187], v[138:139], v[180:181]
	v_pk_mul_f32 v[188:189], v[140:141], v[180:181]
	v_pk_mul_f32 v[190:191], v[142:143], v[180:181]
	v_exp_f32_e32 v184, v184
	v_exp_f32_e32 v185, v185
	v_exp_f32_e32 v186, v186
	v_exp_f32_e32 v187, v187
	v_exp_f32_e32 v188, v188
	v_exp_f32_e32 v189, v189
	v_exp_f32_e32 v190, v190
	v_exp_f32_e32 v191, v191
	s_nop 0
	v_pk_add_f32 v[184:185], v[184:185], v[144:145]
	v_pk_add_f32 v[186:187], v[186:187], v[144:145]
	v_pk_add_f32 v[188:189], v[188:189], v[144:145]
	v_pk_add_f32 v[190:191], v[190:191], v[144:145]
	v_rcp_f32_e32 v184, v184
	v_rcp_f32_e32 v185, v185
	v_rcp_f32_e32 v186, v186
	v_rcp_f32_e32 v187, v187
	v_rcp_f32_e32 v188, v188
	v_rcp_f32_e32 v189, v189
	v_rcp_f32_e32 v190, v190
	v_rcp_f32_e32 v191, v191
	s_nop 0
	v_pk_mul_f32 v[136:137], v[136:137], v[184:185]
	v_pk_mul_f32 v[138:139], v[138:139], v[186:187]
	v_pk_mul_f32 v[140:141], v[140:141], v[188:189]
	v_pk_mul_f32 v[142:143], v[142:143], v[190:191]
	v_pk_mul_f32 v[136:137], v[136:137], v[196:197]
	v_pk_mul_f32 v[138:139], v[138:139], v[198:199]
	v_pk_mul_f32 v[140:141], v[140:141], v[200:201]
	v_pk_mul_f32 v[142:143], v[142:143], v[202:203]
	v_cvt_pk_bf16_f32 v12, v136, v137
	v_cvt_pk_bf16_f32 v13, v138, v139
	v_cvt_pk_bf16_f32 v14, v140, v141
	v_cvt_pk_bf16_f32 v15, v142, v143
	global_store_dwordx4 v6, v[12:15], s[36:37]
	v_add_u32_e32 v6, 5632, v6
	s_waitcnt vmcnt(23)
	v_lshlrev_b32_e32 v32, 16, v120
	v_and_b32_e32 v33, s99, v120
	v_lshlrev_b32_e32 v34, 16, v121
	v_and_b32_e32 v35, s99, v121
	v_lshlrev_b32_e32 v36, 16, v122
	v_and_b32_e32 v37, s99, v122
	v_lshlrev_b32_e32 v38, 16, v123
	v_and_b32_e32 v39, s99, v123
	v_lshlrev_b32_e32 v40, 16, v124
	v_and_b32_e32 v41, s99, v124
	v_lshlrev_b32_e32 v42, 16, v125
	v_and_b32_e32 v43, s99, v125
	v_lshlrev_b32_e32 v44, 16, v126
	v_and_b32_e32 v45, s99, v126
	v_lshlrev_b32_e32 v46, 16, v127
	v_and_b32_e32 v47, s99, v127
	v_add_u32_e32 v10, 188160, v5
	global_load_dwordx4 v[120:123], v10, s[2:3] offset:-2816
	global_load_dwordx4 v[124:127], v10, s[2:3] offset:2816
	v_pk_fma_f32 v[136:137], v[48:49], v[152:153], v[236:237]
	v_pk_fma_f32 v[196:197], v[56:57], v[212:213], v[244:245]
	v_pk_fma_f32 v[138:139], v[50:51], v[154:155], v[238:239]
	v_pk_fma_f32 v[198:199], v[58:59], v[214:215], v[246:247]
	v_pk_fma_f32 v[140:141], v[52:53], v[156:157], v[240:241]
	v_pk_fma_f32 v[200:201], v[60:61], v[216:217], v[248:249]
	v_pk_fma_f32 v[142:143], v[54:55], v[158:159], v[242:243]
	v_pk_fma_f32 v[202:203], v[62:63], v[218:219], v[250:251]
	v_pk_fma_f32 v[136:137], v[16:17], v[160:161], v[136:137]
	v_pk_fma_f32 v[196:197], v[24:25], v[220:221], v[196:197]
	v_pk_fma_f32 v[138:139], v[18:19], v[162:163], v[138:139]
	v_pk_fma_f32 v[198:199], v[26:27], v[222:223], v[198:199]
	v_pk_fma_f32 v[140:141], v[20:21], v[164:165], v[140:141]
	v_pk_fma_f32 v[200:201], v[28:29], v[224:225], v[200:201]
	v_pk_fma_f32 v[142:143], v[22:23], v[166:167], v[142:143]
	v_pk_fma_f32 v[202:203], v[30:31], v[226:227], v[202:203]
	v_pk_fma_f32 v[136:137], v[32:33], v[168:169], v[136:137]
	v_pk_fma_f32 v[196:197], v[40:41], v[228:229], v[196:197]
	v_pk_fma_f32 v[138:139], v[34:35], v[170:171], v[138:139]
	v_pk_fma_f32 v[198:199], v[42:43], v[230:231], v[198:199]
	v_pk_fma_f32 v[140:141], v[36:37], v[172:173], v[140:141]
	v_pk_fma_f32 v[200:201], v[44:45], v[232:233], v[200:201]
	v_pk_fma_f32 v[142:143], v[38:39], v[174:175], v[142:143]
	v_pk_fma_f32 v[202:203], v[46:47], v[234:235], v[202:203]
	v_pk_mul_f32 v[184:185], v[136:137], v[180:181]
	v_pk_mul_f32 v[186:187], v[138:139], v[180:181]
	v_pk_mul_f32 v[188:189], v[140:141], v[180:181]
	v_pk_mul_f32 v[190:191], v[142:143], v[180:181]
	v_exp_f32_e32 v184, v184
	v_exp_f32_e32 v185, v185
	v_exp_f32_e32 v186, v186
	v_exp_f32_e32 v187, v187
	v_exp_f32_e32 v188, v188
	v_exp_f32_e32 v189, v189
	v_exp_f32_e32 v190, v190
	v_exp_f32_e32 v191, v191
	s_nop 0
	v_pk_add_f32 v[184:185], v[184:185], v[144:145]
	v_pk_add_f32 v[186:187], v[186:187], v[144:145]
	v_pk_add_f32 v[188:189], v[188:189], v[144:145]
	v_pk_add_f32 v[190:191], v[190:191], v[144:145]
	v_rcp_f32_e32 v184, v184
	v_rcp_f32_e32 v185, v185
	v_rcp_f32_e32 v186, v186
	v_rcp_f32_e32 v187, v187
	v_rcp_f32_e32 v188, v188
	v_rcp_f32_e32 v189, v189
	v_rcp_f32_e32 v190, v190
	v_rcp_f32_e32 v191, v191
	s_nop 0
	v_pk_mul_f32 v[136:137], v[136:137], v[184:185]
	v_pk_mul_f32 v[138:139], v[138:139], v[186:187]
	v_pk_mul_f32 v[140:141], v[140:141], v[188:189]
	v_pk_mul_f32 v[142:143], v[142:143], v[190:191]
	v_pk_mul_f32 v[136:137], v[136:137], v[196:197]
	v_pk_mul_f32 v[138:139], v[138:139], v[198:199]
	v_pk_mul_f32 v[140:141], v[140:141], v[200:201]
	v_pk_mul_f32 v[142:143], v[142:143], v[202:203]
	v_cvt_pk_bf16_f32 v12, v136, v137
	v_cvt_pk_bf16_f32 v13, v138, v139
	v_cvt_pk_bf16_f32 v14, v140, v141
	v_cvt_pk_bf16_f32 v15, v142, v143
	global_store_dwordx4 v6, v[12:15], s[36:37]
	v_add_u32_e32 v6, 5632, v6
	s_waitcnt vmcnt(23)
; __device__ __forceinline__ unsigned cvt_pk_bf16(float lo, float hi) { unsigned r; asm volatile("v_cvt_pk_bf16_f32 %0, %1, %2" : "=v"(r) : "v"(lo), "v"(hi)); return r; }
; __device__ __forceinline__ float silu_f(float x) { return x * __builtin_amdgcn_rcpf(1.0f + __builtin_amdgcn_exp2f(-LOG2E * x)); }
; __device__ __forceinline__ float bflo(unsigned w) { return __uint_as_float(w << 16); }
; __device__ __forceinline__ float bfhi(unsigned w) { return __uint_as_float(w & 0xffff0000u); }
; __device__ __forceinline__ void conv_phase(const bf16_t* Z, bf16_t* UA, const float* cw, const float* cb, int nrows, int rowoff) {
;     ...
;         for (int rr = 0; rr < 16; ++rr) {
;             u32x4 na = zero, ng = zero; if (rr < 15 || has_right) { na = *(const u32x4*)(zp + (size_t)(rr + 1) * FFN2); ng = *(const u32x4*)(zp + (size_t)(rr + 1) * FFN2 + FFN); }
;             u32x4 o;
; #pragma unroll
;             for (int e2 = 0; e2 < 4; ++e2) {
;                 const float a0 = bflo(pa[e2]) * wa[0][2 * e2] + bflo(ca[e2]) * wa[1][2 * e2] + bflo(na[e2]) * wa[2][2 * e2] + ba[2 * e2];
;                 const float a1 = bfhi(pa[e2]) * wa[0][2 * e2 + 1] + bfhi(ca[e2]) * wa[1][2 * e2 + 1] + bfhi(na[e2]) * wa[2][2 * e2 + 1] + ba[2 * e2 + 1];
;                 const float g0 = bflo(pg[e2]) * wg[0][2 * e2] + bflo(cgv[e2]) * wg[1][2 * e2] + bflo(ng[e2]) * wg[2][2 * e2] + bg[2 * e2];
;                 const float g1 = bfhi(pg[e2]) * wg[0][2 * e2 + 1] + bfhi(cgv[e2]) * wg[1][2 * e2 + 1] + bfhi(ng[e2]) * wg[2][2 * e2 + 1] + bg[2 * e2 + 1];
;                 o[e2] = cvt_pk_bf16(silu_f(a0) * g0, silu_f(a1) * g1); }
;             *(u32x4*)(UA + (size_t)(r0 + rr) * FFN + c0) = o;
;             pa = ca; pg = cgv; ca = na; cgv = ng;
	v_lshlrev_b32_e32 v48, 16, v128
	v_and_b32_e32 v49, s99, v128
	v_lshlrev_b32_e32 v50, 16, v129
	v_and_b32_e32 v51, s99, v129
	v_lshlrev_b32_e32 v52, 16, v130
	v_and_b32_e32 v53, s99, v130
	v_lshlrev_b32_e32 v54, 16, v131
	v_and_b32_e32 v55, s99, v131
	v_lshlrev_b32_e32 v56, 16, v132
	v_and_b32_e32 v57, s99, v132
	v_lshlrev_b32_e32 v58, 16, v133
	v_and_b32_e32 v59, s99, v133
	v_lshlrev_b32_e32 v60, 16, v134
	v_and_b32_e32 v61, s99, v134
	v_lshlrev_b32_e32 v62, 16, v135
	v_and_b32_e32 v63, s99, v135
	v_add_u32_e32 v11, 199424, v5
	global_load_dwordx4 v[128:131], v11, s[2:3] offset:-2816
	global_load_dwordx4 v[132:135], v11, s[2:3] offset:2816
	v_pk_fma_f32 v[136:137], v[16:17], v[152:153], v[236:237]
	v_pk_fma_f32 v[196:197], v[24:25], v[212:213], v[244:245]
	v_pk_fma_f32 v[138:139], v[18:19], v[154:155], v[238:239]
	v_pk_fma_f32 v[198:199], v[26:27], v[214:215], v[246:247]
	v_pk_fma_f32 v[140:141], v[20:21], v[156:157], v[240:241]
	v_pk_fma_f32 v[200:201], v[28:29], v[216:217], v[248:249]
	v_pk_fma_f32 v[142:143], v[22:23], v[158:159], v[242:243]
	v_pk_fma_f32 v[202:203], v[30:31], v[218:219], v[250:251]
	v_pk_fma_f32 v[136:137], v[32:33], v[160:161], v[136:137]
	v_pk_fma_f32 v[196:197], v[40:41], v[220:221], v[196:197]
	v_pk_fma_f32 v[138:139], v[34:35], v[162:163], v[138:139]
	v_pk_fma_f32 v[198:199], v[42:43], v[222:223], v[198:199]
	v_pk_fma_f32 v[140:141], v[36:37], v[164:165], v[140:141]
	v_pk_fma_f32 v[200:201], v[44:45], v[224:225], v[200:201]
	v_pk_fma_f32 v[142:143], v[38:39], v[166:167], v[142:143]
	v_pk_fma_f32 v[202:203], v[46:47], v[226:227], v[202:203]
	v_pk_fma_f32 v[136:137], v[48:49], v[168:169], v[136:137]
	v_pk_fma_f32 v[196:197], v[56:57], v[228:229], v[196:197]
	v_pk_fma_f32 v[138:139], v[50:51], v[170:171], v[138:139]
	v_pk_fma_f32 v[198:199], v[58:59], v[230:231], v[198:199]
	v_pk_fma_f32 v[140:141], v[52:53], v[172:173], v[140:141]
	v_pk_fma_f32 v[200:201], v[60:61], v[232:233], v[200:201]
	v_pk_fma_f32 v[142:143], v[54:55], v[174:175], v[142:143]
	v_pk_fma_f32 v[202:203], v[62:63], v[234:235], v[202:203]
	v_pk_mul_f32 v[184:185], v[136:137], v[180:181]
	v_pk_mul_f32 v[186:187], v[138:139], v[180:181]
	v_pk_mul_f32 v[188:189], v[140:141], v[180:181]
	v_pk_mul_f32 v[190:191], v[142:143], v[180:181]
	v_exp_f32_e32 v184, v184
	v_exp_f32_e32 v185, v185
	v_exp_f32_e32 v186, v186
	v_exp_f32_e32 v187, v187
	v_exp_f32_e32 v188, v188
	v_exp_f32_e32 v189, v189
	v_exp_f32_e32 v190, v190
	v_exp_f32_e32 v191, v191
	s_nop 0
	v_pk_add_f32 v[184:185], v[184:185], v[144:145]
	v_pk_add_f32 v[186:187], v[186:187], v[144:145]
	v_pk_add_f32 v[188:189], v[188:189], v[144:145]
	v_pk_add_f32 v[190:191], v[190:191], v[144:145]
	v_rcp_f32_e32 v184, v184
	v_rcp_f32_e32 v185, v185
	v_rcp_f32_e32 v186, v186
	v_rcp_f32_e32 v187, v187
	v_rcp_f32_e32 v188, v188
	v_rcp_f32_e32 v189, v189
	v_rcp_f32_e32 v190, v190
	v_rcp_f32_e32 v191, v191
	s_nop 0
	v_pk_mul_f32 v[136:137], v[136:137], v[184:185]
	v_pk_mul_f32 v[138:139], v[138:139], v[186:187]
	v_pk_mul_f32 v[140:141], v[140:141], v[188:189]
	v_pk_mul_f32 v[142:143], v[142:143], v[190:191]
	v_pk_mul_f32 v[136:137], v[136:137], v[196:197]
	v_pk_mul_f32 v[138:139], v[138:139], v[198:199]
	v_pk_mul_f32 v[140:141], v[140:141], v[200:201]
	v_pk_mul_f32 v[142:143], v[142:143], v[202:203]
	v_cvt_pk_bf16_f32 v12, v136, v137
	v_cvt_pk_bf16_f32 v13, v138, v139
	v_cvt_pk_bf16_f32 v14, v140, v141
	v_cvt_pk_bf16_f32 v15, v142, v143
	global_store_dwordx4 v6, v[12:15], s[36:37]
	v_add_u32_e32 v6, 5632, v6
	s_waitcnt vmcnt(23)
	v_lshlrev_b32_e32 v16, 16, v64
	v_and_b32_e32 v17, s99, v64
	v_lshlrev_b32_e32 v18, 16, v65
	v_and_b32_e32 v19, s99, v65
	v_lshlrev_b32_e32 v20, 16, v66
	v_and_b32_e32 v21, s99, v66
	v_lshlrev_b32_e32 v22, 16, v67
	v_and_b32_e32 v23, s99, v67
	v_lshlrev_b32_e32 v24, 16, v68
	v_and_b32_e32 v25, s99, v68
	v_lshlrev_b32_e32 v26, 16, v69
	v_and_b32_e32 v27, s99, v69
	v_lshlrev_b32_e32 v28, 16, v70
	v_and_b32_e32 v29, s99, v70
	v_lshlrev_b32_e32 v30, 16, v71
	v_and_b32_e32 v31, s99, v71
	v_add_u32_e32 v10, 67051264, v5
	global_load_dwordx4 v[64:67], v10, s[2:3] offset:-2816
	global_load_dwordx4 v[68:71], v10, s[2:3] offset:2816
	v_pk_fma_f32 v[136:137], v[32:33], v[152:153], v[236:237]
	v_pk_fma_f32 v[196:197], v[40:41], v[212:213], v[244:245]
	v_pk_fma_f32 v[138:139], v[34:35], v[154:155], v[238:239]
	v_pk_fma_f32 v[198:199], v[42:43], v[214:215], v[246:247]
	v_pk_fma_f32 v[140:141], v[36:37], v[156:157], v[240:241]
	v_pk_fma_f32 v[200:201], v[44:45], v[216:217], v[248:249]
	v_pk_fma_f32 v[142:143], v[38:39], v[158:159], v[242:243]
	v_pk_fma_f32 v[202:203], v[46:47], v[218:219], v[250:251]
	v_pk_fma_f32 v[136:137], v[48:49], v[160:161], v[136:137]
	v_pk_fma_f32 v[196:197], v[56:57], v[220:221], v[196:197]
	v_pk_fma_f32 v[138:139], v[50:51], v[162:163], v[138:139]
	v_pk_fma_f32 v[198:199], v[58:59], v[222:223], v[198:199]
	v_pk_fma_f32 v[140:141], v[52:53], v[164:165], v[140:141]
	v_pk_fma_f32 v[200:201], v[60:61], v[224:225], v[200:201]
	v_pk_fma_f32 v[142:143], v[54:55], v[166:167], v[142:143]
	v_pk_fma_f32 v[202:203], v[62:63], v[226:227], v[202:203]
	v_pk_fma_f32 v[136:137], v[16:17], v[168:169], v[136:137]
	v_pk_fma_f32 v[196:197], v[24:25], v[228:229], v[196:197]
	v_pk_fma_f32 v[138:139], v[18:19], v[170:171], v[138:139]
	v_pk_fma_f32 v[198:199], v[26:27], v[230:231], v[198:199]
	v_pk_fma_f32 v[140:141], v[20:21], v[172:173], v[140:141]
	v_pk_fma_f32 v[200:201], v[28:29], v[232:233], v[200:201]
	v_pk_fma_f32 v[142:143], v[22:23], v[174:175], v[142:143]
	v_pk_fma_f32 v[202:203], v[30:31], v[234:235], v[202:203]
	v_pk_mul_f32 v[184:185], v[136:137], v[180:181]
	v_pk_mul_f32 v[186:187], v[138:139], v[180:181]
	v_pk_mul_f32 v[188:189], v[140:141], v[180:181]
	v_pk_mul_f32 v[190:191], v[142:143], v[180:181]
	v_exp_f32_e32 v184, v184
	v_exp_f32_e32 v185, v185
	v_exp_f32_e32 v186, v186
	v_exp_f32_e32 v187, v187
	v_exp_f32_e32 v188, v188
	v_exp_f32_e32 v189, v189
	v_exp_f32_e32 v190, v190
	v_exp_f32_e32 v191, v191
	s_nop 0
	v_pk_add_f32 v[184:185], v[184:185], v[144:145]
	v_pk_add_f32 v[186:187], v[186:187], v[144:145]
	v_pk_add_f32 v[188:189], v[188:189], v[144:145]
	v_pk_add_f32 v[190:191], v[190:191], v[144:145]
	v_rcp_f32_e32 v184, v184
	v_rcp_f32_e32 v185, v185
	v_rcp_f32_e32 v186, v186
	v_rcp_f32_e32 v187, v187
	v_rcp_f32_e32 v188, v188
	v_rcp_f32_e32 v189, v189
	v_rcp_f32_e32 v190, v190
	v_rcp_f32_e32 v191, v191
	s_nop 0
	v_pk_mul_f32 v[136:137], v[136:137], v[184:185]
	v_pk_mul_f32 v[138:139], v[138:139], v[186:187]
	v_pk_mul_f32 v[140:141], v[140:141], v[188:189]
	v_pk_mul_f32 v[142:143], v[142:143], v[190:191]
	v_pk_mul_f32 v[136:137], v[136:137], v[196:197]
	v_pk_mul_f32 v[138:139], v[138:139], v[198:199]
	v_pk_mul_f32 v[140:141], v[140:141], v[200:201]
	v_pk_mul_f32 v[142:143], v[142:143], v[202:203]
	v_cvt_pk_bf16_f32 v12, v136, v137
	v_cvt_pk_bf16_f32 v13, v138, v139
	v_cvt_pk_bf16_f32 v14, v140, v141
	v_cvt_pk_bf16_f32 v15, v142, v143
	global_store_dwordx4 v6, v[12:15], s[36:37]
	v_add_u32_e32 v6, 5632, v6
	s_waitcnt vmcnt(24)
; __device__ __forceinline__ unsigned cvt_pk_bf16(float lo, float hi) { unsigned r; asm volatile("v_cvt_pk_bf16_f32 %0, %1, %2" : "=v"(r) : "v"(lo), "v"(hi)); return r; }
; __device__ __forceinline__ float silu_f(float x) { return x * __builtin_amdgcn_rcpf(1.0f + __builtin_amdgcn_exp2f(-LOG2E * x)); }
; __device__ __forceinline__ float bflo(unsigned w) { return __uint_as_float(w << 16); }
; __device__ __forceinline__ float bfhi(unsigned w) { return __uint_as_float(w & 0xffff0000u); }
; __device__ __forceinline__ void conv_phase(const bf16_t* Z, bf16_t* UA, const float* cw, const float* cb, int nrows, int rowoff) {
;     ...
;         for (int rr = 0; rr < 16; ++rr) {
;             u32x4 na = zero, ng = zero; if (rr < 15 || has_right) { na = *(const u32x4*)(zp + (size_t)(rr + 1) * FFN2); ng = *(const u32x4*)(zp + (size_t)(rr + 1) * FFN2 + FFN); }
;             u32x4 o;
; #pragma unroll
;             for (int e2 = 0; e2 < 4; ++e2) {
;                 const float a0 = bflo(pa[e2]) * wa[0][2 * e2] + bflo(ca[e2]) * wa[1][2 * e2] + bflo(na[e2]) * wa[2][2 * e2] + ba[2 * e2];
;                 const float a1 = bfhi(pa[e2]) * wa[0][2 * e2 + 1] + bfhi(ca[e2]) * wa[1][2 * e2 + 1] + bfhi(na[e2]) * wa[2][2 * e2 + 1] + ba[2 * e2 + 1];
;                 const float g0 = bflo(pg[e2]) * wg[0][2 * e2] + bflo(cgv[e2]) * wg[1][2 * e2] + bflo(ng[e2]) * wg[2][2 * e2] + bg[2 * e2];
;                 const float g1 = bfhi(pg[e2]) * wg[0][2 * e2 + 1] + bfhi(cgv[e2]) * wg[1][2 * e2 + 1] + bfhi(ng[e2]) * wg[2][2 * e2 + 1] + bg[2 * e2 + 1];
;                 o[e2] = cvt_pk_bf16(silu_f(a0) * g0, silu_f(a1) * g1); }
;             *(u32x4*)(UA + (size_t)(r0 + rr) * FFN + c0) = o;
;             pa = ca; pg = cgv; ca = na; cgv = ng;
	v_lshlrev_b32_e32 v32, 16, v72
	v_and_b32_e32 v33, s99, v72
	v_lshlrev_b32_e32 v34, 16, v73
	v_and_b32_e32 v35, s99, v73
	v_lshlrev_b32_e32 v36, 16, v74
	v_and_b32_e32 v37, s99, v74
	v_lshlrev_b32_e32 v38, 16, v75
	v_and_b32_e32 v39, s99, v75
	v_lshlrev_b32_e32 v40, 16, v76
	v_and_b32_e32 v41, s99, v76
	v_lshlrev_b32_e32 v42, 16, v77
	v_and_b32_e32 v43, s99, v77
	v_lshlrev_b32_e32 v44, 16, v78
	v_and_b32_e32 v45, s99, v78
	v_lshlrev_b32_e32 v46, 16, v79
	v_and_b32_e32 v47, s99, v79
	v_add_u32_e32 v11, 67062528, v5
	global_load_dwordx4 v[72:75], v11, s[2:3] offset:-2816
	global_load_dwordx4 v[76:79], v11, s[2:3] offset:2816
	v_pk_fma_f32 v[136:137], v[48:49], v[152:153], v[236:237]
	v_pk_fma_f32 v[196:197], v[56:57], v[212:213], v[244:245]
	v_pk_fma_f32 v[138:139], v[50:51], v[154:155], v[238:239]
	v_pk_fma_f32 v[198:199], v[58:59], v[214:215], v[246:247]
	v_pk_fma_f32 v[140:141], v[52:53], v[156:157], v[240:241]
	v_pk_fma_f32 v[200:201], v[60:61], v[216:217], v[248:249]
	v_pk_fma_f32 v[142:143], v[54:55], v[158:159], v[242:243]
	v_pk_fma_f32 v[202:203], v[62:63], v[218:219], v[250:251]
	v_pk_fma_f32 v[136:137], v[16:17], v[160:161], v[136:137]
	v_pk_fma_f32 v[196:197], v[24:25], v[220:221], v[196:197]
	v_pk_fma_f32 v[138:139], v[18:19], v[162:163], v[138:139]
	v_pk_fma_f32 v[198:199], v[26:27], v[222:223], v[198:199]
	v_pk_fma_f32 v[140:141], v[20:21], v[164:165], v[140:141]
	v_pk_fma_f32 v[200:201], v[28:29], v[224:225], v[200:201]
	v_pk_fma_f32 v[142:143], v[22:23], v[166:167], v[142:143]
	v_pk_fma_f32 v[202:203], v[30:31], v[226:227], v[202:203]
	v_pk_fma_f32 v[136:137], v[32:33], v[168:169], v[136:137]
	v_pk_fma_f32 v[196:197], v[40:41], v[228:229], v[196:197]
	v_pk_fma_f32 v[138:139], v[34:35], v[170:171], v[138:139]
	v_pk_fma_f32 v[198:199], v[42:43], v[230:231], v[198:199]
	v_pk_fma_f32 v[140:141], v[36:37], v[172:173], v[140:141]
	v_pk_fma_f32 v[200:201], v[44:45], v[232:233], v[200:201]
	v_pk_fma_f32 v[142:143], v[38:39], v[174:175], v[142:143]
	v_pk_fma_f32 v[202:203], v[46:47], v[234:235], v[202:203]
	v_pk_mul_f32 v[184:185], v[136:137], v[180:181]
	v_pk_mul_f32 v[186:187], v[138:139], v[180:181]
	v_pk_mul_f32 v[188:189], v[140:141], v[180:181]
	v_pk_mul_f32 v[190:191], v[142:143], v[180:181]
	v_exp_f32_e32 v184, v184
	v_exp_f32_e32 v185, v185
	v_exp_f32_e32 v186, v186
	v_exp_f32_e32 v187, v187
	v_exp_f32_e32 v188, v188
	v_exp_f32_e32 v189, v189
	v_exp_f32_e32 v190, v190
	v_exp_f32_e32 v191, v191
	s_nop 0
	v_pk_add_f32 v[184:185], v[184:185], v[144:145]
	v_pk_add_f32 v[186:187], v[186:187], v[144:145]
	v_pk_add_f32 v[188:189], v[188:189], v[144:145]
	v_pk_add_f32 v[190:191], v[190:191], v[144:145]
	v_rcp_f32_e32 v184, v184
	v_rcp_f32_e32 v185, v185
	v_rcp_f32_e32 v186, v186
	v_rcp_f32_e32 v187, v187
	v_rcp_f32_e32 v188, v188
	v_rcp_f32_e32 v189, v189
	v_rcp_f32_e32 v190, v190
	v_rcp_f32_e32 v191, v191
	s_nop 0
	v_pk_mul_f32 v[136:137], v[136:137], v[184:185]
	v_pk_mul_f32 v[138:139], v[138:139], v[186:187]
	v_pk_mul_f32 v[140:141], v[140:141], v[188:189]
	v_pk_mul_f32 v[142:143], v[142:143], v[190:191]
	v_pk_mul_f32 v[136:137], v[136:137], v[196:197]
	v_pk_mul_f32 v[138:139], v[138:139], v[198:199]
	v_pk_mul_f32 v[140:141], v[140:141], v[200:201]
	v_pk_mul_f32 v[142:143], v[142:143], v[202:203]
	v_cvt_pk_bf16_f32 v12, v136, v137
	v_cvt_pk_bf16_f32 v13, v138, v139
	v_cvt_pk_bf16_f32 v14, v140, v141
	v_cvt_pk_bf16_f32 v15, v142, v143
	global_store_dwordx4 v6, v[12:15], s[36:37]
	v_add_u32_e32 v6, 5632, v6
	s_waitcnt vmcnt(25)
	v_lshlrev_b32_e32 v48, 16, v80
	v_and_b32_e32 v49, s99, v80
	v_lshlrev_b32_e32 v50, 16, v81
	v_and_b32_e32 v51, s99, v81
	v_lshlrev_b32_e32 v52, 16, v82
	v_and_b32_e32 v53, s99, v82
	v_lshlrev_b32_e32 v54, 16, v83
	v_and_b32_e32 v55, s99, v83
	v_lshlrev_b32_e32 v56, 16, v84
	v_and_b32_e32 v57, s99, v84
	v_lshlrev_b32_e32 v58, 16, v85
	v_and_b32_e32 v59, s99, v85
	v_lshlrev_b32_e32 v60, 16, v86
	v_and_b32_e32 v61, s99, v86
	v_lshlrev_b32_e32 v62, 16, v87
	v_and_b32_e32 v63, s99, v87
	v_add_u32_e32 v10, 67073792, v5
	global_load_dwordx4 v[80:83], v10, s[2:3] offset:-2816
	global_load_dwordx4 v[84:87], v10, s[2:3] offset:2816
	v_pk_fma_f32 v[136:137], v[16:17], v[152:153], v[236:237]
	v_pk_fma_f32 v[196:197], v[24:25], v[212:213], v[244:245]
	v_pk_fma_f32 v[138:139], v[18:19], v[154:155], v[238:239]
	v_pk_fma_f32 v[198:199], v[26:27], v[214:215], v[246:247]
	v_pk_fma_f32 v[140:141], v[20:21], v[156:157], v[240:241]
	v_pk_fma_f32 v[200:201], v[28:29], v[216:217], v[248:249]
	v_pk_fma_f32 v[142:143], v[22:23], v[158:159], v[242:243]
	v_pk_fma_f32 v[202:203], v[30:31], v[218:219], v[250:251]
	v_pk_fma_f32 v[136:137], v[32:33], v[160:161], v[136:137]
	v_pk_fma_f32 v[196:197], v[40:41], v[220:221], v[196:197]
	v_pk_fma_f32 v[138:139], v[34:35], v[162:163], v[138:139]
	v_pk_fma_f32 v[198:199], v[42:43], v[222:223], v[198:199]
	v_pk_fma_f32 v[140:141], v[36:37], v[164:165], v[140:141]
	v_pk_fma_f32 v[200:201], v[44:45], v[224:225], v[200:201]
	v_pk_fma_f32 v[142:143], v[38:39], v[166:167], v[142:143]
	v_pk_fma_f32 v[202:203], v[46:47], v[226:227], v[202:203]
	v_pk_fma_f32 v[136:137], v[48:49], v[168:169], v[136:137]
	v_pk_fma_f32 v[196:197], v[56:57], v[228:229], v[196:197]
	v_pk_fma_f32 v[138:139], v[50:51], v[170:171], v[138:139]
	v_pk_fma_f32 v[198:199], v[58:59], v[230:231], v[198:199]
	v_pk_fma_f32 v[140:141], v[52:53], v[172:173], v[140:141]
	v_pk_fma_f32 v[200:201], v[60:61], v[232:233], v[200:201]
	v_pk_fma_f32 v[142:143], v[54:55], v[174:175], v[142:143]
	v_pk_fma_f32 v[202:203], v[62:63], v[234:235], v[202:203]
	v_pk_mul_f32 v[184:185], v[136:137], v[180:181]
	v_pk_mul_f32 v[186:187], v[138:139], v[180:181]
	v_pk_mul_f32 v[188:189], v[140:141], v[180:181]
	v_pk_mul_f32 v[190:191], v[142:143], v[180:181]
	v_exp_f32_e32 v184, v184
	v_exp_f32_e32 v185, v185
	v_exp_f32_e32 v186, v186
	v_exp_f32_e32 v187, v187
	v_exp_f32_e32 v188, v188
	v_exp_f32_e32 v189, v189
	v_exp_f32_e32 v190, v190
	v_exp_f32_e32 v191, v191
	s_nop 0
	v_pk_add_f32 v[184:185], v[184:185], v[144:145]
	v_pk_add_f32 v[186:187], v[186:187], v[144:145]
	v_pk_add_f32 v[188:189], v[188:189], v[144:145]
	v_pk_add_f32 v[190:191], v[190:191], v[144:145]
	v_rcp_f32_e32 v184, v184
	v_rcp_f32_e32 v185, v185
	v_rcp_f32_e32 v186, v186
	v_rcp_f32_e32 v187, v187
	v_rcp_f32_e32 v188, v188
	v_rcp_f32_e32 v189, v189
	v_rcp_f32_e32 v190, v190
	v_rcp_f32_e32 v191, v191
	s_nop 0
	v_pk_mul_f32 v[136:137], v[136:137], v[184:185]
	v_pk_mul_f32 v[138:139], v[138:139], v[186:187]
	v_pk_mul_f32 v[140:141], v[140:141], v[188:189]
	v_pk_mul_f32 v[142:143], v[142:143], v[190:191]
	v_pk_mul_f32 v[136:137], v[136:137], v[196:197]
	v_pk_mul_f32 v[138:139], v[138:139], v[198:199]
	v_pk_mul_f32 v[140:141], v[140:141], v[200:201]
	v_pk_mul_f32 v[142:143], v[142:143], v[202:203]
	v_cvt_pk_bf16_f32 v12, v136, v137
	v_cvt_pk_bf16_f32 v13, v138, v139
	v_cvt_pk_bf16_f32 v14, v140, v141
	v_cvt_pk_bf16_f32 v15, v142, v143
	global_store_dwordx4 v6, v[12:15], s[36:37]
	v_add_u32_e32 v6, 5632, v6
	s_waitcnt vmcnt(25)
; __device__ __forceinline__ unsigned cvt_pk_bf16(float lo, float hi) { unsigned r; asm volatile("v_cvt_pk_bf16_f32 %0, %1, %2" : "=v"(r) : "v"(lo), "v"(hi)); return r; }
; __device__ __forceinline__ float silu_f(float x) { return x * __builtin_amdgcn_rcpf(1.0f + __builtin_amdgcn_exp2f(-LOG2E * x)); }
; __device__ __forceinline__ float bflo(unsigned w) { return __uint_as_float(w << 16); }
; __device__ __forceinline__ float bfhi(unsigned w) { return __uint_as_float(w & 0xffff0000u); }
; __device__ __forceinline__ void conv_phase(const bf16_t* Z, bf16_t* UA, const float* cw, const float* cb, int nrows, int rowoff) {
;     ...
;         for (int rr = 0; rr < 16; ++rr) {
;             u32x4 na = zero, ng = zero; if (rr < 15 || has_right) { na = *(const u32x4*)(zp + (size_t)(rr + 1) * FFN2); ng = *(const u32x4*)(zp + (size_t)(rr + 1) * FFN2 + FFN); }
;             u32x4 o;
; #pragma unroll
;             for (int e2 = 0; e2 < 4; ++e2) {
;                 const float a0 = bflo(pa[e2]) * wa[0][2 * e2] + bflo(ca[e2]) * wa[1][2 * e2] + bflo(na[e2]) * wa[2][2 * e2] + ba[2 * e2];
;                 const float a1 = bfhi(pa[e2]) * wa[0][2 * e2 + 1] + bfhi(ca[e2]) * wa[1][2 * e2 + 1] + bfhi(na[e2]) * wa[2][2 * e2 + 1] + ba[2 * e2 + 1];
;                 const float g0 = bflo(pg[e2]) * wg[0][2 * e2] + bflo(cgv[e2]) * wg[1][2 * e2] + bflo(ng[e2]) * wg[2][2 * e2] + bg[2 * e2];
;                 const float g1 = bfhi(pg[e2]) * wg[0][2 * e2 + 1] + bfhi(cgv[e2]) * wg[1][2 * e2 + 1] + bfhi(ng[e2]) * wg[2][2 * e2 + 1] + bg[2 * e2 + 1];
;                 o[e2] = cvt_pk_bf16(silu_f(a0) * g0, silu_f(a1) * g1); }
;             *(u32x4*)(UA + (size_t)(r0 + rr) * FFN + c0) = o;
;             pa = ca; pg = cgv; ca = na; cgv = ng;
	v_lshlrev_b32_e32 v16, 16, v88
	v_and_b32_e32 v17, s99, v88
	v_lshlrev_b32_e32 v18, 16, v89
	v_and_b32_e32 v19, s99, v89
	v_lshlrev_b32_e32 v20, 16, v90
	v_and_b32_e32 v21, s99, v90
	v_lshlrev_b32_e32 v22, 16, v91
	v_and_b32_e32 v23, s99, v91
	v_lshlrev_b32_e32 v24, 16, v92
	v_and_b32_e32 v25, s99, v92
	v_lshlrev_b32_e32 v26, 16, v93
	v_and_b32_e32 v27, s99, v93
	v_lshlrev_b32_e32 v28, 16, v94
	v_and_b32_e32 v29, s99, v94
	v_lshlrev_b32_e32 v30, 16, v95
	v_and_b32_e32 v31, s99, v95
	v_add_u32_e32 v11, 67085056, v5
	global_load_dwordx4 v[88:91], v11, s[2:3] offset:-2816
	global_load_dwordx4 v[92:95], v11, s[2:3] offset:2816
	v_pk_fma_f32 v[136:137], v[32:33], v[152:153], v[236:237]
	v_pk_fma_f32 v[196:197], v[40:41], v[212:213], v[244:245]
	v_pk_fma_f32 v[138:139], v[34:35], v[154:155], v[238:239]
	v_pk_fma_f32 v[198:199], v[42:43], v[214:215], v[246:247]
	v_pk_fma_f32 v[140:141], v[36:37], v[156:157], v[240:241]
	v_pk_fma_f32 v[200:201], v[44:45], v[216:217], v[248:249]
	v_pk_fma_f32 v[142:143], v[38:39], v[158:159], v[242:243]
	v_pk_fma_f32 v[202:203], v[46:47], v[218:219], v[250:251]
	v_pk_fma_f32 v[136:137], v[48:49], v[160:161], v[136:137]
	v_pk_fma_f32 v[196:197], v[56:57], v[220:221], v[196:197]
	v_pk_fma_f32 v[138:139], v[50:51], v[162:163], v[138:139]
	v_pk_fma_f32 v[198:199], v[58:59], v[222:223], v[198:199]
	v_pk_fma_f32 v[140:141], v[52:53], v[164:165], v[140:141]
	v_pk_fma_f32 v[200:201], v[60:61], v[224:225], v[200:201]
	v_pk_fma_f32 v[142:143], v[54:55], v[166:167], v[142:143]
	v_pk_fma_f32 v[202:203], v[62:63], v[226:227], v[202:203]
	v_pk_fma_f32 v[136:137], v[16:17], v[168:169], v[136:137]
	v_pk_fma_f32 v[196:197], v[24:25], v[228:229], v[196:197]
	v_pk_fma_f32 v[138:139], v[18:19], v[170:171], v[138:139]
	v_pk_fma_f32 v[198:199], v[26:27], v[230:231], v[198:199]
	v_pk_fma_f32 v[140:141], v[20:21], v[172:173], v[140:141]
	v_pk_fma_f32 v[200:201], v[28:29], v[232:233], v[200:201]
	v_pk_fma_f32 v[142:143], v[22:23], v[174:175], v[142:143]
	v_pk_fma_f32 v[202:203], v[30:31], v[234:235], v[202:203]
	v_pk_mul_f32 v[184:185], v[136:137], v[180:181]
	v_pk_mul_f32 v[186:187], v[138:139], v[180:181]
	v_pk_mul_f32 v[188:189], v[140:141], v[180:181]
	v_pk_mul_f32 v[190:191], v[142:143], v[180:181]
	v_exp_f32_e32 v184, v184
	v_exp_f32_e32 v185, v185
	v_exp_f32_e32 v186, v186
	v_exp_f32_e32 v187, v187
	v_exp_f32_e32 v188, v188
	v_exp_f32_e32 v189, v189
	v_exp_f32_e32 v190, v190
	v_exp_f32_e32 v191, v191
	s_nop 0
	v_pk_add_f32 v[184:185], v[184:185], v[144:145]
	v_pk_add_f32 v[186:187], v[186:187], v[144:145]
	v_pk_add_f32 v[188:189], v[188:189], v[144:145]
	v_pk_add_f32 v[190:191], v[190:191], v[144:145]
	v_rcp_f32_e32 v184, v184
	v_rcp_f32_e32 v185, v185
	v_rcp_f32_e32 v186, v186
	v_rcp_f32_e32 v187, v187
	v_rcp_f32_e32 v188, v188
	v_rcp_f32_e32 v189, v189
	v_rcp_f32_e32 v190, v190
	v_rcp_f32_e32 v191, v191
	s_nop 0
	v_pk_mul_f32 v[136:137], v[136:137], v[184:185]
	v_pk_mul_f32 v[138:139], v[138:139], v[186:187]
	v_pk_mul_f32 v[140:141], v[140:141], v[188:189]
	v_pk_mul_f32 v[142:143], v[142:143], v[190:191]
	v_pk_mul_f32 v[136:137], v[136:137], v[196:197]
	v_pk_mul_f32 v[138:139], v[138:139], v[198:199]
	v_pk_mul_f32 v[140:141], v[140:141], v[200:201]
	v_pk_mul_f32 v[142:143], v[142:143], v[202:203]
	v_cvt_pk_bf16_f32 v12, v136, v137
	v_cvt_pk_bf16_f32 v13, v138, v139
	v_cvt_pk_bf16_f32 v14, v140, v141
	v_cvt_pk_bf16_f32 v15, v142, v143
	global_store_dwordx4 v6, v[12:15], s[36:37]
	v_add_u32_e32 v6, 5632, v6
	s_waitcnt vmcnt(25)
	v_lshlrev_b32_e32 v32, 16, v96
	v_and_b32_e32 v33, s99, v96
	v_lshlrev_b32_e32 v34, 16, v97
	v_and_b32_e32 v35, s99, v97
	v_lshlrev_b32_e32 v36, 16, v98
	v_and_b32_e32 v37, s99, v98
	v_lshlrev_b32_e32 v38, 16, v99
	v_and_b32_e32 v39, s99, v99
	v_lshlrev_b32_e32 v40, 16, v100
	v_and_b32_e32 v41, s99, v100
	v_lshlrev_b32_e32 v42, 16, v101
	v_and_b32_e32 v43, s99, v101
	v_lshlrev_b32_e32 v44, 16, v102
	v_and_b32_e32 v45, s99, v102
	v_lshlrev_b32_e32 v46, 16, v103
	v_and_b32_e32 v47, s99, v103
	v_add_u32_e32 v10, 67096320, v5
	global_load_dwordx4 v[96:99], v10, s[2:3] offset:-2816
	global_load_dwordx4 v[100:103], v10, s[2:3] offset:2816
	v_pk_fma_f32 v[136:137], v[48:49], v[152:153], v[236:237]
	v_pk_fma_f32 v[196:197], v[56:57], v[212:213], v[244:245]
	v_pk_fma_f32 v[138:139], v[50:51], v[154:155], v[238:239]
	v_pk_fma_f32 v[198:199], v[58:59], v[214:215], v[246:247]
	v_pk_fma_f32 v[140:141], v[52:53], v[156:157], v[240:241]
	v_pk_fma_f32 v[200:201], v[60:61], v[216:217], v[248:249]
	v_pk_fma_f32 v[142:143], v[54:55], v[158:159], v[242:243]
	v_pk_fma_f32 v[202:203], v[62:63], v[218:219], v[250:251]
	v_pk_fma_f32 v[136:137], v[16:17], v[160:161], v[136:137]
	v_pk_fma_f32 v[196:197], v[24:25], v[220:221], v[196:197]
	v_pk_fma_f32 v[138:139], v[18:19], v[162:163], v[138:139]
	v_pk_fma_f32 v[198:199], v[26:27], v[222:223], v[198:199]
	v_pk_fma_f32 v[140:141], v[20:21], v[164:165], v[140:141]
	v_pk_fma_f32 v[200:201], v[28:29], v[224:225], v[200:201]
	v_pk_fma_f32 v[142:143], v[22:23], v[166:167], v[142:143]
	v_pk_fma_f32 v[202:203], v[30:31], v[226:227], v[202:203]
	v_pk_fma_f32 v[136:137], v[32:33], v[168:169], v[136:137]
	v_pk_fma_f32 v[196:197], v[40:41], v[228:229], v[196:197]
	v_pk_fma_f32 v[138:139], v[34:35], v[170:171], v[138:139]
	v_pk_fma_f32 v[198:199], v[42:43], v[230:231], v[198:199]
	v_pk_fma_f32 v[140:141], v[36:37], v[172:173], v[140:141]
	v_pk_fma_f32 v[200:201], v[44:45], v[232:233], v[200:201]
	v_pk_fma_f32 v[142:143], v[38:39], v[174:175], v[142:143]
	v_pk_fma_f32 v[202:203], v[46:47], v[234:235], v[202:203]
	v_pk_mul_f32 v[184:185], v[136:137], v[180:181]
	v_pk_mul_f32 v[186:187], v[138:139], v[180:181]
	v_pk_mul_f32 v[188:189], v[140:141], v[180:181]
	v_pk_mul_f32 v[190:191], v[142:143], v[180:181]
	v_exp_f32_e32 v184, v184
	v_exp_f32_e32 v185, v185
	v_exp_f32_e32 v186, v186
	v_exp_f32_e32 v187, v187
	v_exp_f32_e32 v188, v188
	v_exp_f32_e32 v189, v189
	v_exp_f32_e32 v190, v190
	v_exp_f32_e32 v191, v191
	s_nop 0
	v_pk_add_f32 v[184:185], v[184:185], v[144:145]
	v_pk_add_f32 v[186:187], v[186:187], v[144:145]
	v_pk_add_f32 v[188:189], v[188:189], v[144:145]
	v_pk_add_f32 v[190:191], v[190:191], v[144:145]
	v_rcp_f32_e32 v184, v184
	v_rcp_f32_e32 v185, v185
	v_rcp_f32_e32 v186, v186
	v_rcp_f32_e32 v187, v187
	v_rcp_f32_e32 v188, v188
	v_rcp_f32_e32 v189, v189
	v_rcp_f32_e32 v190, v190
	v_rcp_f32_e32 v191, v191
	s_nop 0
	v_pk_mul_f32 v[136:137], v[136:137], v[184:185]
	v_pk_mul_f32 v[138:139], v[138:139], v[186:187]
	v_pk_mul_f32 v[140:141], v[140:141], v[188:189]
	v_pk_mul_f32 v[142:143], v[142:143], v[190:191]
	v_pk_mul_f32 v[136:137], v[136:137], v[196:197]
	v_pk_mul_f32 v[138:139], v[138:139], v[198:199]
	v_pk_mul_f32 v[140:141], v[140:141], v[200:201]
	v_pk_mul_f32 v[142:143], v[142:143], v[202:203]
	v_cvt_pk_bf16_f32 v12, v136, v137
	v_cvt_pk_bf16_f32 v13, v138, v139
	v_cvt_pk_bf16_f32 v14, v140, v141
	v_cvt_pk_bf16_f32 v15, v142, v143
	global_store_dwordx4 v6, v[12:15], s[36:37]
	v_add_u32_e32 v6, 5632, v6
	s_waitcnt vmcnt(25)
; __device__ __forceinline__ unsigned cvt_pk_bf16(float lo, float hi) { unsigned r; asm volatile("v_cvt_pk_bf16_f32 %0, %1, %2" : "=v"(r) : "v"(lo), "v"(hi)); return r; }
; __device__ __forceinline__ float silu_f(float x) { return x * __builtin_amdgcn_rcpf(1.0f + __builtin_amdgcn_exp2f(-LOG2E * x)); }
; __device__ __forceinline__ float bflo(unsigned w) { return __uint_as_float(w << 16); }
; __device__ __forceinline__ float bfhi(unsigned w) { return __uint_as_float(w & 0xffff0000u); }
; __device__ __forceinline__ void conv_phase(const bf16_t* Z, bf16_t* UA, const float* cw, const float* cb, int nrows, int rowoff) {
;     ...
;         for (int rr = 0; rr < 16; ++rr) {
;             u32x4 na = zero, ng = zero; if (rr < 15 || has_right) { na = *(const u32x4*)(zp + (size_t)(rr + 1) * FFN2); ng = *(const u32x4*)(zp + (size_t)(rr + 1) * FFN2 + FFN); }
;             u32x4 o;
; #pragma unroll
;             for (int e2 = 0; e2 < 4; ++e2) {
;                 const float a0 = bflo(pa[e2]) * wa[0][2 * e2] + bflo(ca[e2]) * wa[1][2 * e2] + bflo(na[e2]) * wa[2][2 * e2] + ba[2 * e2];
;                 const float a1 = bfhi(pa[e2]) * wa[0][2 * e2 + 1] + bfhi(ca[e2]) * wa[1][2 * e2 + 1] + bfhi(na[e2]) * wa[2][2 * e2 + 1] + ba[2 * e2 + 1];
;                 const float g0 = bflo(pg[e2]) * wg[0][2 * e2] + bflo(cgv[e2]) * wg[1][2 * e2] + bflo(ng[e2]) * wg[2][2 * e2] + bg[2 * e2];
;                 const float g1 = bfhi(pg[e2]) * wg[0][2 * e2 + 1] + bfhi(cgv[e2]) * wg[1][2 * e2 + 1] + bfhi(ng[e2]) * wg[2][2 * e2 + 1] + bg[2 * e2 + 1];
;                 o[e2] = cvt_pk_bf16(silu_f(a0) * g0, silu_f(a1) * g1); }
;             *(u32x4*)(UA + (size_t)(r0 + rr) * FFN + c0) = o;
;             pa = ca; pg = cgv; ca = na; cgv = ng;
	v_lshlrev_b32_e32 v48, 16, v104
	v_and_b32_e32 v49, s99, v104
	v_lshlrev_b32_e32 v50, 16, v105
	v_and_b32_e32 v51, s99, v105
	v_lshlrev_b32_e32 v52, 16, v106
	v_and_b32_e32 v53, s99, v106
	v_lshlrev_b32_e32 v54, 16, v107
	v_and_b32_e32 v55, s99, v107
	v_lshlrev_b32_e32 v56, 16, v108
	v_and_b32_e32 v57, s99, v108
	v_lshlrev_b32_e32 v58, 16, v109
	v_and_b32_e32 v59, s99, v109
	v_lshlrev_b32_e32 v60, 16, v110
	v_and_b32_e32 v61, s99, v110
	v_lshlrev_b32_e32 v62, 16, v111
	v_and_b32_e32 v63, s99, v111
	v_add_u32_e32 v11, 67107584, v5
	global_load_dwordx4 v[104:107], v11, s[2:3] offset:-2816
	global_load_dwordx4 v[108:111], v11, s[2:3] offset:2816
	v_pk_fma_f32 v[136:137], v[16:17], v[152:153], v[236:237]
	v_pk_fma_f32 v[196:197], v[24:25], v[212:213], v[244:245]
	v_pk_fma_f32 v[138:139], v[18:19], v[154:155], v[238:239]
	v_pk_fma_f32 v[198:199], v[26:27], v[214:215], v[246:247]
	v_pk_fma_f32 v[140:141], v[20:21], v[156:157], v[240:241]
	v_pk_fma_f32 v[200:201], v[28:29], v[216:217], v[248:249]
	v_pk_fma_f32 v[142:143], v[22:23], v[158:159], v[242:243]
	v_pk_fma_f32 v[202:203], v[30:31], v[218:219], v[250:251]
	v_pk_fma_f32 v[136:137], v[32:33], v[160:161], v[136:137]
	v_pk_fma_f32 v[196:197], v[40:41], v[220:221], v[196:197]
	v_pk_fma_f32 v[138:139], v[34:35], v[162:163], v[138:139]
	v_pk_fma_f32 v[198:199], v[42:43], v[222:223], v[198:199]
	v_pk_fma_f32 v[140:141], v[36:37], v[164:165], v[140:141]
	v_pk_fma_f32 v[200:201], v[44:45], v[224:225], v[200:201]
	v_pk_fma_f32 v[142:143], v[38:39], v[166:167], v[142:143]
	v_pk_fma_f32 v[202:203], v[46:47], v[226:227], v[202:203]
	v_pk_fma_f32 v[136:137], v[48:49], v[168:169], v[136:137]
	v_pk_fma_f32 v[196:197], v[56:57], v[228:229], v[196:197]
	v_pk_fma_f32 v[138:139], v[50:51], v[170:171], v[138:139]
	v_pk_fma_f32 v[198:199], v[58:59], v[230:231], v[198:199]
	v_pk_fma_f32 v[140:141], v[52:53], v[172:173], v[140:141]
	v_pk_fma_f32 v[200:201], v[60:61], v[232:233], v[200:201]
	v_pk_fma_f32 v[142:143], v[54:55], v[174:175], v[142:143]
	v_pk_fma_f32 v[202:203], v[62:63], v[234:235], v[202:203]
	v_pk_mul_f32 v[184:185], v[136:137], v[180:181]
	v_pk_mul_f32 v[186:187], v[138:139], v[180:181]
	v_pk_mul_f32 v[188:189], v[140:141], v[180:181]
	v_pk_mul_f32 v[190:191], v[142:143], v[180:181]
	v_exp_f32_e32 v184, v184
	v_exp_f32_e32 v185, v185
	v_exp_f32_e32 v186, v186
	v_exp_f32_e32 v187, v187
	v_exp_f32_e32 v188, v188
	v_exp_f32_e32 v189, v189
	v_exp_f32_e32 v190, v190
	v_exp_f32_e32 v191, v191
	s_nop 0
	v_pk_add_f32 v[184:185], v[184:185], v[144:145]
	v_pk_add_f32 v[186:187], v[186:187], v[144:145]
	v_pk_add_f32 v[188:189], v[188:189], v[144:145]
	v_pk_add_f32 v[190:191], v[190:191], v[144:145]
	v_rcp_f32_e32 v184, v184
	v_rcp_f32_e32 v185, v185
	v_rcp_f32_e32 v186, v186
	v_rcp_f32_e32 v187, v187
	v_rcp_f32_e32 v188, v188
	v_rcp_f32_e32 v189, v189
	v_rcp_f32_e32 v190, v190
	v_rcp_f32_e32 v191, v191
	s_nop 0
	v_pk_mul_f32 v[136:137], v[136:137], v[184:185]
	v_pk_mul_f32 v[138:139], v[138:139], v[186:187]
	v_pk_mul_f32 v[140:141], v[140:141], v[188:189]
	v_pk_mul_f32 v[142:143], v[142:143], v[190:191]
	v_pk_mul_f32 v[136:137], v[136:137], v[196:197]
	v_pk_mul_f32 v[138:139], v[138:139], v[198:199]
	v_pk_mul_f32 v[140:141], v[140:141], v[200:201]
	v_pk_mul_f32 v[142:143], v[142:143], v[202:203]
	v_cvt_pk_bf16_f32 v12, v136, v137
	v_cvt_pk_bf16_f32 v13, v138, v139
	v_cvt_pk_bf16_f32 v14, v140, v141
	v_cvt_pk_bf16_f32 v15, v142, v143
	global_store_dwordx4 v6, v[12:15], s[36:37]
	v_add_u32_e32 v6, 5632, v6
	s_waitcnt vmcnt(25)
	v_lshlrev_b32_e32 v16, 16, v112
	v_and_b32_e32 v17, s99, v112
	v_lshlrev_b32_e32 v18, 16, v113
	v_and_b32_e32 v19, s99, v113
	v_lshlrev_b32_e32 v20, 16, v114
	v_and_b32_e32 v21, s99, v114
	v_lshlrev_b32_e32 v22, 16, v115
	v_and_b32_e32 v23, s99, v115
	v_lshlrev_b32_e32 v24, 16, v116
	v_and_b32_e32 v25, s99, v116
	v_lshlrev_b32_e32 v26, 16, v117
	v_and_b32_e32 v27, s99, v117
	v_lshlrev_b32_e32 v28, 16, v118
	v_and_b32_e32 v29, s99, v118
	v_lshlrev_b32_e32 v30, 16, v119
	v_and_b32_e32 v31, s99, v119
	v_add_u32_e32 v10, 67118848, v5
	global_load_dwordx4 v[112:115], v10, s[2:3] offset:-2816
	global_load_dwordx4 v[116:119], v10, s[2:3] offset:2816
	v_pk_fma_f32 v[136:137], v[32:33], v[152:153], v[236:237]
	v_pk_fma_f32 v[196:197], v[40:41], v[212:213], v[244:245]
	v_pk_fma_f32 v[138:139], v[34:35], v[154:155], v[238:239]
	v_pk_fma_f32 v[198:199], v[42:43], v[214:215], v[246:247]
	v_pk_fma_f32 v[140:141], v[36:37], v[156:157], v[240:241]
	v_pk_fma_f32 v[200:201], v[44:45], v[216:217], v[248:249]
	v_pk_fma_f32 v[142:143], v[38:39], v[158:159], v[242:243]
	v_pk_fma_f32 v[202:203], v[46:47], v[218:219], v[250:251]
	v_pk_fma_f32 v[136:137], v[48:49], v[160:161], v[136:137]
	v_pk_fma_f32 v[196:197], v[56:57], v[220:221], v[196:197]
	v_pk_fma_f32 v[138:139], v[50:51], v[162:163], v[138:139]
	v_pk_fma_f32 v[198:199], v[58:59], v[222:223], v[198:199]
	v_pk_fma_f32 v[140:141], v[52:53], v[164:165], v[140:141]
	v_pk_fma_f32 v[200:201], v[60:61], v[224:225], v[200:201]
	v_pk_fma_f32 v[142:143], v[54:55], v[166:167], v[142:143]
	v_pk_fma_f32 v[202:203], v[62:63], v[226:227], v[202:203]
	v_pk_fma_f32 v[136:137], v[16:17], v[168:169], v[136:137]
	v_pk_fma_f32 v[196:197], v[24:25], v[228:229], v[196:197]
	v_pk_fma_f32 v[138:139], v[18:19], v[170:171], v[138:139]
	v_pk_fma_f32 v[198:199], v[26:27], v[230:231], v[198:199]
	v_pk_fma_f32 v[140:141], v[20:21], v[172:173], v[140:141]
	v_pk_fma_f32 v[200:201], v[28:29], v[232:233], v[200:201]
	v_pk_fma_f32 v[142:143], v[22:23], v[174:175], v[142:143]
	v_pk_fma_f32 v[202:203], v[30:31], v[234:235], v[202:203]
	v_pk_mul_f32 v[184:185], v[136:137], v[180:181]
	v_pk_mul_f32 v[186:187], v[138:139], v[180:181]
	v_pk_mul_f32 v[188:189], v[140:141], v[180:181]
	v_pk_mul_f32 v[190:191], v[142:143], v[180:181]
	v_exp_f32_e32 v184, v184
	v_exp_f32_e32 v185, v185
	v_exp_f32_e32 v186, v186
	v_exp_f32_e32 v187, v187
	v_exp_f32_e32 v188, v188
	v_exp_f32_e32 v189, v189
	v_exp_f32_e32 v190, v190
	v_exp_f32_e32 v191, v191
	s_nop 0
	v_pk_add_f32 v[184:185], v[184:185], v[144:145]
	v_pk_add_f32 v[186:187], v[186:187], v[144:145]
	v_pk_add_f32 v[188:189], v[188:189], v[144:145]
	v_pk_add_f32 v[190:191], v[190:191], v[144:145]
	v_rcp_f32_e32 v184, v184
	v_rcp_f32_e32 v185, v185
	v_rcp_f32_e32 v186, v186
	v_rcp_f32_e32 v187, v187
	v_rcp_f32_e32 v188, v188
	v_rcp_f32_e32 v189, v189
	v_rcp_f32_e32 v190, v190
	v_rcp_f32_e32 v191, v191
	s_nop 0
	v_pk_mul_f32 v[136:137], v[136:137], v[184:185]
	v_pk_mul_f32 v[138:139], v[138:139], v[186:187]
	v_pk_mul_f32 v[140:141], v[140:141], v[188:189]
	v_pk_mul_f32 v[142:143], v[142:143], v[190:191]
	v_pk_mul_f32 v[136:137], v[136:137], v[196:197]
	v_pk_mul_f32 v[138:139], v[138:139], v[198:199]
	v_pk_mul_f32 v[140:141], v[140:141], v[200:201]
	v_pk_mul_f32 v[142:143], v[142:143], v[202:203]
	v_cvt_pk_bf16_f32 v12, v136, v137
	v_cvt_pk_bf16_f32 v13, v138, v139
	v_cvt_pk_bf16_f32 v14, v140, v141
	v_cvt_pk_bf16_f32 v15, v142, v143
	global_store_dwordx4 v6, v[12:15], s[36:37]
	v_add_u32_e32 v6, 5632, v6
	s_waitcnt vmcnt(25)
; __device__ __forceinline__ unsigned cvt_pk_bf16(float lo, float hi) { unsigned r; asm volatile("v_cvt_pk_bf16_f32 %0, %1, %2" : "=v"(r) : "v"(lo), "v"(hi)); return r; }
; __device__ __forceinline__ float silu_f(float x) { return x * __builtin_amdgcn_rcpf(1.0f + __builtin_amdgcn_exp2f(-LOG2E * x)); }
; __device__ __forceinline__ float bflo(unsigned w) { return __uint_as_float(w << 16); }
; __device__ __forceinline__ float bfhi(unsigned w) { return __uint_as_float(w & 0xffff0000u); }
; __device__ __forceinline__ void conv_phase(const bf16_t* Z, bf16_t* UA, const float* cw, const float* cb, int nrows, int rowoff) {
;     ...
;         for (int rr = 0; rr < 16; ++rr) {
;             u32x4 na = zero, ng = zero; if (rr < 15 || has_right) { na = *(const u32x4*)(zp + (size_t)(rr + 1) * FFN2); ng = *(const u32x4*)(zp + (size_t)(rr + 1) * FFN2 + FFN); }
;             u32x4 o;
; #pragma unroll
;             for (int e2 = 0; e2 < 4; ++e2) {
;                 const float a0 = bflo(pa[e2]) * wa[0][2 * e2] + bflo(ca[e2]) * wa[1][2 * e2] + bflo(na[e2]) * wa[2][2 * e2] + ba[2 * e2];
;                 const float a1 = bfhi(pa[e2]) * wa[0][2 * e2 + 1] + bfhi(ca[e2]) * wa[1][2 * e2 + 1] + bfhi(na[e2]) * wa[2][2 * e2 + 1] + ba[2 * e2 + 1];
;                 const float g0 = bflo(pg[e2]) * wg[0][2 * e2] + bflo(cgv[e2]) * wg[1][2 * e2] + bflo(ng[e2]) * wg[2][2 * e2] + bg[2 * e2];
;                 const float g1 = bfhi(pg[e2]) * wg[0][2 * e2 + 1] + bfhi(cgv[e2]) * wg[1][2 * e2 + 1] + bfhi(ng[e2]) * wg[2][2 * e2 + 1] + bg[2 * e2 + 1];
;                 o[e2] = cvt_pk_bf16(silu_f(a0) * g0, silu_f(a1) * g1); }
;             *(u32x4*)(UA + (size_t)(r0 + rr) * FFN + c0) = o;
;             pa = ca; pg = cgv; ca = na; cgv = ng;
	v_lshlrev_b32_e32 v32, 16, v120
	v_and_b32_e32 v33, s99, v120
	v_lshlrev_b32_e32 v34, 16, v121
	v_and_b32_e32 v35, s99, v121
	v_lshlrev_b32_e32 v36, 16, v122
	v_and_b32_e32 v37, s99, v122
	v_lshlrev_b32_e32 v38, 16, v123
	v_and_b32_e32 v39, s99, v123
	v_lshlrev_b32_e32 v40, 16, v124
	v_and_b32_e32 v41, s99, v124
	v_lshlrev_b32_e32 v42, 16, v125
	v_and_b32_e32 v43, s99, v125
	v_lshlrev_b32_e32 v44, 16, v126
	v_and_b32_e32 v45, s99, v126
	v_lshlrev_b32_e32 v46, 16, v127
	v_and_b32_e32 v47, s99, v127
	v_add_u32_e32 v11, 67130112, v5
	global_load_dwordx4 v[120:123], v11, s[2:3] offset:-2816
	global_load_dwordx4 v[124:127], v11, s[2:3] offset:2816
	v_pk_fma_f32 v[136:137], v[48:49], v[152:153], v[236:237]
	v_pk_fma_f32 v[196:197], v[56:57], v[212:213], v[244:245]
	v_pk_fma_f32 v[138:139], v[50:51], v[154:155], v[238:239]
	v_pk_fma_f32 v[198:199], v[58:59], v[214:215], v[246:247]
	v_pk_fma_f32 v[140:141], v[52:53], v[156:157], v[240:241]
	v_pk_fma_f32 v[200:201], v[60:61], v[216:217], v[248:249]
	v_pk_fma_f32 v[142:143], v[54:55], v[158:159], v[242:243]
	v_pk_fma_f32 v[202:203], v[62:63], v[218:219], v[250:251]
	v_pk_fma_f32 v[136:137], v[16:17], v[160:161], v[136:137]
	v_pk_fma_f32 v[196:197], v[24:25], v[220:221], v[196:197]
	v_pk_fma_f32 v[138:139], v[18:19], v[162:163], v[138:139]
	v_pk_fma_f32 v[198:199], v[26:27], v[222:223], v[198:199]
	v_pk_fma_f32 v[140:141], v[20:21], v[164:165], v[140:141]
	v_pk_fma_f32 v[200:201], v[28:29], v[224:225], v[200:201]
	v_pk_fma_f32 v[142:143], v[22:23], v[166:167], v[142:143]
	v_pk_fma_f32 v[202:203], v[30:31], v[226:227], v[202:203]
	v_pk_fma_f32 v[136:137], v[32:33], v[168:169], v[136:137]
	v_pk_fma_f32 v[196:197], v[40:41], v[228:229], v[196:197]
	v_pk_fma_f32 v[138:139], v[34:35], v[170:171], v[138:139]
	v_pk_fma_f32 v[198:199], v[42:43], v[230:231], v[198:199]
	v_pk_fma_f32 v[140:141], v[36:37], v[172:173], v[140:141]
	v_pk_fma_f32 v[200:201], v[44:45], v[232:233], v[200:201]
	v_pk_fma_f32 v[142:143], v[38:39], v[174:175], v[142:143]
	v_pk_fma_f32 v[202:203], v[46:47], v[234:235], v[202:203]
	v_pk_mul_f32 v[184:185], v[136:137], v[180:181]
	v_pk_mul_f32 v[186:187], v[138:139], v[180:181]
	v_pk_mul_f32 v[188:189], v[140:141], v[180:181]
	v_pk_mul_f32 v[190:191], v[142:143], v[180:181]
	v_exp_f32_e32 v184, v184
	v_exp_f32_e32 v185, v185
	v_exp_f32_e32 v186, v186
	v_exp_f32_e32 v187, v187
	v_exp_f32_e32 v188, v188
	v_exp_f32_e32 v189, v189
	v_exp_f32_e32 v190, v190
	v_exp_f32_e32 v191, v191
	s_nop 0
	v_pk_add_f32 v[184:185], v[184:185], v[144:145]
	v_pk_add_f32 v[186:187], v[186:187], v[144:145]
	v_pk_add_f32 v[188:189], v[188:189], v[144:145]
	v_pk_add_f32 v[190:191], v[190:191], v[144:145]
	v_rcp_f32_e32 v184, v184
	v_rcp_f32_e32 v185, v185
	v_rcp_f32_e32 v186, v186
	v_rcp_f32_e32 v187, v187
	v_rcp_f32_e32 v188, v188
	v_rcp_f32_e32 v189, v189
	v_rcp_f32_e32 v190, v190
	v_rcp_f32_e32 v191, v191
	s_nop 0
	v_pk_mul_f32 v[136:137], v[136:137], v[184:185]
	v_pk_mul_f32 v[138:139], v[138:139], v[186:187]
	v_pk_mul_f32 v[140:141], v[140:141], v[188:189]
	v_pk_mul_f32 v[142:143], v[142:143], v[190:191]
	v_pk_mul_f32 v[136:137], v[136:137], v[196:197]
	v_pk_mul_f32 v[138:139], v[138:139], v[198:199]
	v_pk_mul_f32 v[140:141], v[140:141], v[200:201]
	v_pk_mul_f32 v[142:143], v[142:143], v[202:203]
	v_cvt_pk_bf16_f32 v12, v136, v137
	v_cvt_pk_bf16_f32 v13, v138, v139
	v_cvt_pk_bf16_f32 v14, v140, v141
	v_cvt_pk_bf16_f32 v15, v142, v143
	global_store_dwordx4 v6, v[12:15], s[36:37]
	v_add_u32_e32 v6, 5632, v6
	s_waitcnt vmcnt(25)
; __device__ __forceinline__ unsigned cvt_pk_bf16(float lo, float hi) { unsigned r; asm volatile("v_cvt_pk_bf16_f32 %0, %1, %2" : "=v"(r) : "v"(lo), "v"(hi)); return r; }
; __device__ __forceinline__ float silu_f(float x) { return x * __builtin_amdgcn_rcpf(1.0f + __builtin_amdgcn_exp2f(-LOG2E * x)); }
; __device__ __forceinline__ float bflo(unsigned w) { return __uint_as_float(w << 16); }
; __device__ __forceinline__ float bfhi(unsigned w) { return __uint_as_float(w & 0xffff0000u); }
; __device__ __forceinline__ void conv_phase(const bf16_t* Z, bf16_t* UA, const float* cw, const float* cb, int nrows, int rowoff) {
;     ...
;         for (int rr = 0; rr < 16; ++rr) {
;             u32x4 na = zero, ng = zero; if (rr < 15 || has_right) { na = *(const u32x4*)(zp + (size_t)(rr + 1) * FFN2); ng = *(const u32x4*)(zp + (size_t)(rr + 1) * FFN2 + FFN); }
;             u32x4 o;
; #pragma unroll
;             for (int e2 = 0; e2 < 4; ++e2) {
;                 const float a0 = bflo(pa[e2]) * wa[0][2 * e2] + bflo(ca[e2]) * wa[1][2 * e2] + bflo(na[e2]) * wa[2][2 * e2] + ba[2 * e2];
;                 const float a1 = bfhi(pa[e2]) * wa[0][2 * e2 + 1] + bfhi(ca[e2]) * wa[1][2 * e2 + 1] + bfhi(na[e2]) * wa[2][2 * e2 + 1] + ba[2 * e2 + 1];
;                 const float g0 = bflo(pg[e2]) * wg[0][2 * e2] + bflo(cgv[e2]) * wg[1][2 * e2] + bflo(ng[e2]) * wg[2][2 * e2] + bg[2 * e2];
;                 const float g1 = bfhi(pg[e2]) * wg[0][2 * e2 + 1] + bfhi(cgv[e2]) * wg[1][2 * e2 + 1] + bfhi(ng[e2]) * wg[2][2 * e2 + 1] + bg[2 * e2 + 1];
;                 o[e2] = cvt_pk_bf16(silu_f(a0) * g0, silu_f(a1) * g1); }
;             *(u32x4*)(UA + (size_t)(r0 + rr) * FFN + c0) = o;
;             pa = ca; pg = cgv; ca = na; cgv = ng;
; __device__ __forceinline__ void xcd_barrier(const XcdBarrier& b) {
;     asm volatile("s_waitcnt vmcnt(0)" ::: "memory");
;     __syncthreads();
;     if (threadIdx.x == 0) {
;         unsigned* bar = b.bar;
;         __builtin_amdgcn_s_waitcnt(0);
;         unsigned nloc = b.st[0], nx = b.st[1];
;         if (nloc == 0u) { xcd_barrier_complete(bar, b.x, nloc, nx); b.st[0] = nloc; b.st[1] = nx; }
	v_cndmask_b32_e64 v128, 0, v128, s[100:101]
	v_cndmask_b32_e64 v129, 0, v129, s[100:101]
	v_cndmask_b32_e64 v130, 0, v130, s[100:101]
	v_cndmask_b32_e64 v131, 0, v131, s[100:101]
	v_cndmask_b32_e64 v132, 0, v132, s[100:101]
	v_cndmask_b32_e64 v133, 0, v133, s[100:101]
	v_cndmask_b32_e64 v134, 0, v134, s[100:101]
	v_cndmask_b32_e64 v135, 0, v135, s[100:101]
	v_lshlrev_b32_e32 v48, 16, v128
	v_and_b32_e32 v49, s99, v128
	v_lshlrev_b32_e32 v50, 16, v129
	v_and_b32_e32 v51, s99, v129
	v_lshlrev_b32_e32 v52, 16, v130
	v_and_b32_e32 v53, s99, v130
	v_lshlrev_b32_e32 v54, 16, v131
	v_and_b32_e32 v55, s99, v131
	v_lshlrev_b32_e32 v56, 16, v132
	v_and_b32_e32 v57, s99, v132
	v_lshlrev_b32_e32 v58, 16, v133
	v_and_b32_e32 v59, s99, v133
	v_lshlrev_b32_e32 v60, 16, v134
	v_and_b32_e32 v61, s99, v134
	v_lshlrev_b32_e32 v62, 16, v135
	v_and_b32_e32 v63, s99, v135
	v_add_u32_e32 v10, 67141376, v5
	global_load_dwordx4 v[128:131], v10, s[2:3] offset:-2816
	global_load_dwordx4 v[132:135], v10, s[2:3] offset:2816
	v_pk_fma_f32 v[136:137], v[16:17], v[152:153], v[236:237]
	v_pk_fma_f32 v[196:197], v[24:25], v[212:213], v[244:245]
	v_pk_fma_f32 v[138:139], v[18:19], v[154:155], v[238:239]
	v_pk_fma_f32 v[198:199], v[26:27], v[214:215], v[246:247]
	v_pk_fma_f32 v[140:141], v[20:21], v[156:157], v[240:241]
	v_pk_fma_f32 v[200:201], v[28:29], v[216:217], v[248:249]
	v_pk_fma_f32 v[142:143], v[22:23], v[158:159], v[242:243]
	v_pk_fma_f32 v[202:203], v[30:31], v[218:219], v[250:251]
	v_pk_fma_f32 v[136:137], v[32:33], v[160:161], v[136:137]
	v_pk_fma_f32 v[196:197], v[40:41], v[220:221], v[196:197]
	v_pk_fma_f32 v[138:139], v[34:35], v[162:163], v[138:139]
	v_pk_fma_f32 v[198:199], v[42:43], v[222:223], v[198:199]
	v_pk_fma_f32 v[140:141], v[36:37], v[164:165], v[140:141]
	v_pk_fma_f32 v[200:201], v[44:45], v[224:225], v[200:201]
	v_pk_fma_f32 v[142:143], v[38:39], v[166:167], v[142:143]
	v_pk_fma_f32 v[202:203], v[46:47], v[226:227], v[202:203]
	v_pk_fma_f32 v[136:137], v[48:49], v[168:169], v[136:137]
	v_pk_fma_f32 v[196:197], v[56:57], v[228:229], v[196:197]
	v_pk_fma_f32 v[138:139], v[50:51], v[170:171], v[138:139]
	v_pk_fma_f32 v[198:199], v[58:59], v[230:231], v[198:199]
	v_pk_fma_f32 v[140:141], v[52:53], v[172:173], v[140:141]
	v_pk_fma_f32 v[200:201], v[60:61], v[232:233], v[200:201]
	v_pk_fma_f32 v[142:143], v[54:55], v[174:175], v[142:143]
	v_pk_fma_f32 v[202:203], v[62:63], v[234:235], v[202:203]
	v_pk_mul_f32 v[184:185], v[136:137], v[180:181]
	v_pk_mul_f32 v[186:187], v[138:139], v[180:181]
	v_pk_mul_f32 v[188:189], v[140:141], v[180:181]
	v_pk_mul_f32 v[190:191], v[142:143], v[180:181]
	v_exp_f32_e32 v184, v184
	v_exp_f32_e32 v185, v185
	v_exp_f32_e32 v186, v186
	v_exp_f32_e32 v187, v187
	v_exp_f32_e32 v188, v188
	v_exp_f32_e32 v189, v189
	v_exp_f32_e32 v190, v190
	v_exp_f32_e32 v191, v191
	s_nop 0
	v_pk_add_f32 v[184:185], v[184:185], v[144:145]
	v_pk_add_f32 v[186:187], v[186:187], v[144:145]
	v_pk_add_f32 v[188:189], v[188:189], v[144:145]
	v_pk_add_f32 v[190:191], v[190:191], v[144:145]
	v_rcp_f32_e32 v184, v184
	v_rcp_f32_e32 v185, v185
	v_rcp_f32_e32 v186, v186
	v_rcp_f32_e32 v187, v187
	v_rcp_f32_e32 v188, v188
	v_rcp_f32_e32 v189, v189
	v_rcp_f32_e32 v190, v190
	v_rcp_f32_e32 v191, v191
	s_nop 0
	v_pk_mul_f32 v[136:137], v[136:137], v[184:185]
	v_pk_mul_f32 v[138:139], v[138:139], v[186:187]
	v_pk_mul_f32 v[140:141], v[140:141], v[188:189]
	v_pk_mul_f32 v[142:143], v[142:143], v[190:191]
	v_pk_mul_f32 v[136:137], v[136:137], v[196:197]
	v_pk_mul_f32 v[138:139], v[138:139], v[198:199]
	v_pk_mul_f32 v[140:141], v[140:141], v[200:201]
	v_pk_mul_f32 v[142:143], v[142:143], v[202:203]
	v_cvt_pk_bf16_f32 v12, v136, v137
	v_cvt_pk_bf16_f32 v13, v138, v139
	v_cvt_pk_bf16_f32 v14, v140, v141
	v_cvt_pk_bf16_f32 v15, v142, v143
	global_store_dwordx4 v6, v[12:15], s[36:37]
	v_add_u32_e32 v5, 67043328, v5
	v_add_u32_e32 v6, 33437184, v6
	v_add_u32_e32 v7, 372, v7
	v_add_u32_e32 v2, 372, v2
	s_add_u32 s98, s98, 1
	s_cmp_lt_u32 s98, 6
	s_cbranch_scc1 .Lconv_item_l0
.Lconv_done_l0:
	s_waitcnt vmcnt(0)
	s_barrier
	s_mov_b64 s[2:3], exec
	v_readlane_b32 s12, v254, 0
	v_readlane_b32 s13, v254, 1
	s_and_b64 s[12:13], s[2:3], s[12:13]
	s_mov_b64 exec, s[12:13]
	s_cbranch_execz .LBB0_516
	v_readlane_b32 s12, v255, 22
	s_waitcnt vmcnt(0) expcnt(0) lgkmcnt(0)
	s_nop 0
	v_mov_b32_e32 v1, s12
	ds_read_b32 v3, v1
	v_readlane_b32 s12, v255, 23
	s_waitcnt lgkmcnt(0)
	v_cmp_ne_u32_e32 vcc, 0, v3
	v_mov_b32_e32 v1, s12
	ds_read_b32 v2, v1
	s_cbranch_vccnz .LBB0_484
	s_mov_b32 s30, 1
	s_branch .LBB0_472

; __device__ __forceinline__ void conv_phase(const bf16_t* Z, bf16_t* UA, const float* cw, const float* cb, int nrows, int rowoff) {
;     ...
;         const int cgp = idx % 352, rb = idx / 352, c0 = cgp * 8, r0 = rb * 16, grow0 = rowoff + r0;
;         const int seg = grow0 < MLAT ? SEQ : CTXL; const bool has_left = (grow0 & (seg - 1)) != 0, has_right = ((grow0 + 16) & (seg - 1)) != 0;
;         float wa[3][8], wg[3][8], ba[8], bg[8];
; #pragma unroll
;         for (int j = 0; j < 3; ++j)
; #pragma unroll
;             for (int h = 0; h < 2; ++h) { const f32x4 x = *(const f32x4*)(cw + j * FFN2 + c0 + 4 * h), y = *(const f32x4*)(cw + j * FFN2 + FFN + c0 + 4 * h);
; #pragma unroll
;                 for (int e = 0; e < 4; ++e) { wa[j][4 * h + e] = x[e]; wg[j][4 * h + e] = y[e]; } }
; #pragma unroll
;         for (int h = 0; h < 2; ++h) { const f32x4 x = *(const f32x4*)(cb + c0 + 4 * h), y = *(const f32x4*)(cb + FFN + c0 + 4 * h);
; #pragma unroll
;             for (int e = 0; e < 4; ++e) { ba[4 * h + e] = x[e]; bg[4 * h + e] = y[e]; } }
;         const bf16_t* zp = Z + (size_t)r0 * FFN2 + c0; const u32x4 zero = (u32x4){0u, 0u, 0u, 0u};
;         u32x4 pa = zero, pg = zero; if (has_left) { pa = *(const u32x4*)(zp - FFN2); pg = *(const u32x4*)(zp - FFN2 + FFN); }
;         u32x4 ca = *(const u32x4*)(zp), cgv = *(const u32x4*)(zp + FFN);
; #pragma unroll 4
;         for (int rr = 0; rr < 16; ++rr) {
;             u32x4 na = zero, ng = zero; if (rr < 15 || has_right) { na = *(const u32x4*)(zp + (size_t)(rr + 1) * FFN2); ng = *(const u32x4*)(zp + (size_t)(rr + 1) * FFN2 + FFN); }
;             u32x4 o;
; #pragma unroll
;             for (int e2 = 0; e2 < 4; ++e2) {
;                 const float a0 = bflo(pa[e2]) * wa[0][2 * e2] + bflo(ca[e2]) * wa[1][2 * e2] + bflo(na[e2]) * wa[2][2 * e2] + ba[2 * e2];
;                 const float a1 = bfhi(pa[e2]) * wa[0][2 * e2 + 1] + bfhi(ca[e2]) * wa[1][2 * e2 + 1] + bfhi(na[e2]) * wa[2][2 * e2 + 1] + ba[2 * e2 + 1];
;                 const float g0 = bflo(pg[e2]) * wg[0][2 * e2] + bflo(cgv[e2]) * wg[1][2 * e2] + bflo(ng[e2]) * wg[2][2 * e2] + bg[2 * e2];
;                 const float g1 = bfhi(pg[e2]) * wg[0][2 * e2 + 1] + bfhi(cgv[e2]) * wg[1][2 * e2 + 1] + bfhi(ng[e2]) * wg[2][2 * e2 + 1] + bg[2 * e2 + 1];
;                 o[e2] = cvt_pk_bf16(silu_f(a0) * g0, silu_f(a1) * g1); }
.Lconv_item_l1:
	v_cmp_gt_u32_e32 vcc, 0x800, v2
	s_nop 4
	s_cbranch_vccz .Lconv_done_l1
	v_mov_b32_e32 v9, 0x1ff
	v_cmp_gt_u32_e32 vcc, 0x1000, v7
	s_nop 1
	v_cndmask_b32_e32 v8, 15, v9, vcc
	v_and_b32_e32 v9, v7, v8
	v_cmp_ne_u32_e64 s[34:35], 0, v9
	v_add_u32_e32 v9, 1, v7
	v_and_b32_e32 v9, v9, v8
	v_cmp_ne_u32_e64 s[100:101], 0, v9
	s_waitcnt vmcnt(25)
	v_cndmask_b32_e64 v64, 0, v64, s[34:35]
	v_cndmask_b32_e64 v65, 0, v65, s[34:35]
	v_cndmask_b32_e64 v66, 0, v66, s[34:35]
	v_cndmask_b32_e64 v67, 0, v67, s[34:35]
	v_cndmask_b32_e64 v68, 0, v68, s[34:35]
	v_cndmask_b32_e64 v69, 0, v69, s[34:35]
	v_cndmask_b32_e64 v70, 0, v70, s[34:35]
	v_cndmask_b32_e64 v71, 0, v71, s[34:35]
	v_lshlrev_b32_e32 v16, 16, v64
	v_and_b32_e32 v17, s99, v64
	v_lshlrev_b32_e32 v18, 16, v65
	v_and_b32_e32 v19, s99, v65
	v_lshlrev_b32_e32 v20, 16, v66
	v_and_b32_e32 v21, s99, v66
	v_lshlrev_b32_e32 v22, 16, v67
	v_and_b32_e32 v23, s99, v67
	v_lshlrev_b32_e32 v24, 16, v68
	v_and_b32_e32 v25, s99, v68
	v_lshlrev_b32_e32 v26, 16, v69
	v_and_b32_e32 v27, s99, v69
	v_lshlrev_b32_e32 v28, 16, v70
	v_and_b32_e32 v29, s99, v70
	v_lshlrev_b32_e32 v30, 16, v71
	v_and_b32_e32 v31, s99, v71
	v_add_u32_e32 v11, 109312, v5
	global_load_dwordx4 v[64:67], v11, s[2:3] offset:-2816
	global_load_dwordx4 v[68:71], v11, s[2:3] offset:2816
	s_waitcnt vmcnt(24)
	v_lshlrev_b32_e32 v32, 16, v72
	v_and_b32_e32 v33, s99, v72
	v_lshlrev_b32_e32 v34, 16, v73
	v_and_b32_e32 v35, s99, v73
	v_lshlrev_b32_e32 v36, 16, v74
	v_and_b32_e32 v37, s99, v74
	v_lshlrev_b32_e32 v38, 16, v75
	v_and_b32_e32 v39, s99, v75
	v_lshlrev_b32_e32 v40, 16, v76
	v_and_b32_e32 v41, s99, v76
	v_lshlrev_b32_e32 v42, 16, v77
	v_and_b32_e32 v43, s99, v77
	v_lshlrev_b32_e32 v44, 16, v78
	v_and_b32_e32 v45, s99, v78
	v_lshlrev_b32_e32 v46, 16, v79
	v_and_b32_e32 v47, s99, v79
	v_add_u32_e32 v10, 120576, v5
	global_load_dwordx4 v[72:75], v10, s[2:3] offset:-2816
	global_load_dwordx4 v[76:79], v10, s[2:3] offset:2816
	s_waitcnt vmcnt(23)
	v_lshlrev_b32_e32 v48, 16, v80
	v_and_b32_e32 v49, s99, v80
	v_lshlrev_b32_e32 v50, 16, v81
	v_and_b32_e32 v51, s99, v81
	v_lshlrev_b32_e32 v52, 16, v82
	v_and_b32_e32 v53, s99, v82
	v_lshlrev_b32_e32 v54, 16, v83
	v_and_b32_e32 v55, s99, v83
	v_lshlrev_b32_e32 v56, 16, v84
	v_and_b32_e32 v57, s99, v84
	v_lshlrev_b32_e32 v58, 16, v85
	v_and_b32_e32 v59, s99, v85
	v_lshlrev_b32_e32 v60, 16, v86
	v_and_b32_e32 v61, s99, v86
	v_lshlrev_b32_e32 v62, 16, v87
	v_and_b32_e32 v63, s99, v87
	v_add_u32_e32 v11, 131840, v5
	global_load_dwordx4 v[80:83], v11, s[2:3] offset:-2816
	global_load_dwordx4 v[84:87], v11, s[2:3] offset:2816
	v_pk_fma_f32 v[136:137], v[16:17], v[152:153], v[236:237]
	v_pk_fma_f32 v[196:197], v[24:25], v[212:213], v[244:245]
	v_pk_fma_f32 v[138:139], v[18:19], v[154:155], v[238:239]
	v_pk_fma_f32 v[198:199], v[26:27], v[214:215], v[246:247]
	v_pk_fma_f32 v[140:141], v[20:21], v[156:157], v[240:241]
	v_pk_fma_f32 v[200:201], v[28:29], v[216:217], v[248:249]
	v_pk_fma_f32 v[142:143], v[22:23], v[158:159], v[242:243]
	v_pk_fma_f32 v[202:203], v[30:31], v[218:219], v[250:251]
	v_pk_fma_f32 v[136:137], v[32:33], v[160:161], v[136:137]
	v_pk_fma_f32 v[196:197], v[40:41], v[220:221], v[196:197]
	v_pk_fma_f32 v[138:139], v[34:35], v[162:163], v[138:139]
	v_pk_fma_f32 v[198:199], v[42:43], v[222:223], v[198:199]
	v_pk_fma_f32 v[140:141], v[36:37], v[164:165], v[140:141]
	v_pk_fma_f32 v[200:201], v[44:45], v[224:225], v[200:201]
	v_pk_fma_f32 v[142:143], v[38:39], v[166:167], v[142:143]
	v_pk_fma_f32 v[202:203], v[46:47], v[226:227], v[202:203]
	v_pk_fma_f32 v[136:137], v[48:49], v[168:169], v[136:137]
	v_pk_fma_f32 v[196:197], v[56:57], v[228:229], v[196:197]
	v_pk_fma_f32 v[138:139], v[50:51], v[170:171], v[138:139]
	v_pk_fma_f32 v[198:199], v[58:59], v[230:231], v[198:199]
	v_pk_fma_f32 v[140:141], v[52:53], v[172:173], v[140:141]
	v_pk_fma_f32 v[200:201], v[60:61], v[232:233], v[200:201]
	v_pk_fma_f32 v[142:143], v[54:55], v[174:175], v[142:143]
	v_pk_fma_f32 v[202:203], v[62:63], v[234:235], v[202:203]
	v_pk_mul_f32 v[184:185], v[136:137], v[180:181]
	v_pk_mul_f32 v[186:187], v[138:139], v[180:181]
	v_pk_mul_f32 v[188:189], v[140:141], v[180:181]
	v_pk_mul_f32 v[190:191], v[142:143], v[180:181]
	v_exp_f32_e32 v184, v184
	v_exp_f32_e32 v185, v185
	v_exp_f32_e32 v186, v186
	v_exp_f32_e32 v187, v187
	v_exp_f32_e32 v188, v188
	v_exp_f32_e32 v189, v189
	v_exp_f32_e32 v190, v190
	v_exp_f32_e32 v191, v191
	s_nop 0
	v_pk_add_f32 v[184:185], v[184:185], v[144:145]
	v_pk_add_f32 v[186:187], v[186:187], v[144:145]
	v_pk_add_f32 v[188:189], v[188:189], v[144:145]
	v_pk_add_f32 v[190:191], v[190:191], v[144:145]
	v_rcp_f32_e32 v184, v184
	v_rcp_f32_e32 v185, v185
	v_rcp_f32_e32 v186, v186
	v_rcp_f32_e32 v187, v187
	v_rcp_f32_e32 v188, v188
	v_rcp_f32_e32 v189, v189
	v_rcp_f32_e32 v190, v190
	v_rcp_f32_e32 v191, v191
	s_nop 0
	v_pk_mul_f32 v[136:137], v[136:137], v[184:185]
	v_pk_mul_f32 v[138:139], v[138:139], v[186:187]
	v_pk_mul_f32 v[140:141], v[140:141], v[188:189]
	v_pk_mul_f32 v[142:143], v[142:143], v[190:191]
	v_pk_mul_f32 v[136:137], v[136:137], v[196:197]
	v_pk_mul_f32 v[138:139], v[138:139], v[198:199]
	v_pk_mul_f32 v[140:141], v[140:141], v[200:201]
	v_pk_mul_f32 v[142:143], v[142:143], v[202:203]
	v_cvt_pk_bf16_f32 v12, v136, v137
	v_cvt_pk_bf16_f32 v13, v138, v139
	v_cvt_pk_bf16_f32 v14, v140, v141
	v_cvt_pk_bf16_f32 v15, v142, v143
	global_store_dwordx4 v6, v[12:15], s[30:31]
	v_add_u32_e32 v6, 5632, v6
	s_waitcnt vmcnt(23)
; __device__ __forceinline__ unsigned cvt_pk_bf16(float lo, float hi) { unsigned r; asm volatile("v_cvt_pk_bf16_f32 %0, %1, %2" : "=v"(r) : "v"(lo), "v"(hi)); return r; }
; __device__ __forceinline__ float silu_f(float x) { return x * __builtin_amdgcn_rcpf(1.0f + __builtin_amdgcn_exp2f(-LOG2E * x)); }
; __device__ __forceinline__ float bflo(unsigned w) { return __uint_as_float(w << 16); }
; __device__ __forceinline__ float bfhi(unsigned w) { return __uint_as_float(w & 0xffff0000u); }
; __device__ __forceinline__ void conv_phase(const bf16_t* Z, bf16_t* UA, const float* cw, const float* cb, int nrows, int rowoff) {
;     ...
;         for (int rr = 0; rr < 16; ++rr) {
;             u32x4 na = zero, ng = zero; if (rr < 15 || has_right) { na = *(const u32x4*)(zp + (size_t)(rr + 1) * FFN2); ng = *(const u32x4*)(zp + (size_t)(rr + 1) * FFN2 + FFN); }
;             u32x4 o;
; #pragma unroll
;             for (int e2 = 0; e2 < 4; ++e2) {
;                 const float a0 = bflo(pa[e2]) * wa[0][2 * e2] + bflo(ca[e2]) * wa[1][2 * e2] + bflo(na[e2]) * wa[2][2 * e2] + ba[2 * e2];
;                 const float a1 = bfhi(pa[e2]) * wa[0][2 * e2 + 1] + bfhi(ca[e2]) * wa[1][2 * e2 + 1] + bfhi(na[e2]) * wa[2][2 * e2 + 1] + ba[2 * e2 + 1];
;                 const float g0 = bflo(pg[e2]) * wg[0][2 * e2] + bflo(cgv[e2]) * wg[1][2 * e2] + bflo(ng[e2]) * wg[2][2 * e2] + bg[2 * e2];
;                 const float g1 = bfhi(pg[e2]) * wg[0][2 * e2 + 1] + bfhi(cgv[e2]) * wg[1][2 * e2 + 1] + bfhi(ng[e2]) * wg[2][2 * e2 + 1] + bg[2 * e2 + 1];
;                 o[e2] = cvt_pk_bf16(silu_f(a0) * g0, silu_f(a1) * g1); }
;             *(u32x4*)(UA + (size_t)(r0 + rr) * FFN + c0) = o;
;             pa = ca; pg = cgv; ca = na; cgv = ng;
	v_lshlrev_b32_e32 v16, 16, v88
	v_and_b32_e32 v17, s99, v88
	v_lshlrev_b32_e32 v18, 16, v89
	v_and_b32_e32 v19, s99, v89
	v_lshlrev_b32_e32 v20, 16, v90
	v_and_b32_e32 v21, s99, v90
	v_lshlrev_b32_e32 v22, 16, v91
	v_and_b32_e32 v23, s99, v91
	v_lshlrev_b32_e32 v24, 16, v92
	v_and_b32_e32 v25, s99, v92
	v_lshlrev_b32_e32 v26, 16, v93
	v_and_b32_e32 v27, s99, v93
	v_lshlrev_b32_e32 v28, 16, v94
	v_and_b32_e32 v29, s99, v94
	v_lshlrev_b32_e32 v30, 16, v95
	v_and_b32_e32 v31, s99, v95
	v_add_u32_e32 v10, 143104, v5
	global_load_dwordx4 v[88:91], v10, s[2:3] offset:-2816
	global_load_dwordx4 v[92:95], v10, s[2:3] offset:2816
	v_pk_fma_f32 v[136:137], v[32:33], v[152:153], v[236:237]
	v_pk_fma_f32 v[196:197], v[40:41], v[212:213], v[244:245]
	v_pk_fma_f32 v[138:139], v[34:35], v[154:155], v[238:239]
	v_pk_fma_f32 v[198:199], v[42:43], v[214:215], v[246:247]
	v_pk_fma_f32 v[140:141], v[36:37], v[156:157], v[240:241]
	v_pk_fma_f32 v[200:201], v[44:45], v[216:217], v[248:249]
	v_pk_fma_f32 v[142:143], v[38:39], v[158:159], v[242:243]
	v_pk_fma_f32 v[202:203], v[46:47], v[218:219], v[250:251]
	v_pk_fma_f32 v[136:137], v[48:49], v[160:161], v[136:137]
	v_pk_fma_f32 v[196:197], v[56:57], v[220:221], v[196:197]
	v_pk_fma_f32 v[138:139], v[50:51], v[162:163], v[138:139]
	v_pk_fma_f32 v[198:199], v[58:59], v[222:223], v[198:199]
	v_pk_fma_f32 v[140:141], v[52:53], v[164:165], v[140:141]
	v_pk_fma_f32 v[200:201], v[60:61], v[224:225], v[200:201]
	v_pk_fma_f32 v[142:143], v[54:55], v[166:167], v[142:143]
	v_pk_fma_f32 v[202:203], v[62:63], v[226:227], v[202:203]
	v_pk_fma_f32 v[136:137], v[16:17], v[168:169], v[136:137]
	v_pk_fma_f32 v[196:197], v[24:25], v[228:229], v[196:197]
	v_pk_fma_f32 v[138:139], v[18:19], v[170:171], v[138:139]
	v_pk_fma_f32 v[198:199], v[26:27], v[230:231], v[198:199]
	v_pk_fma_f32 v[140:141], v[20:21], v[172:173], v[140:141]
	v_pk_fma_f32 v[200:201], v[28:29], v[232:233], v[200:201]
	v_pk_fma_f32 v[142:143], v[22:23], v[174:175], v[142:143]
	v_pk_fma_f32 v[202:203], v[30:31], v[234:235], v[202:203]
	v_pk_mul_f32 v[184:185], v[136:137], v[180:181]
	v_pk_mul_f32 v[186:187], v[138:139], v[180:181]
	v_pk_mul_f32 v[188:189], v[140:141], v[180:181]
	v_pk_mul_f32 v[190:191], v[142:143], v[180:181]
	v_exp_f32_e32 v184, v184
	v_exp_f32_e32 v185, v185
	v_exp_f32_e32 v186, v186
	v_exp_f32_e32 v187, v187
	v_exp_f32_e32 v188, v188
	v_exp_f32_e32 v189, v189
	v_exp_f32_e32 v190, v190
	v_exp_f32_e32 v191, v191
	s_nop 0
	v_pk_add_f32 v[184:185], v[184:185], v[144:145]
	v_pk_add_f32 v[186:187], v[186:187], v[144:145]
	v_pk_add_f32 v[188:189], v[188:189], v[144:145]
	v_pk_add_f32 v[190:191], v[190:191], v[144:145]
	v_rcp_f32_e32 v184, v184
	v_rcp_f32_e32 v185, v185
	v_rcp_f32_e32 v186, v186
	v_rcp_f32_e32 v187, v187
	v_rcp_f32_e32 v188, v188
	v_rcp_f32_e32 v189, v189
	v_rcp_f32_e32 v190, v190
	v_rcp_f32_e32 v191, v191
	s_nop 0
	v_pk_mul_f32 v[136:137], v[136:137], v[184:185]
	v_pk_mul_f32 v[138:139], v[138:139], v[186:187]
	v_pk_mul_f32 v[140:141], v[140:141], v[188:189]
	v_pk_mul_f32 v[142:143], v[142:143], v[190:191]
	v_pk_mul_f32 v[136:137], v[136:137], v[196:197]
	v_pk_mul_f32 v[138:139], v[138:139], v[198:199]
	v_pk_mul_f32 v[140:141], v[140:141], v[200:201]
	v_pk_mul_f32 v[142:143], v[142:143], v[202:203]
	v_cvt_pk_bf16_f32 v12, v136, v137
	v_cvt_pk_bf16_f32 v13, v138, v139
	v_cvt_pk_bf16_f32 v14, v140, v141
	v_cvt_pk_bf16_f32 v15, v142, v143
	global_store_dwordx4 v6, v[12:15], s[30:31]
	v_add_u32_e32 v6, 5632, v6
	s_waitcnt vmcnt(23)
	v_lshlrev_b32_e32 v32, 16, v96
	v_and_b32_e32 v33, s99, v96
	v_lshlrev_b32_e32 v34, 16, v97
	v_and_b32_e32 v35, s99, v97
	v_lshlrev_b32_e32 v36, 16, v98
	v_and_b32_e32 v37, s99, v98
	v_lshlrev_b32_e32 v38, 16, v99
	v_and_b32_e32 v39, s99, v99
	v_lshlrev_b32_e32 v40, 16, v100
	v_and_b32_e32 v41, s99, v100
	v_lshlrev_b32_e32 v42, 16, v101
	v_and_b32_e32 v43, s99, v101
	v_lshlrev_b32_e32 v44, 16, v102
	v_and_b32_e32 v45, s99, v102
	v_lshlrev_b32_e32 v46, 16, v103
	v_and_b32_e32 v47, s99, v103
	v_add_u32_e32 v11, 154368, v5
	global_load_dwordx4 v[96:99], v11, s[2:3] offset:-2816
	global_load_dwordx4 v[100:103], v11, s[2:3] offset:2816
	v_pk_fma_f32 v[136:137], v[48:49], v[152:153], v[236:237]
	v_pk_fma_f32 v[196:197], v[56:57], v[212:213], v[244:245]
	v_pk_fma_f32 v[138:139], v[50:51], v[154:155], v[238:239]
	v_pk_fma_f32 v[198:199], v[58:59], v[214:215], v[246:247]
	v_pk_fma_f32 v[140:141], v[52:53], v[156:157], v[240:241]
	v_pk_fma_f32 v[200:201], v[60:61], v[216:217], v[248:249]
	v_pk_fma_f32 v[142:143], v[54:55], v[158:159], v[242:243]
	v_pk_fma_f32 v[202:203], v[62:63], v[218:219], v[250:251]
	v_pk_fma_f32 v[136:137], v[16:17], v[160:161], v[136:137]
	v_pk_fma_f32 v[196:197], v[24:25], v[220:221], v[196:197]
	v_pk_fma_f32 v[138:139], v[18:19], v[162:163], v[138:139]
	v_pk_fma_f32 v[198:199], v[26:27], v[222:223], v[198:199]
	v_pk_fma_f32 v[140:141], v[20:21], v[164:165], v[140:141]
	v_pk_fma_f32 v[200:201], v[28:29], v[224:225], v[200:201]
	v_pk_fma_f32 v[142:143], v[22:23], v[166:167], v[142:143]
	v_pk_fma_f32 v[202:203], v[30:31], v[226:227], v[202:203]
	v_pk_fma_f32 v[136:137], v[32:33], v[168:169], v[136:137]
	v_pk_fma_f32 v[196:197], v[40:41], v[228:229], v[196:197]
	v_pk_fma_f32 v[138:139], v[34:35], v[170:171], v[138:139]
	v_pk_fma_f32 v[198:199], v[42:43], v[230:231], v[198:199]
	v_pk_fma_f32 v[140:141], v[36:37], v[172:173], v[140:141]
	v_pk_fma_f32 v[200:201], v[44:45], v[232:233], v[200:201]
	v_pk_fma_f32 v[142:143], v[38:39], v[174:175], v[142:143]
	v_pk_fma_f32 v[202:203], v[46:47], v[234:235], v[202:203]
	v_pk_mul_f32 v[184:185], v[136:137], v[180:181]
	v_pk_mul_f32 v[186:187], v[138:139], v[180:181]
	v_pk_mul_f32 v[188:189], v[140:141], v[180:181]
	v_pk_mul_f32 v[190:191], v[142:143], v[180:181]
	v_exp_f32_e32 v184, v184
	v_exp_f32_e32 v185, v185
	v_exp_f32_e32 v186, v186
	v_exp_f32_e32 v187, v187
	v_exp_f32_e32 v188, v188
	v_exp_f32_e32 v189, v189
	v_exp_f32_e32 v190, v190
	v_exp_f32_e32 v191, v191
	s_nop 0
	v_pk_add_f32 v[184:185], v[184:185], v[144:145]
	v_pk_add_f32 v[186:187], v[186:187], v[144:145]
	v_pk_add_f32 v[188:189], v[188:189], v[144:145]
	v_pk_add_f32 v[190:191], v[190:191], v[144:145]
	v_rcp_f32_e32 v184, v184
	v_rcp_f32_e32 v185, v185
	v_rcp_f32_e32 v186, v186
	v_rcp_f32_e32 v187, v187
	v_rcp_f32_e32 v188, v188
	v_rcp_f32_e32 v189, v189
	v_rcp_f32_e32 v190, v190
	v_rcp_f32_e32 v191, v191
	s_nop 0
	v_pk_mul_f32 v[136:137], v[136:137], v[184:185]
	v_pk_mul_f32 v[138:139], v[138:139], v[186:187]
	v_pk_mul_f32 v[140:141], v[140:141], v[188:189]
	v_pk_mul_f32 v[142:143], v[142:143], v[190:191]
	v_pk_mul_f32 v[136:137], v[136:137], v[196:197]
	v_pk_mul_f32 v[138:139], v[138:139], v[198:199]
	v_pk_mul_f32 v[140:141], v[140:141], v[200:201]
	v_pk_mul_f32 v[142:143], v[142:143], v[202:203]
	v_cvt_pk_bf16_f32 v12, v136, v137
	v_cvt_pk_bf16_f32 v13, v138, v139
	v_cvt_pk_bf16_f32 v14, v140, v141
	v_cvt_pk_bf16_f32 v15, v142, v143
	global_store_dwordx4 v6, v[12:15], s[30:31]
	v_add_u32_e32 v6, 5632, v6
	s_waitcnt vmcnt(23)
; __device__ __forceinline__ unsigned cvt_pk_bf16(float lo, float hi) { unsigned r; asm volatile("v_cvt_pk_bf16_f32 %0, %1, %2" : "=v"(r) : "v"(lo), "v"(hi)); return r; }
; __device__ __forceinline__ float silu_f(float x) { return x * __builtin_amdgcn_rcpf(1.0f + __builtin_amdgcn_exp2f(-LOG2E * x)); }
; __device__ __forceinline__ float bflo(unsigned w) { return __uint_as_float(w << 16); }
; __device__ __forceinline__ float bfhi(unsigned w) { return __uint_as_float(w & 0xffff0000u); }
; __device__ __forceinline__ void conv_phase(const bf16_t* Z, bf16_t* UA, const float* cw, const float* cb, int nrows, int rowoff) {
;     ...
;         for (int rr = 0; rr < 16; ++rr) {
;             u32x4 na = zero, ng = zero; if (rr < 15 || has_right) { na = *(const u32x4*)(zp + (size_t)(rr + 1) * FFN2); ng = *(const u32x4*)(zp + (size_t)(rr + 1) * FFN2 + FFN); }
;             u32x4 o;
; #pragma unroll
;             for (int e2 = 0; e2 < 4; ++e2) {
;                 const float a0 = bflo(pa[e2]) * wa[0][2 * e2] + bflo(ca[e2]) * wa[1][2 * e2] + bflo(na[e2]) * wa[2][2 * e2] + ba[2 * e2];
;                 const float a1 = bfhi(pa[e2]) * wa[0][2 * e2 + 1] + bfhi(ca[e2]) * wa[1][2 * e2 + 1] + bfhi(na[e2]) * wa[2][2 * e2 + 1] + ba[2 * e2 + 1];
;                 const float g0 = bflo(pg[e2]) * wg[0][2 * e2] + bflo(cgv[e2]) * wg[1][2 * e2] + bflo(ng[e2]) * wg[2][2 * e2] + bg[2 * e2];
;                 const float g1 = bfhi(pg[e2]) * wg[0][2 * e2 + 1] + bfhi(cgv[e2]) * wg[1][2 * e2 + 1] + bfhi(ng[e2]) * wg[2][2 * e2 + 1] + bg[2 * e2 + 1];
;                 o[e2] = cvt_pk_bf16(silu_f(a0) * g0, silu_f(a1) * g1); }
;             *(u32x4*)(UA + (size_t)(r0 + rr) * FFN + c0) = o;
;             pa = ca; pg = cgv; ca = na; cgv = ng;
	v_lshlrev_b32_e32 v48, 16, v104
	v_and_b32_e32 v49, s99, v104
	v_lshlrev_b32_e32 v50, 16, v105
	v_and_b32_e32 v51, s99, v105
	v_lshlrev_b32_e32 v52, 16, v106
	v_and_b32_e32 v53, s99, v106
	v_lshlrev_b32_e32 v54, 16, v107
	v_and_b32_e32 v55, s99, v107
	v_lshlrev_b32_e32 v56, 16, v108
	v_and_b32_e32 v57, s99, v108
	v_lshlrev_b32_e32 v58, 16, v109
	v_and_b32_e32 v59, s99, v109
	v_lshlrev_b32_e32 v60, 16, v110
	v_and_b32_e32 v61, s99, v110
	v_lshlrev_b32_e32 v62, 16, v111
	v_and_b32_e32 v63, s99, v111
	v_add_u32_e32 v10, 165632, v5
	global_load_dwordx4 v[104:107], v10, s[2:3] offset:-2816
	global_load_dwordx4 v[108:111], v10, s[2:3] offset:2816
	v_pk_fma_f32 v[136:137], v[16:17], v[152:153], v[236:237]
	v_pk_fma_f32 v[196:197], v[24:25], v[212:213], v[244:245]
	v_pk_fma_f32 v[138:139], v[18:19], v[154:155], v[238:239]
	v_pk_fma_f32 v[198:199], v[26:27], v[214:215], v[246:247]
	v_pk_fma_f32 v[140:141], v[20:21], v[156:157], v[240:241]
	v_pk_fma_f32 v[200:201], v[28:29], v[216:217], v[248:249]
	v_pk_fma_f32 v[142:143], v[22:23], v[158:159], v[242:243]
	v_pk_fma_f32 v[202:203], v[30:31], v[218:219], v[250:251]
	v_pk_fma_f32 v[136:137], v[32:33], v[160:161], v[136:137]
	v_pk_fma_f32 v[196:197], v[40:41], v[220:221], v[196:197]
	v_pk_fma_f32 v[138:139], v[34:35], v[162:163], v[138:139]
	v_pk_fma_f32 v[198:199], v[42:43], v[222:223], v[198:199]
	v_pk_fma_f32 v[140:141], v[36:37], v[164:165], v[140:141]
	v_pk_fma_f32 v[200:201], v[44:45], v[224:225], v[200:201]
	v_pk_fma_f32 v[142:143], v[38:39], v[166:167], v[142:143]
	v_pk_fma_f32 v[202:203], v[46:47], v[226:227], v[202:203]
	v_pk_fma_f32 v[136:137], v[48:49], v[168:169], v[136:137]
	v_pk_fma_f32 v[196:197], v[56:57], v[228:229], v[196:197]
	v_pk_fma_f32 v[138:139], v[50:51], v[170:171], v[138:139]
	v_pk_fma_f32 v[198:199], v[58:59], v[230:231], v[198:199]
	v_pk_fma_f32 v[140:141], v[52:53], v[172:173], v[140:141]
	v_pk_fma_f32 v[200:201], v[60:61], v[232:233], v[200:201]
	v_pk_fma_f32 v[142:143], v[54:55], v[174:175], v[142:143]
	v_pk_fma_f32 v[202:203], v[62:63], v[234:235], v[202:203]
	v_pk_mul_f32 v[184:185], v[136:137], v[180:181]
	v_pk_mul_f32 v[186:187], v[138:139], v[180:181]
	v_pk_mul_f32 v[188:189], v[140:141], v[180:181]
	v_pk_mul_f32 v[190:191], v[142:143], v[180:181]
	v_exp_f32_e32 v184, v184
	v_exp_f32_e32 v185, v185
	v_exp_f32_e32 v186, v186
	v_exp_f32_e32 v187, v187
	v_exp_f32_e32 v188, v188
	v_exp_f32_e32 v189, v189
	v_exp_f32_e32 v190, v190
	v_exp_f32_e32 v191, v191
	s_nop 0
	v_pk_add_f32 v[184:185], v[184:185], v[144:145]
	v_pk_add_f32 v[186:187], v[186:187], v[144:145]
	v_pk_add_f32 v[188:189], v[188:189], v[144:145]
	v_pk_add_f32 v[190:191], v[190:191], v[144:145]
	v_rcp_f32_e32 v184, v184
	v_rcp_f32_e32 v185, v185
	v_rcp_f32_e32 v186, v186
	v_rcp_f32_e32 v187, v187
	v_rcp_f32_e32 v188, v188
	v_rcp_f32_e32 v189, v189
	v_rcp_f32_e32 v190, v190
	v_rcp_f32_e32 v191, v191
	s_nop 0
	v_pk_mul_f32 v[136:137], v[136:137], v[184:185]
	v_pk_mul_f32 v[138:139], v[138:139], v[186:187]
	v_pk_mul_f32 v[140:141], v[140:141], v[188:189]
	v_pk_mul_f32 v[142:143], v[142:143], v[190:191]
	v_pk_mul_f32 v[136:137], v[136:137], v[196:197]
	v_pk_mul_f32 v[138:139], v[138:139], v[198:199]
	v_pk_mul_f32 v[140:141], v[140:141], v[200:201]
	v_pk_mul_f32 v[142:143], v[142:143], v[202:203]
	v_cvt_pk_bf16_f32 v12, v136, v137
	v_cvt_pk_bf16_f32 v13, v138, v139
	v_cvt_pk_bf16_f32 v14, v140, v141
	v_cvt_pk_bf16_f32 v15, v142, v143
	global_store_dwordx4 v6, v[12:15], s[30:31]
	v_add_u32_e32 v6, 5632, v6
	s_waitcnt vmcnt(23)
	v_lshlrev_b32_e32 v16, 16, v112
	v_and_b32_e32 v17, s99, v112
	v_lshlrev_b32_e32 v18, 16, v113
	v_and_b32_e32 v19, s99, v113
	v_lshlrev_b32_e32 v20, 16, v114
	v_and_b32_e32 v21, s99, v114
	v_lshlrev_b32_e32 v22, 16, v115
	v_and_b32_e32 v23, s99, v115
	v_lshlrev_b32_e32 v24, 16, v116
	v_and_b32_e32 v25, s99, v116
	v_lshlrev_b32_e32 v26, 16, v117
	v_and_b32_e32 v27, s99, v117
	v_lshlrev_b32_e32 v28, 16, v118
	v_and_b32_e32 v29, s99, v118
	v_lshlrev_b32_e32 v30, 16, v119
	v_and_b32_e32 v31, s99, v119
	v_add_u32_e32 v11, 176896, v5
	global_load_dwordx4 v[112:115], v11, s[2:3] offset:-2816
	global_load_dwordx4 v[116:119], v11, s[2:3] offset:2816
	v_pk_fma_f32 v[136:137], v[32:33], v[152:153], v[236:237]
	v_pk_fma_f32 v[196:197], v[40:41], v[212:213], v[244:245]
	v_pk_fma_f32 v[138:139], v[34:35], v[154:155], v[238:239]
	v_pk_fma_f32 v[198:199], v[42:43], v[214:215], v[246:247]
	v_pk_fma_f32 v[140:141], v[36:37], v[156:157], v[240:241]
	v_pk_fma_f32 v[200:201], v[44:45], v[216:217], v[248:249]
	v_pk_fma_f32 v[142:143], v[38:39], v[158:159], v[242:243]
	v_pk_fma_f32 v[202:203], v[46:47], v[218:219], v[250:251]
	v_pk_fma_f32 v[136:137], v[48:49], v[160:161], v[136:137]
	v_pk_fma_f32 v[196:197], v[56:57], v[220:221], v[196:197]
	v_pk_fma_f32 v[138:139], v[50:51], v[162:163], v[138:139]
	v_pk_fma_f32 v[198:199], v[58:59], v[222:223], v[198:199]
	v_pk_fma_f32 v[140:141], v[52:53], v[164:165], v[140:141]
	v_pk_fma_f32 v[200:201], v[60:61], v[224:225], v[200:201]
	v_pk_fma_f32 v[142:143], v[54:55], v[166:167], v[142:143]
	v_pk_fma_f32 v[202:203], v[62:63], v[226:227], v[202:203]
	v_pk_fma_f32 v[136:137], v[16:17], v[168:169], v[136:137]
	v_pk_fma_f32 v[196:197], v[24:25], v[228:229], v[196:197]
	v_pk_fma_f32 v[138:139], v[18:19], v[170:171], v[138:139]
	v_pk_fma_f32 v[198:199], v[26:27], v[230:231], v[198:199]
	v_pk_fma_f32 v[140:141], v[20:21], v[172:173], v[140:141]
	v_pk_fma_f32 v[200:201], v[28:29], v[232:233], v[200:201]
	v_pk_fma_f32 v[142:143], v[22:23], v[174:175], v[142:143]
	v_pk_fma_f32 v[202:203], v[30:31], v[234:235], v[202:203]
	v_pk_mul_f32 v[184:185], v[136:137], v[180:181]
	v_pk_mul_f32 v[186:187], v[138:139], v[180:181]
	v_pk_mul_f32 v[188:189], v[140:141], v[180:181]
	v_pk_mul_f32 v[190:191], v[142:143], v[180:181]
	v_exp_f32_e32 v184, v184
	v_exp_f32_e32 v185, v185
	v_exp_f32_e32 v186, v186
	v_exp_f32_e32 v187, v187
	v_exp_f32_e32 v188, v188
	v_exp_f32_e32 v189, v189
	v_exp_f32_e32 v190, v190
	v_exp_f32_e32 v191, v191
	s_nop 0
	v_pk_add_f32 v[184:185], v[184:185], v[144:145]
	v_pk_add_f32 v[186:187], v[186:187], v[144:145]
	v_pk_add_f32 v[188:189], v[188:189], v[144:145]
	v_pk_add_f32 v[190:191], v[190:191], v[144:145]
	v_rcp_f32_e32 v184, v184
	v_rcp_f32_e32 v185, v185
	v_rcp_f32_e32 v186, v186
	v_rcp_f32_e32 v187, v187
	v_rcp_f32_e32 v188, v188
	v_rcp_f32_e32 v189, v189
	v_rcp_f32_e32 v190, v190
	v_rcp_f32_e32 v191, v191
	s_nop 0
	v_pk_mul_f32 v[136:137], v[136:137], v[184:185]
	v_pk_mul_f32 v[138:139], v[138:139], v[186:187]
	v_pk_mul_f32 v[140:141], v[140:141], v[188:189]
	v_pk_mul_f32 v[142:143], v[142:143], v[190:191]
	v_pk_mul_f32 v[136:137], v[136:137], v[196:197]
	v_pk_mul_f32 v[138:139], v[138:139], v[198:199]
	v_pk_mul_f32 v[140:141], v[140:141], v[200:201]
	v_pk_mul_f32 v[142:143], v[142:143], v[202:203]
	v_cvt_pk_bf16_f32 v12, v136, v137
	v_cvt_pk_bf16_f32 v13, v138, v139
	v_cvt_pk_bf16_f32 v14, v140, v141
	v_cvt_pk_bf16_f32 v15, v142, v143
	global_store_dwordx4 v6, v[12:15], s[30:31]
	v_add_u32_e32 v6, 5632, v6
	s_waitcnt vmcnt(23)
; __device__ __forceinline__ unsigned cvt_pk_bf16(float lo, float hi) { unsigned r; asm volatile("v_cvt_pk_bf16_f32 %0, %1, %2" : "=v"(r) : "v"(lo), "v"(hi)); return r; }
; __device__ __forceinline__ float silu_f(float x) { return x * __builtin_amdgcn_rcpf(1.0f + __builtin_amdgcn_exp2f(-LOG2E * x)); }
; __device__ __forceinline__ float bflo(unsigned w) { return __uint_as_float(w << 16); }
; __device__ __forceinline__ float bfhi(unsigned w) { return __uint_as_float(w & 0xffff0000u); }
; __device__ __forceinline__ void conv_phase(const bf16_t* Z, bf16_t* UA, const float* cw, const float* cb, int nrows, int rowoff) {
;     ...
;         for (int rr = 0; rr < 16; ++rr) {
;             u32x4 na = zero, ng = zero; if (rr < 15 || has_right) { na = *(const u32x4*)(zp + (size_t)(rr + 1) * FFN2); ng = *(const u32x4*)(zp + (size_t)(rr + 1) * FFN2 + FFN); }
;             u32x4 o;
; #pragma unroll
;             for (int e2 = 0; e2 < 4; ++e2) {
;                 const float a0 = bflo(pa[e2]) * wa[0][2 * e2] + bflo(ca[e2]) * wa[1][2 * e2] + bflo(na[e2]) * wa[2][2 * e2] + ba[2 * e2];
;                 const float a1 = bfhi(pa[e2]) * wa[0][2 * e2 + 1] + bfhi(ca[e2]) * wa[1][2 * e2 + 1] + bfhi(na[e2]) * wa[2][2 * e2 + 1] + ba[2 * e2 + 1];
;                 const float g0 = bflo(pg[e2]) * wg[0][2 * e2] + bflo(cgv[e2]) * wg[1][2 * e2] + bflo(ng[e2]) * wg[2][2 * e2] + bg[2 * e2];
;                 const float g1 = bfhi(pg[e2]) * wg[0][2 * e2 + 1] + bfhi(cgv[e2]) * wg[1][2 * e2 + 1] + bfhi(ng[e2]) * wg[2][2 * e2 + 1] + bg[2 * e2 + 1];
;                 o[e2] = cvt_pk_bf16(silu_f(a0) * g0, silu_f(a1) * g1); }
;             *(u32x4*)(UA + (size_t)(r0 + rr) * FFN + c0) = o;
;             pa = ca; pg = cgv; ca = na; cgv = ng;
	v_lshlrev_b32_e32 v32, 16, v120
	v_and_b32_e32 v33, s99, v120
	v_lshlrev_b32_e32 v34, 16, v121
	v_and_b32_e32 v35, s99, v121
	v_lshlrev_b32_e32 v36, 16, v122
	v_and_b32_e32 v37, s99, v122
	v_lshlrev_b32_e32 v38, 16, v123
	v_and_b32_e32 v39, s99, v123
	v_lshlrev_b32_e32 v40, 16, v124
	v_and_b32_e32 v41, s99, v124
	v_lshlrev_b32_e32 v42, 16, v125
	v_and_b32_e32 v43, s99, v125
	v_lshlrev_b32_e32 v44, 16, v126
	v_and_b32_e32 v45, s99, v126
	v_lshlrev_b32_e32 v46, 16, v127
	v_and_b32_e32 v47, s99, v127
	v_add_u32_e32 v10, 188160, v5
	global_load_dwordx4 v[120:123], v10, s[2:3] offset:-2816
	global_load_dwordx4 v[124:127], v10, s[2:3] offset:2816
	v_pk_fma_f32 v[136:137], v[48:49], v[152:153], v[236:237]
	v_pk_fma_f32 v[196:197], v[56:57], v[212:213], v[244:245]
	v_pk_fma_f32 v[138:139], v[50:51], v[154:155], v[238:239]
	v_pk_fma_f32 v[198:199], v[58:59], v[214:215], v[246:247]
	v_pk_fma_f32 v[140:141], v[52:53], v[156:157], v[240:241]
	v_pk_fma_f32 v[200:201], v[60:61], v[216:217], v[248:249]
	v_pk_fma_f32 v[142:143], v[54:55], v[158:159], v[242:243]
	v_pk_fma_f32 v[202:203], v[62:63], v[218:219], v[250:251]
	v_pk_fma_f32 v[136:137], v[16:17], v[160:161], v[136:137]
	v_pk_fma_f32 v[196:197], v[24:25], v[220:221], v[196:197]
	v_pk_fma_f32 v[138:139], v[18:19], v[162:163], v[138:139]
	v_pk_fma_f32 v[198:199], v[26:27], v[222:223], v[198:199]
	v_pk_fma_f32 v[140:141], v[20:21], v[164:165], v[140:141]
	v_pk_fma_f32 v[200:201], v[28:29], v[224:225], v[200:201]
	v_pk_fma_f32 v[142:143], v[22:23], v[166:167], v[142:143]
	v_pk_fma_f32 v[202:203], v[30:31], v[226:227], v[202:203]
	v_pk_fma_f32 v[136:137], v[32:33], v[168:169], v[136:137]
	v_pk_fma_f32 v[196:197], v[40:41], v[228:229], v[196:197]
	v_pk_fma_f32 v[138:139], v[34:35], v[170:171], v[138:139]
	v_pk_fma_f32 v[198:199], v[42:43], v[230:231], v[198:199]
	v_pk_fma_f32 v[140:141], v[36:37], v[172:173], v[140:141]
	v_pk_fma_f32 v[200:201], v[44:45], v[232:233], v[200:201]
	v_pk_fma_f32 v[142:143], v[38:39], v[174:175], v[142:143]
	v_pk_fma_f32 v[202:203], v[46:47], v[234:235], v[202:203]
	v_pk_mul_f32 v[184:185], v[136:137], v[180:181]
	v_pk_mul_f32 v[186:187], v[138:139], v[180:181]
	v_pk_mul_f32 v[188:189], v[140:141], v[180:181]
	v_pk_mul_f32 v[190:191], v[142:143], v[180:181]
	v_exp_f32_e32 v184, v184
	v_exp_f32_e32 v185, v185
	v_exp_f32_e32 v186, v186
	v_exp_f32_e32 v187, v187
	v_exp_f32_e32 v188, v188
	v_exp_f32_e32 v189, v189
	v_exp_f32_e32 v190, v190
	v_exp_f32_e32 v191, v191
	s_nop 0
	v_pk_add_f32 v[184:185], v[184:185], v[144:145]
	v_pk_add_f32 v[186:187], v[186:187], v[144:145]
	v_pk_add_f32 v[188:189], v[188:189], v[144:145]
	v_pk_add_f32 v[190:191], v[190:191], v[144:145]
	v_rcp_f32_e32 v184, v184
	v_rcp_f32_e32 v185, v185
	v_rcp_f32_e32 v186, v186
	v_rcp_f32_e32 v187, v187
	v_rcp_f32_e32 v188, v188
	v_rcp_f32_e32 v189, v189
	v_rcp_f32_e32 v190, v190
	v_rcp_f32_e32 v191, v191
	s_nop 0
	v_pk_mul_f32 v[136:137], v[136:137], v[184:185]
	v_pk_mul_f32 v[138:139], v[138:139], v[186:187]
	v_pk_mul_f32 v[140:141], v[140:141], v[188:189]
	v_pk_mul_f32 v[142:143], v[142:143], v[190:191]
	v_pk_mul_f32 v[136:137], v[136:137], v[196:197]
	v_pk_mul_f32 v[138:139], v[138:139], v[198:199]
	v_pk_mul_f32 v[140:141], v[140:141], v[200:201]
	v_pk_mul_f32 v[142:143], v[142:143], v[202:203]
	v_cvt_pk_bf16_f32 v12, v136, v137
	v_cvt_pk_bf16_f32 v13, v138, v139
	v_cvt_pk_bf16_f32 v14, v140, v141
	v_cvt_pk_bf16_f32 v15, v142, v143
	global_store_dwordx4 v6, v[12:15], s[30:31]
	v_add_u32_e32 v6, 5632, v6
	s_waitcnt vmcnt(23)
	v_lshlrev_b32_e32 v48, 16, v128
	v_and_b32_e32 v49, s99, v128
	v_lshlrev_b32_e32 v50, 16, v129
	v_and_b32_e32 v51, s99, v129
	v_lshlrev_b32_e32 v52, 16, v130
	v_and_b32_e32 v53, s99, v130
	v_lshlrev_b32_e32 v54, 16, v131
	v_and_b32_e32 v55, s99, v131
	v_lshlrev_b32_e32 v56, 16, v132
	v_and_b32_e32 v57, s99, v132
	v_lshlrev_b32_e32 v58, 16, v133
	v_and_b32_e32 v59, s99, v133
	v_lshlrev_b32_e32 v60, 16, v134
	v_and_b32_e32 v61, s99, v134
	v_lshlrev_b32_e32 v62, 16, v135
	v_and_b32_e32 v63, s99, v135
	v_add_u32_e32 v11, 199424, v5
	global_load_dwordx4 v[128:131], v11, s[2:3] offset:-2816
	global_load_dwordx4 v[132:135], v11, s[2:3] offset:2816
	v_pk_fma_f32 v[136:137], v[16:17], v[152:153], v[236:237]
	v_pk_fma_f32 v[196:197], v[24:25], v[212:213], v[244:245]
	v_pk_fma_f32 v[138:139], v[18:19], v[154:155], v[238:239]
	v_pk_fma_f32 v[198:199], v[26:27], v[214:215], v[246:247]
	v_pk_fma_f32 v[140:141], v[20:21], v[156:157], v[240:241]
	v_pk_fma_f32 v[200:201], v[28:29], v[216:217], v[248:249]
	v_pk_fma_f32 v[142:143], v[22:23], v[158:159], v[242:243]
	v_pk_fma_f32 v[202:203], v[30:31], v[218:219], v[250:251]
	v_pk_fma_f32 v[136:137], v[32:33], v[160:161], v[136:137]
	v_pk_fma_f32 v[196:197], v[40:41], v[220:221], v[196:197]
	v_pk_fma_f32 v[138:139], v[34:35], v[162:163], v[138:139]
	v_pk_fma_f32 v[198:199], v[42:43], v[222:223], v[198:199]
	v_pk_fma_f32 v[140:141], v[36:37], v[164:165], v[140:141]
	v_pk_fma_f32 v[200:201], v[44:45], v[224:225], v[200:201]
	v_pk_fma_f32 v[142:143], v[38:39], v[166:167], v[142:143]
	v_pk_fma_f32 v[202:203], v[46:47], v[226:227], v[202:203]
	v_pk_fma_f32 v[136:137], v[48:49], v[168:169], v[136:137]
	v_pk_fma_f32 v[196:197], v[56:57], v[228:229], v[196:197]
	v_pk_fma_f32 v[138:139], v[50:51], v[170:171], v[138:139]
	v_pk_fma_f32 v[198:199], v[58:59], v[230:231], v[198:199]
	v_pk_fma_f32 v[140:141], v[52:53], v[172:173], v[140:141]
	v_pk_fma_f32 v[200:201], v[60:61], v[232:233], v[200:201]
	v_pk_fma_f32 v[142:143], v[54:55], v[174:175], v[142:143]
	v_pk_fma_f32 v[202:203], v[62:63], v[234:235], v[202:203]
	v_pk_mul_f32 v[184:185], v[136:137], v[180:181]
	v_pk_mul_f32 v[186:187], v[138:139], v[180:181]
	v_pk_mul_f32 v[188:189], v[140:141], v[180:181]
	v_pk_mul_f32 v[190:191], v[142:143], v[180:181]
	v_exp_f32_e32 v184, v184
	v_exp_f32_e32 v185, v185
	v_exp_f32_e32 v186, v186
	v_exp_f32_e32 v187, v187
	v_exp_f32_e32 v188, v188
	v_exp_f32_e32 v189, v189
	v_exp_f32_e32 v190, v190
	v_exp_f32_e32 v191, v191
	s_nop 0
	v_pk_add_f32 v[184:185], v[184:185], v[144:145]
	v_pk_add_f32 v[186:187], v[186:187], v[144:145]
	v_pk_add_f32 v[188:189], v[188:189], v[144:145]
	v_pk_add_f32 v[190:191], v[190:191], v[144:145]
	v_rcp_f32_e32 v184, v184
	v_rcp_f32_e32 v185, v185
	v_rcp_f32_e32 v186, v186
	v_rcp_f32_e32 v187, v187
	v_rcp_f32_e32 v188, v188
	v_rcp_f32_e32 v189, v189
	v_rcp_f32_e32 v190, v190
	v_rcp_f32_e32 v191, v191
	s_nop 0
	v_pk_mul_f32 v[136:137], v[136:137], v[184:185]
	v_pk_mul_f32 v[138:139], v[138:139], v[186:187]
	v_pk_mul_f32 v[140:141], v[140:141], v[188:189]
	v_pk_mul_f32 v[142:143], v[142:143], v[190:191]
	v_pk_mul_f32 v[136:137], v[136:137], v[196:197]
	v_pk_mul_f32 v[138:139], v[138:139], v[198:199]
	v_pk_mul_f32 v[140:141], v[140:141], v[200:201]
	v_pk_mul_f32 v[142:143], v[142:143], v[202:203]
	v_cvt_pk_bf16_f32 v12, v136, v137
	v_cvt_pk_bf16_f32 v13, v138, v139
	v_cvt_pk_bf16_f32 v14, v140, v141
	v_cvt_pk_bf16_f32 v15, v142, v143
	global_store_dwordx4 v6, v[12:15], s[30:31]
	v_add_u32_e32 v6, 5632, v6
	s_waitcnt vmcnt(23)
; __device__ __forceinline__ unsigned cvt_pk_bf16(float lo, float hi) { unsigned r; asm volatile("v_cvt_pk_bf16_f32 %0, %1, %2" : "=v"(r) : "v"(lo), "v"(hi)); return r; }
; __device__ __forceinline__ float silu_f(float x) { return x * __builtin_amdgcn_rcpf(1.0f + __builtin_amdgcn_exp2f(-LOG2E * x)); }
; __device__ __forceinline__ float bflo(unsigned w) { return __uint_as_float(w << 16); }
; __device__ __forceinline__ float bfhi(unsigned w) { return __uint_as_float(w & 0xffff0000u); }
; __device__ __forceinline__ void conv_phase(const bf16_t* Z, bf16_t* UA, const float* cw, const float* cb, int nrows, int rowoff) {
;     ...
;         for (int rr = 0; rr < 16; ++rr) {
;             u32x4 na = zero, ng = zero; if (rr < 15 || has_right) { na = *(const u32x4*)(zp + (size_t)(rr + 1) * FFN2); ng = *(const u32x4*)(zp + (size_t)(rr + 1) * FFN2 + FFN); }
;             u32x4 o;
; #pragma unroll
;             for (int e2 = 0; e2 < 4; ++e2) {
;                 const float a0 = bflo(pa[e2]) * wa[0][2 * e2] + bflo(ca[e2]) * wa[1][2 * e2] + bflo(na[e2]) * wa[2][2 * e2] + ba[2 * e2];
;                 const float a1 = bfhi(pa[e2]) * wa[0][2 * e2 + 1] + bfhi(ca[e2]) * wa[1][2 * e2 + 1] + bfhi(na[e2]) * wa[2][2 * e2 + 1] + ba[2 * e2 + 1];
;                 const float g0 = bflo(pg[e2]) * wg[0][2 * e2] + bflo(cgv[e2]) * wg[1][2 * e2] + bflo(ng[e2]) * wg[2][2 * e2] + bg[2 * e2];
;                 const float g1 = bfhi(pg[e2]) * wg[0][2 * e2 + 1] + bfhi(cgv[e2]) * wg[1][2 * e2 + 1] + bfhi(ng[e2]) * wg[2][2 * e2 + 1] + bg[2 * e2 + 1];
;                 o[e2] = cvt_pk_bf16(silu_f(a0) * g0, silu_f(a1) * g1); }
;             *(u32x4*)(UA + (size_t)(r0 + rr) * FFN + c0) = o;
;             pa = ca; pg = cgv; ca = na; cgv = ng;
	v_lshlrev_b32_e32 v16, 16, v64
	v_and_b32_e32 v17, s99, v64
	v_lshlrev_b32_e32 v18, 16, v65
	v_and_b32_e32 v19, s99, v65
	v_lshlrev_b32_e32 v20, 16, v66
	v_and_b32_e32 v21, s99, v66
	v_lshlrev_b32_e32 v22, 16, v67
	v_and_b32_e32 v23, s99, v67
	v_lshlrev_b32_e32 v24, 16, v68
	v_and_b32_e32 v25, s99, v68
	v_lshlrev_b32_e32 v26, 16, v69
	v_and_b32_e32 v27, s99, v69
	v_lshlrev_b32_e32 v28, 16, v70
	v_and_b32_e32 v29, s99, v70
	v_lshlrev_b32_e32 v30, 16, v71
	v_and_b32_e32 v31, s99, v71
	v_add_u32_e32 v10, 67051264, v5
	global_load_dwordx4 v[64:67], v10, s[2:3] offset:-2816
	global_load_dwordx4 v[68:71], v10, s[2:3] offset:2816
	v_pk_fma_f32 v[136:137], v[32:33], v[152:153], v[236:237]
	v_pk_fma_f32 v[196:197], v[40:41], v[212:213], v[244:245]
	v_pk_fma_f32 v[138:139], v[34:35], v[154:155], v[238:239]
	v_pk_fma_f32 v[198:199], v[42:43], v[214:215], v[246:247]
	v_pk_fma_f32 v[140:141], v[36:37], v[156:157], v[240:241]
	v_pk_fma_f32 v[200:201], v[44:45], v[216:217], v[248:249]
	v_pk_fma_f32 v[142:143], v[38:39], v[158:159], v[242:243]
	v_pk_fma_f32 v[202:203], v[46:47], v[218:219], v[250:251]
	v_pk_fma_f32 v[136:137], v[48:49], v[160:161], v[136:137]
	v_pk_fma_f32 v[196:197], v[56:57], v[220:221], v[196:197]
	v_pk_fma_f32 v[138:139], v[50:51], v[162:163], v[138:139]
	v_pk_fma_f32 v[198:199], v[58:59], v[222:223], v[198:199]
	v_pk_fma_f32 v[140:141], v[52:53], v[164:165], v[140:141]
	v_pk_fma_f32 v[200:201], v[60:61], v[224:225], v[200:201]
	v_pk_fma_f32 v[142:143], v[54:55], v[166:167], v[142:143]
	v_pk_fma_f32 v[202:203], v[62:63], v[226:227], v[202:203]
	v_pk_fma_f32 v[136:137], v[16:17], v[168:169], v[136:137]
	v_pk_fma_f32 v[196:197], v[24:25], v[228:229], v[196:197]
	v_pk_fma_f32 v[138:139], v[18:19], v[170:171], v[138:139]
	v_pk_fma_f32 v[198:199], v[26:27], v[230:231], v[198:199]
	v_pk_fma_f32 v[140:141], v[20:21], v[172:173], v[140:141]
	v_pk_fma_f32 v[200:201], v[28:29], v[232:233], v[200:201]
	v_pk_fma_f32 v[142:143], v[22:23], v[174:175], v[142:143]
	v_pk_fma_f32 v[202:203], v[30:31], v[234:235], v[202:203]
	v_pk_mul_f32 v[184:185], v[136:137], v[180:181]
	v_pk_mul_f32 v[186:187], v[138:139], v[180:181]
	v_pk_mul_f32 v[188:189], v[140:141], v[180:181]
	v_pk_mul_f32 v[190:191], v[142:143], v[180:181]
	v_exp_f32_e32 v184, v184
	v_exp_f32_e32 v185, v185
	v_exp_f32_e32 v186, v186
	v_exp_f32_e32 v187, v187
	v_exp_f32_e32 v188, v188
	v_exp_f32_e32 v189, v189
	v_exp_f32_e32 v190, v190
	v_exp_f32_e32 v191, v191
	s_nop 0
	v_pk_add_f32 v[184:185], v[184:185], v[144:145]
	v_pk_add_f32 v[186:187], v[186:187], v[144:145]
	v_pk_add_f32 v[188:189], v[188:189], v[144:145]
	v_pk_add_f32 v[190:191], v[190:191], v[144:145]
	v_rcp_f32_e32 v184, v184
	v_rcp_f32_e32 v185, v185
	v_rcp_f32_e32 v186, v186
	v_rcp_f32_e32 v187, v187
	v_rcp_f32_e32 v188, v188
	v_rcp_f32_e32 v189, v189
	v_rcp_f32_e32 v190, v190
	v_rcp_f32_e32 v191, v191
	s_nop 0
	v_pk_mul_f32 v[136:137], v[136:137], v[184:185]
	v_pk_mul_f32 v[138:139], v[138:139], v[186:187]
	v_pk_mul_f32 v[140:141], v[140:141], v[188:189]
	v_pk_mul_f32 v[142:143], v[142:143], v[190:191]
	v_pk_mul_f32 v[136:137], v[136:137], v[196:197]
	v_pk_mul_f32 v[138:139], v[138:139], v[198:199]
	v_pk_mul_f32 v[140:141], v[140:141], v[200:201]
	v_pk_mul_f32 v[142:143], v[142:143], v[202:203]
	v_cvt_pk_bf16_f32 v12, v136, v137
	v_cvt_pk_bf16_f32 v13, v138, v139
	v_cvt_pk_bf16_f32 v14, v140, v141
	v_cvt_pk_bf16_f32 v15, v142, v143
	global_store_dwordx4 v6, v[12:15], s[30:31]
	v_add_u32_e32 v6, 5632, v6
	s_waitcnt vmcnt(24)
	v_lshlrev_b32_e32 v32, 16, v72
	v_and_b32_e32 v33, s99, v72
	v_lshlrev_b32_e32 v34, 16, v73
	v_and_b32_e32 v35, s99, v73
	v_lshlrev_b32_e32 v36, 16, v74
	v_and_b32_e32 v37, s99, v74
	v_lshlrev_b32_e32 v38, 16, v75
	v_and_b32_e32 v39, s99, v75
	v_lshlrev_b32_e32 v40, 16, v76
	v_and_b32_e32 v41, s99, v76
	v_lshlrev_b32_e32 v42, 16, v77
	v_and_b32_e32 v43, s99, v77
	v_lshlrev_b32_e32 v44, 16, v78
	v_and_b32_e32 v45, s99, v78
	v_lshlrev_b32_e32 v46, 16, v79
	v_and_b32_e32 v47, s99, v79
	v_add_u32_e32 v11, 67062528, v5
	global_load_dwordx4 v[72:75], v11, s[2:3] offset:-2816
	global_load_dwordx4 v[76:79], v11, s[2:3] offset:2816
	v_pk_fma_f32 v[136:137], v[48:49], v[152:153], v[236:237]
	v_pk_fma_f32 v[196:197], v[56:57], v[212:213], v[244:245]
	v_pk_fma_f32 v[138:139], v[50:51], v[154:155], v[238:239]
	v_pk_fma_f32 v[198:199], v[58:59], v[214:215], v[246:247]
	v_pk_fma_f32 v[140:141], v[52:53], v[156:157], v[240:241]
	v_pk_fma_f32 v[200:201], v[60:61], v[216:217], v[248:249]
	v_pk_fma_f32 v[142:143], v[54:55], v[158:159], v[242:243]
	v_pk_fma_f32 v[202:203], v[62:63], v[218:219], v[250:251]
	v_pk_fma_f32 v[136:137], v[16:17], v[160:161], v[136:137]
	v_pk_fma_f32 v[196:197], v[24:25], v[220:221], v[196:197]
	v_pk_fma_f32 v[138:139], v[18:19], v[162:163], v[138:139]
	v_pk_fma_f32 v[198:199], v[26:27], v[222:223], v[198:199]
	v_pk_fma_f32 v[140:141], v[20:21], v[164:165], v[140:141]
	v_pk_fma_f32 v[200:201], v[28:29], v[224:225], v[200:201]
	v_pk_fma_f32 v[142:143], v[22:23], v[166:167], v[142:143]
	v_pk_fma_f32 v[202:203], v[30:31], v[226:227], v[202:203]
	v_pk_fma_f32 v[136:137], v[32:33], v[168:169], v[136:137]
	v_pk_fma_f32 v[196:197], v[40:41], v[228:229], v[196:197]
	v_pk_fma_f32 v[138:139], v[34:35], v[170:171], v[138:139]
	v_pk_fma_f32 v[198:199], v[42:43], v[230:231], v[198:199]
	v_pk_fma_f32 v[140:141], v[36:37], v[172:173], v[140:141]
	v_pk_fma_f32 v[200:201], v[44:45], v[232:233], v[200:201]
	v_pk_fma_f32 v[142:143], v[38:39], v[174:175], v[142:143]
	v_pk_fma_f32 v[202:203], v[46:47], v[234:235], v[202:203]
	v_pk_mul_f32 v[184:185], v[136:137], v[180:181]
	v_pk_mul_f32 v[186:187], v[138:139], v[180:181]
	v_pk_mul_f32 v[188:189], v[140:141], v[180:181]
	v_pk_mul_f32 v[190:191], v[142:143], v[180:181]
	v_exp_f32_e32 v184, v184
	v_exp_f32_e32 v185, v185
	v_exp_f32_e32 v186, v186
	v_exp_f32_e32 v187, v187
	v_exp_f32_e32 v188, v188
	v_exp_f32_e32 v189, v189
	v_exp_f32_e32 v190, v190
	v_exp_f32_e32 v191, v191
	s_nop 0
	v_pk_add_f32 v[184:185], v[184:185], v[144:145]
	v_pk_add_f32 v[186:187], v[186:187], v[144:145]
	v_pk_add_f32 v[188:189], v[188:189], v[144:145]
	v_pk_add_f32 v[190:191], v[190:191], v[144:145]
	v_rcp_f32_e32 v184, v184
	v_rcp_f32_e32 v185, v185
	v_rcp_f32_e32 v186, v186
	v_rcp_f32_e32 v187, v187
	v_rcp_f32_e32 v188, v188
	v_rcp_f32_e32 v189, v189
	v_rcp_f32_e32 v190, v190
	v_rcp_f32_e32 v191, v191
	s_nop 0
	v_pk_mul_f32 v[136:137], v[136:137], v[184:185]
	v_pk_mul_f32 v[138:139], v[138:139], v[186:187]
	v_pk_mul_f32 v[140:141], v[140:141], v[188:189]
	v_pk_mul_f32 v[142:143], v[142:143], v[190:191]
	v_pk_mul_f32 v[136:137], v[136:137], v[196:197]
	v_pk_mul_f32 v[138:139], v[138:139], v[198:199]
	v_pk_mul_f32 v[140:141], v[140:141], v[200:201]
	v_pk_mul_f32 v[142:143], v[142:143], v[202:203]
	v_cvt_pk_bf16_f32 v12, v136, v137
	v_cvt_pk_bf16_f32 v13, v138, v139
	v_cvt_pk_bf16_f32 v14, v140, v141
	v_cvt_pk_bf16_f32 v15, v142, v143
	global_store_dwordx4 v6, v[12:15], s[30:31]
	v_add_u32_e32 v6, 5632, v6
	s_waitcnt vmcnt(25)
; __device__ __forceinline__ unsigned cvt_pk_bf16(float lo, float hi) { unsigned r; asm volatile("v_cvt_pk_bf16_f32 %0, %1, %2" : "=v"(r) : "v"(lo), "v"(hi)); return r; }
; __device__ __forceinline__ float silu_f(float x) { return x * __builtin_amdgcn_rcpf(1.0f + __builtin_amdgcn_exp2f(-LOG2E * x)); }
; __device__ __forceinline__ float bflo(unsigned w) { return __uint_as_float(w << 16); }
; __device__ __forceinline__ float bfhi(unsigned w) { return __uint_as_float(w & 0xffff0000u); }
; __device__ __forceinline__ void conv_phase(const bf16_t* Z, bf16_t* UA, const float* cw, const float* cb, int nrows, int rowoff) {
;     ...
;         for (int rr = 0; rr < 16; ++rr) {
;             u32x4 na = zero, ng = zero; if (rr < 15 || has_right) { na = *(const u32x4*)(zp + (size_t)(rr + 1) * FFN2); ng = *(const u32x4*)(zp + (size_t)(rr + 1) * FFN2 + FFN); }
;             u32x4 o;
; #pragma unroll
;             for (int e2 = 0; e2 < 4; ++e2) {
;                 const float a0 = bflo(pa[e2]) * wa[0][2 * e2] + bflo(ca[e2]) * wa[1][2 * e2] + bflo(na[e2]) * wa[2][2 * e2] + ba[2 * e2];
;                 const float a1 = bfhi(pa[e2]) * wa[0][2 * e2 + 1] + bfhi(ca[e2]) * wa[1][2 * e2 + 1] + bfhi(na[e2]) * wa[2][2 * e2 + 1] + ba[2 * e2 + 1];
;                 const float g0 = bflo(pg[e2]) * wg[0][2 * e2] + bflo(cgv[e2]) * wg[1][2 * e2] + bflo(ng[e2]) * wg[2][2 * e2] + bg[2 * e2];
;                 const float g1 = bfhi(pg[e2]) * wg[0][2 * e2 + 1] + bfhi(cgv[e2]) * wg[1][2 * e2 + 1] + bfhi(ng[e2]) * wg[2][2 * e2 + 1] + bg[2 * e2 + 1];
;                 o[e2] = cvt_pk_bf16(silu_f(a0) * g0, silu_f(a1) * g1); }
;             *(u32x4*)(UA + (size_t)(r0 + rr) * FFN + c0) = o;
;             pa = ca; pg = cgv; ca = na; cgv = ng;
	v_lshlrev_b32_e32 v48, 16, v80
	v_and_b32_e32 v49, s99, v80
	v_lshlrev_b32_e32 v50, 16, v81
	v_and_b32_e32 v51, s99, v81
	v_lshlrev_b32_e32 v52, 16, v82
	v_and_b32_e32 v53, s99, v82
	v_lshlrev_b32_e32 v54, 16, v83
	v_and_b32_e32 v55, s99, v83
	v_lshlrev_b32_e32 v56, 16, v84
	v_and_b32_e32 v57, s99, v84
	v_lshlrev_b32_e32 v58, 16, v85
	v_and_b32_e32 v59, s99, v85
	v_lshlrev_b32_e32 v60, 16, v86
	v_and_b32_e32 v61, s99, v86
	v_lshlrev_b32_e32 v62, 16, v87
	v_and_b32_e32 v63, s99, v87
	v_add_u32_e32 v10, 67073792, v5
	global_load_dwordx4 v[80:83], v10, s[2:3] offset:-2816
	global_load_dwordx4 v[84:87], v10, s[2:3] offset:2816
	v_pk_fma_f32 v[136:137], v[16:17], v[152:153], v[236:237]
	v_pk_fma_f32 v[196:197], v[24:25], v[212:213], v[244:245]
	v_pk_fma_f32 v[138:139], v[18:19], v[154:155], v[238:239]
	v_pk_fma_f32 v[198:199], v[26:27], v[214:215], v[246:247]
	v_pk_fma_f32 v[140:141], v[20:21], v[156:157], v[240:241]
	v_pk_fma_f32 v[200:201], v[28:29], v[216:217], v[248:249]
	v_pk_fma_f32 v[142:143], v[22:23], v[158:159], v[242:243]
	v_pk_fma_f32 v[202:203], v[30:31], v[218:219], v[250:251]
	v_pk_fma_f32 v[136:137], v[32:33], v[160:161], v[136:137]
	v_pk_fma_f32 v[196:197], v[40:41], v[220:221], v[196:197]
	v_pk_fma_f32 v[138:139], v[34:35], v[162:163], v[138:139]
	v_pk_fma_f32 v[198:199], v[42:43], v[222:223], v[198:199]
	v_pk_fma_f32 v[140:141], v[36:37], v[164:165], v[140:141]
	v_pk_fma_f32 v[200:201], v[44:45], v[224:225], v[200:201]
	v_pk_fma_f32 v[142:143], v[38:39], v[166:167], v[142:143]
	v_pk_fma_f32 v[202:203], v[46:47], v[226:227], v[202:203]
	v_pk_fma_f32 v[136:137], v[48:49], v[168:169], v[136:137]
	v_pk_fma_f32 v[196:197], v[56:57], v[228:229], v[196:197]
	v_pk_fma_f32 v[138:139], v[50:51], v[170:171], v[138:139]
	v_pk_fma_f32 v[198:199], v[58:59], v[230:231], v[198:199]
	v_pk_fma_f32 v[140:141], v[52:53], v[172:173], v[140:141]
	v_pk_fma_f32 v[200:201], v[60:61], v[232:233], v[200:201]
	v_pk_fma_f32 v[142:143], v[54:55], v[174:175], v[142:143]
	v_pk_fma_f32 v[202:203], v[62:63], v[234:235], v[202:203]
	v_pk_mul_f32 v[184:185], v[136:137], v[180:181]
	v_pk_mul_f32 v[186:187], v[138:139], v[180:181]
	v_pk_mul_f32 v[188:189], v[140:141], v[180:181]
	v_pk_mul_f32 v[190:191], v[142:143], v[180:181]
	v_exp_f32_e32 v184, v184
	v_exp_f32_e32 v185, v185
	v_exp_f32_e32 v186, v186
	v_exp_f32_e32 v187, v187
	v_exp_f32_e32 v188, v188
	v_exp_f32_e32 v189, v189
	v_exp_f32_e32 v190, v190
	v_exp_f32_e32 v191, v191
	s_nop 0
	v_pk_add_f32 v[184:185], v[184:185], v[144:145]
	v_pk_add_f32 v[186:187], v[186:187], v[144:145]
	v_pk_add_f32 v[188:189], v[188:189], v[144:145]
	v_pk_add_f32 v[190:191], v[190:191], v[144:145]
	v_rcp_f32_e32 v184, v184
	v_rcp_f32_e32 v185, v185
	v_rcp_f32_e32 v186, v186
	v_rcp_f32_e32 v187, v187
	v_rcp_f32_e32 v188, v188
	v_rcp_f32_e32 v189, v189
	v_rcp_f32_e32 v190, v190
	v_rcp_f32_e32 v191, v191
	s_nop 0
	v_pk_mul_f32 v[136:137], v[136:137], v[184:185]
	v_pk_mul_f32 v[138:139], v[138:139], v[186:187]
	v_pk_mul_f32 v[140:141], v[140:141], v[188:189]
	v_pk_mul_f32 v[142:143], v[142:143], v[190:191]
	v_pk_mul_f32 v[136:137], v[136:137], v[196:197]
	v_pk_mul_f32 v[138:139], v[138:139], v[198:199]
	v_pk_mul_f32 v[140:141], v[140:141], v[200:201]
	v_pk_mul_f32 v[142:143], v[142:143], v[202:203]
	v_cvt_pk_bf16_f32 v12, v136, v137
	v_cvt_pk_bf16_f32 v13, v138, v139
	v_cvt_pk_bf16_f32 v14, v140, v141
	v_cvt_pk_bf16_f32 v15, v142, v143
	global_store_dwordx4 v6, v[12:15], s[30:31]
	v_add_u32_e32 v6, 5632, v6
	s_waitcnt vmcnt(25)
	v_lshlrev_b32_e32 v16, 16, v88
	v_and_b32_e32 v17, s99, v88
	v_lshlrev_b32_e32 v18, 16, v89
	v_and_b32_e32 v19, s99, v89
	v_lshlrev_b32_e32 v20, 16, v90
	v_and_b32_e32 v21, s99, v90
	v_lshlrev_b32_e32 v22, 16, v91
	v_and_b32_e32 v23, s99, v91
	v_lshlrev_b32_e32 v24, 16, v92
	v_and_b32_e32 v25, s99, v92
	v_lshlrev_b32_e32 v26, 16, v93
	v_and_b32_e32 v27, s99, v93
	v_lshlrev_b32_e32 v28, 16, v94
	v_and_b32_e32 v29, s99, v94
	v_lshlrev_b32_e32 v30, 16, v95
	v_and_b32_e32 v31, s99, v95
	v_add_u32_e32 v11, 67085056, v5
	global_load_dwordx4 v[88:91], v11, s[2:3] offset:-2816
	global_load_dwordx4 v[92:95], v11, s[2:3] offset:2816
	v_pk_fma_f32 v[136:137], v[32:33], v[152:153], v[236:237]
	v_pk_fma_f32 v[196:197], v[40:41], v[212:213], v[244:245]
	v_pk_fma_f32 v[138:139], v[34:35], v[154:155], v[238:239]
	v_pk_fma_f32 v[198:199], v[42:43], v[214:215], v[246:247]
	v_pk_fma_f32 v[140:141], v[36:37], v[156:157], v[240:241]
	v_pk_fma_f32 v[200:201], v[44:45], v[216:217], v[248:249]
	v_pk_fma_f32 v[142:143], v[38:39], v[158:159], v[242:243]
	v_pk_fma_f32 v[202:203], v[46:47], v[218:219], v[250:251]
	v_pk_fma_f32 v[136:137], v[48:49], v[160:161], v[136:137]
	v_pk_fma_f32 v[196:197], v[56:57], v[220:221], v[196:197]
	v_pk_fma_f32 v[138:139], v[50:51], v[162:163], v[138:139]
	v_pk_fma_f32 v[198:199], v[58:59], v[222:223], v[198:199]
	v_pk_fma_f32 v[140:141], v[52:53], v[164:165], v[140:141]
	v_pk_fma_f32 v[200:201], v[60:61], v[224:225], v[200:201]
	v_pk_fma_f32 v[142:143], v[54:55], v[166:167], v[142:143]
	v_pk_fma_f32 v[202:203], v[62:63], v[226:227], v[202:203]
	v_pk_fma_f32 v[136:137], v[16:17], v[168:169], v[136:137]
	v_pk_fma_f32 v[196:197], v[24:25], v[228:229], v[196:197]
	v_pk_fma_f32 v[138:139], v[18:19], v[170:171], v[138:139]
	v_pk_fma_f32 v[198:199], v[26:27], v[230:231], v[198:199]
	v_pk_fma_f32 v[140:141], v[20:21], v[172:173], v[140:141]
	v_pk_fma_f32 v[200:201], v[28:29], v[232:233], v[200:201]
	v_pk_fma_f32 v[142:143], v[22:23], v[174:175], v[142:143]
	v_pk_fma_f32 v[202:203], v[30:31], v[234:235], v[202:203]
	v_pk_mul_f32 v[184:185], v[136:137], v[180:181]
	v_pk_mul_f32 v[186:187], v[138:139], v[180:181]
	v_pk_mul_f32 v[188:189], v[140:141], v[180:181]
	v_pk_mul_f32 v[190:191], v[142:143], v[180:181]
	v_exp_f32_e32 v184, v184
	v_exp_f32_e32 v185, v185
	v_exp_f32_e32 v186, v186
	v_exp_f32_e32 v187, v187
	v_exp_f32_e32 v188, v188
	v_exp_f32_e32 v189, v189
	v_exp_f32_e32 v190, v190
	v_exp_f32_e32 v191, v191
	s_nop 0
	v_pk_add_f32 v[184:185], v[184:185], v[144:145]
	v_pk_add_f32 v[186:187], v[186:187], v[144:145]
	v_pk_add_f32 v[188:189], v[188:189], v[144:145]
	v_pk_add_f32 v[190:191], v[190:191], v[144:145]
	v_rcp_f32_e32 v184, v184
	v_rcp_f32_e32 v185, v185
	v_rcp_f32_e32 v186, v186
	v_rcp_f32_e32 v187, v187
	v_rcp_f32_e32 v188, v188
	v_rcp_f32_e32 v189, v189
	v_rcp_f32_e32 v190, v190
	v_rcp_f32_e32 v191, v191
	s_nop 0
	v_pk_mul_f32 v[136:137], v[136:137], v[184:185]
	v_pk_mul_f32 v[138:139], v[138:139], v[186:187]
	v_pk_mul_f32 v[140:141], v[140:141], v[188:189]
	v_pk_mul_f32 v[142:143], v[142:143], v[190:191]
	v_pk_mul_f32 v[136:137], v[136:137], v[196:197]
	v_pk_mul_f32 v[138:139], v[138:139], v[198:199]
	v_pk_mul_f32 v[140:141], v[140:141], v[200:201]
	v_pk_mul_f32 v[142:143], v[142:143], v[202:203]
	v_cvt_pk_bf16_f32 v12, v136, v137
	v_cvt_pk_bf16_f32 v13, v138, v139
	v_cvt_pk_bf16_f32 v14, v140, v141
	v_cvt_pk_bf16_f32 v15, v142, v143
	global_store_dwordx4 v6, v[12:15], s[30:31]
	v_add_u32_e32 v6, 5632, v6
	s_waitcnt vmcnt(25)
; __device__ __forceinline__ unsigned cvt_pk_bf16(float lo, float hi) { unsigned r; asm volatile("v_cvt_pk_bf16_f32 %0, %1, %2" : "=v"(r) : "v"(lo), "v"(hi)); return r; }
; __device__ __forceinline__ float silu_f(float x) { return x * __builtin_amdgcn_rcpf(1.0f + __builtin_amdgcn_exp2f(-LOG2E * x)); }
; __device__ __forceinline__ float bflo(unsigned w) { return __uint_as_float(w << 16); }
; __device__ __forceinline__ float bfhi(unsigned w) { return __uint_as_float(w & 0xffff0000u); }
; __device__ __forceinline__ void conv_phase(const bf16_t* Z, bf16_t* UA, const float* cw, const float* cb, int nrows, int rowoff) {
;     ...
;         for (int rr = 0; rr < 16; ++rr) {
;             u32x4 na = zero, ng = zero; if (rr < 15 || has_right) { na = *(const u32x4*)(zp + (size_t)(rr + 1) * FFN2); ng = *(const u32x4*)(zp + (size_t)(rr + 1) * FFN2 + FFN); }
;             u32x4 o;
; #pragma unroll
;             for (int e2 = 0; e2 < 4; ++e2) {
;                 const float a0 = bflo(pa[e2]) * wa[0][2 * e2] + bflo(ca[e2]) * wa[1][2 * e2] + bflo(na[e2]) * wa[2][2 * e2] + ba[2 * e2];
;                 const float a1 = bfhi(pa[e2]) * wa[0][2 * e2 + 1] + bfhi(ca[e2]) * wa[1][2 * e2 + 1] + bfhi(na[e2]) * wa[2][2 * e2 + 1] + ba[2 * e2 + 1];
;                 const float g0 = bflo(pg[e2]) * wg[0][2 * e2] + bflo(cgv[e2]) * wg[1][2 * e2] + bflo(ng[e2]) * wg[2][2 * e2] + bg[2 * e2];
;                 const float g1 = bfhi(pg[e2]) * wg[0][2 * e2 + 1] + bfhi(cgv[e2]) * wg[1][2 * e2 + 1] + bfhi(ng[e2]) * wg[2][2 * e2 + 1] + bg[2 * e2 + 1];
;                 o[e2] = cvt_pk_bf16(silu_f(a0) * g0, silu_f(a1) * g1); }
;             *(u32x4*)(UA + (size_t)(r0 + rr) * FFN + c0) = o;
;             pa = ca; pg = cgv; ca = na; cgv = ng;
	v_lshlrev_b32_e32 v32, 16, v96
	v_and_b32_e32 v33, s99, v96
	v_lshlrev_b32_e32 v34, 16, v97
	v_and_b32_e32 v35, s99, v97
	v_lshlrev_b32_e32 v36, 16, v98
	v_and_b32_e32 v37, s99, v98
	v_lshlrev_b32_e32 v38, 16, v99
	v_and_b32_e32 v39, s99, v99
	v_lshlrev_b32_e32 v40, 16, v100
	v_and_b32_e32 v41, s99, v100
	v_lshlrev_b32_e32 v42, 16, v101
	v_and_b32_e32 v43, s99, v101
	v_lshlrev_b32_e32 v44, 16, v102
	v_and_b32_e32 v45, s99, v102
	v_lshlrev_b32_e32 v46, 16, v103
	v_and_b32_e32 v47, s99, v103
	v_add_u32_e32 v10, 67096320, v5
	global_load_dwordx4 v[96:99], v10, s[2:3] offset:-2816
	global_load_dwordx4 v[100:103], v10, s[2:3] offset:2816
	v_pk_fma_f32 v[136:137], v[48:49], v[152:153], v[236:237]
	v_pk_fma_f32 v[196:197], v[56:57], v[212:213], v[244:245]
	v_pk_fma_f32 v[138:139], v[50:51], v[154:155], v[238:239]
	v_pk_fma_f32 v[198:199], v[58:59], v[214:215], v[246:247]
	v_pk_fma_f32 v[140:141], v[52:53], v[156:157], v[240:241]
	v_pk_fma_f32 v[200:201], v[60:61], v[216:217], v[248:249]
	v_pk_fma_f32 v[142:143], v[54:55], v[158:159], v[242:243]
	v_pk_fma_f32 v[202:203], v[62:63], v[218:219], v[250:251]
	v_pk_fma_f32 v[136:137], v[16:17], v[160:161], v[136:137]
	v_pk_fma_f32 v[196:197], v[24:25], v[220:221], v[196:197]
	v_pk_fma_f32 v[138:139], v[18:19], v[162:163], v[138:139]
	v_pk_fma_f32 v[198:199], v[26:27], v[222:223], v[198:199]
	v_pk_fma_f32 v[140:141], v[20:21], v[164:165], v[140:141]
	v_pk_fma_f32 v[200:201], v[28:29], v[224:225], v[200:201]
	v_pk_fma_f32 v[142:143], v[22:23], v[166:167], v[142:143]
	v_pk_fma_f32 v[202:203], v[30:31], v[226:227], v[202:203]
	v_pk_fma_f32 v[136:137], v[32:33], v[168:169], v[136:137]
	v_pk_fma_f32 v[196:197], v[40:41], v[228:229], v[196:197]
	v_pk_fma_f32 v[138:139], v[34:35], v[170:171], v[138:139]
	v_pk_fma_f32 v[198:199], v[42:43], v[230:231], v[198:199]
	v_pk_fma_f32 v[140:141], v[36:37], v[172:173], v[140:141]
	v_pk_fma_f32 v[200:201], v[44:45], v[232:233], v[200:201]
	v_pk_fma_f32 v[142:143], v[38:39], v[174:175], v[142:143]
	v_pk_fma_f32 v[202:203], v[46:47], v[234:235], v[202:203]
	v_pk_mul_f32 v[184:185], v[136:137], v[180:181]
	v_pk_mul_f32 v[186:187], v[138:139], v[180:181]
	v_pk_mul_f32 v[188:189], v[140:141], v[180:181]
	v_pk_mul_f32 v[190:191], v[142:143], v[180:181]
	v_exp_f32_e32 v184, v184
	v_exp_f32_e32 v185, v185
	v_exp_f32_e32 v186, v186
	v_exp_f32_e32 v187, v187
	v_exp_f32_e32 v188, v188
	v_exp_f32_e32 v189, v189
	v_exp_f32_e32 v190, v190
	v_exp_f32_e32 v191, v191
	s_nop 0
	v_pk_add_f32 v[184:185], v[184:185], v[144:145]
	v_pk_add_f32 v[186:187], v[186:187], v[144:145]
	v_pk_add_f32 v[188:189], v[188:189], v[144:145]
	v_pk_add_f32 v[190:191], v[190:191], v[144:145]
	v_rcp_f32_e32 v184, v184
	v_rcp_f32_e32 v185, v185
	v_rcp_f32_e32 v186, v186
	v_rcp_f32_e32 v187, v187
	v_rcp_f32_e32 v188, v188
	v_rcp_f32_e32 v189, v189
	v_rcp_f32_e32 v190, v190
	v_rcp_f32_e32 v191, v191
	s_nop 0
	v_pk_mul_f32 v[136:137], v[136:137], v[184:185]
	v_pk_mul_f32 v[138:139], v[138:139], v[186:187]
	v_pk_mul_f32 v[140:141], v[140:141], v[188:189]
	v_pk_mul_f32 v[142:143], v[142:143], v[190:191]
	v_pk_mul_f32 v[136:137], v[136:137], v[196:197]
	v_pk_mul_f32 v[138:139], v[138:139], v[198:199]
	v_pk_mul_f32 v[140:141], v[140:141], v[200:201]
	v_pk_mul_f32 v[142:143], v[142:143], v[202:203]
	v_cvt_pk_bf16_f32 v12, v136, v137
	v_cvt_pk_bf16_f32 v13, v138, v139
	v_cvt_pk_bf16_f32 v14, v140, v141
	v_cvt_pk_bf16_f32 v15, v142, v143
	global_store_dwordx4 v6, v[12:15], s[30:31]
	v_add_u32_e32 v6, 5632, v6
	s_waitcnt vmcnt(25)
	v_lshlrev_b32_e32 v48, 16, v104
	v_and_b32_e32 v49, s99, v104
	v_lshlrev_b32_e32 v50, 16, v105
	v_and_b32_e32 v51, s99, v105
	v_lshlrev_b32_e32 v52, 16, v106
	v_and_b32_e32 v53, s99, v106
	v_lshlrev_b32_e32 v54, 16, v107
	v_and_b32_e32 v55, s99, v107
	v_lshlrev_b32_e32 v56, 16, v108
	v_and_b32_e32 v57, s99, v108
	v_lshlrev_b32_e32 v58, 16, v109
	v_and_b32_e32 v59, s99, v109
	v_lshlrev_b32_e32 v60, 16, v110
	v_and_b32_e32 v61, s99, v110
	v_lshlrev_b32_e32 v62, 16, v111
	v_and_b32_e32 v63, s99, v111
	v_add_u32_e32 v11, 67107584, v5
	global_load_dwordx4 v[104:107], v11, s[2:3] offset:-2816
	global_load_dwordx4 v[108:111], v11, s[2:3] offset:2816
	v_pk_fma_f32 v[136:137], v[16:17], v[152:153], v[236:237]
	v_pk_fma_f32 v[196:197], v[24:25], v[212:213], v[244:245]
	v_pk_fma_f32 v[138:139], v[18:19], v[154:155], v[238:239]
	v_pk_fma_f32 v[198:199], v[26:27], v[214:215], v[246:247]
	v_pk_fma_f32 v[140:141], v[20:21], v[156:157], v[240:241]
	v_pk_fma_f32 v[200:201], v[28:29], v[216:217], v[248:249]
	v_pk_fma_f32 v[142:143], v[22:23], v[158:159], v[242:243]
	v_pk_fma_f32 v[202:203], v[30:31], v[218:219], v[250:251]
	v_pk_fma_f32 v[136:137], v[32:33], v[160:161], v[136:137]
	v_pk_fma_f32 v[196:197], v[40:41], v[220:221], v[196:197]
	v_pk_fma_f32 v[138:139], v[34:35], v[162:163], v[138:139]
	v_pk_fma_f32 v[198:199], v[42:43], v[222:223], v[198:199]
	v_pk_fma_f32 v[140:141], v[36:37], v[164:165], v[140:141]
	v_pk_fma_f32 v[200:201], v[44:45], v[224:225], v[200:201]
	v_pk_fma_f32 v[142:143], v[38:39], v[166:167], v[142:143]
	v_pk_fma_f32 v[202:203], v[46:47], v[226:227], v[202:203]
	v_pk_fma_f32 v[136:137], v[48:49], v[168:169], v[136:137]
	v_pk_fma_f32 v[196:197], v[56:57], v[228:229], v[196:197]
	v_pk_fma_f32 v[138:139], v[50:51], v[170:171], v[138:139]
	v_pk_fma_f32 v[198:199], v[58:59], v[230:231], v[198:199]
	v_pk_fma_f32 v[140:141], v[52:53], v[172:173], v[140:141]
	v_pk_fma_f32 v[200:201], v[60:61], v[232:233], v[200:201]
	v_pk_fma_f32 v[142:143], v[54:55], v[174:175], v[142:143]
	v_pk_fma_f32 v[202:203], v[62:63], v[234:235], v[202:203]
	v_pk_mul_f32 v[184:185], v[136:137], v[180:181]
	v_pk_mul_f32 v[186:187], v[138:139], v[180:181]
	v_pk_mul_f32 v[188:189], v[140:141], v[180:181]
	v_pk_mul_f32 v[190:191], v[142:143], v[180:181]
	v_exp_f32_e32 v184, v184
	v_exp_f32_e32 v185, v185
	v_exp_f32_e32 v186, v186
	v_exp_f32_e32 v187, v187
	v_exp_f32_e32 v188, v188
	v_exp_f32_e32 v189, v189
	v_exp_f32_e32 v190, v190
	v_exp_f32_e32 v191, v191
	s_nop 0
	v_pk_add_f32 v[184:185], v[184:185], v[144:145]
	v_pk_add_f32 v[186:187], v[186:187], v[144:145]
	v_pk_add_f32 v[188:189], v[188:189], v[144:145]
	v_pk_add_f32 v[190:191], v[190:191], v[144:145]
	v_rcp_f32_e32 v184, v184
	v_rcp_f32_e32 v185, v185
	v_rcp_f32_e32 v186, v186
	v_rcp_f32_e32 v187, v187
	v_rcp_f32_e32 v188, v188
	v_rcp_f32_e32 v189, v189
	v_rcp_f32_e32 v190, v190
	v_rcp_f32_e32 v191, v191
	s_nop 0
	v_pk_mul_f32 v[136:137], v[136:137], v[184:185]
	v_pk_mul_f32 v[138:139], v[138:139], v[186:187]
	v_pk_mul_f32 v[140:141], v[140:141], v[188:189]
	v_pk_mul_f32 v[142:143], v[142:143], v[190:191]
	v_pk_mul_f32 v[136:137], v[136:137], v[196:197]
	v_pk_mul_f32 v[138:139], v[138:139], v[198:199]
	v_pk_mul_f32 v[140:141], v[140:141], v[200:201]
	v_pk_mul_f32 v[142:143], v[142:143], v[202:203]
	v_cvt_pk_bf16_f32 v12, v136, v137
	v_cvt_pk_bf16_f32 v13, v138, v139
	v_cvt_pk_bf16_f32 v14, v140, v141
	v_cvt_pk_bf16_f32 v15, v142, v143
	global_store_dwordx4 v6, v[12:15], s[30:31]
	v_add_u32_e32 v6, 5632, v6
	s_waitcnt vmcnt(25)
; __device__ __forceinline__ unsigned cvt_pk_bf16(float lo, float hi) { unsigned r; asm volatile("v_cvt_pk_bf16_f32 %0, %1, %2" : "=v"(r) : "v"(lo), "v"(hi)); return r; }
; __device__ __forceinline__ float silu_f(float x) { return x * __builtin_amdgcn_rcpf(1.0f + __builtin_amdgcn_exp2f(-LOG2E * x)); }
; __device__ __forceinline__ float bflo(unsigned w) { return __uint_as_float(w << 16); }
; __device__ __forceinline__ float bfhi(unsigned w) { return __uint_as_float(w & 0xffff0000u); }
; __device__ __forceinline__ void conv_phase(const bf16_t* Z, bf16_t* UA, const float* cw, const float* cb, int nrows, int rowoff) {
;     ...
;         for (int rr = 0; rr < 16; ++rr) {
;             u32x4 na = zero, ng = zero; if (rr < 15 || has_right) { na = *(const u32x4*)(zp + (size_t)(rr + 1) * FFN2); ng = *(const u32x4*)(zp + (size_t)(rr + 1) * FFN2 + FFN); }
;             u32x4 o;
; #pragma unroll
;             for (int e2 = 0; e2 < 4; ++e2) {
;                 const float a0 = bflo(pa[e2]) * wa[0][2 * e2] + bflo(ca[e2]) * wa[1][2 * e2] + bflo(na[e2]) * wa[2][2 * e2] + ba[2 * e2];
;                 const float a1 = bfhi(pa[e2]) * wa[0][2 * e2 + 1] + bfhi(ca[e2]) * wa[1][2 * e2 + 1] + bfhi(na[e2]) * wa[2][2 * e2 + 1] + ba[2 * e2 + 1];
;                 const float g0 = bflo(pg[e2]) * wg[0][2 * e2] + bflo(cgv[e2]) * wg[1][2 * e2] + bflo(ng[e2]) * wg[2][2 * e2] + bg[2 * e2];
;                 const float g1 = bfhi(pg[e2]) * wg[0][2 * e2 + 1] + bfhi(cgv[e2]) * wg[1][2 * e2 + 1] + bfhi(ng[e2]) * wg[2][2 * e2 + 1] + bg[2 * e2 + 1];
;                 o[e2] = cvt_pk_bf16(silu_f(a0) * g0, silu_f(a1) * g1); }
;             *(u32x4*)(UA + (size_t)(r0 + rr) * FFN + c0) = o;
;             pa = ca; pg = cgv; ca = na; cgv = ng;
	v_lshlrev_b32_e32 v16, 16, v112
	v_and_b32_e32 v17, s99, v112
	v_lshlrev_b32_e32 v18, 16, v113
	v_and_b32_e32 v19, s99, v113
	v_lshlrev_b32_e32 v20, 16, v114
	v_and_b32_e32 v21, s99, v114
	v_lshlrev_b32_e32 v22, 16, v115
	v_and_b32_e32 v23, s99, v115
	v_lshlrev_b32_e32 v24, 16, v116
	v_and_b32_e32 v25, s99, v116
	v_lshlrev_b32_e32 v26, 16, v117
	v_and_b32_e32 v27, s99, v117
	v_lshlrev_b32_e32 v28, 16, v118
	v_and_b32_e32 v29, s99, v118
	v_lshlrev_b32_e32 v30, 16, v119
	v_and_b32_e32 v31, s99, v119
	v_add_u32_e32 v10, 67118848, v5
	global_load_dwordx4 v[112:115], v10, s[2:3] offset:-2816
	global_load_dwordx4 v[116:119], v10, s[2:3] offset:2816
	v_pk_fma_f32 v[136:137], v[32:33], v[152:153], v[236:237]
	v_pk_fma_f32 v[196:197], v[40:41], v[212:213], v[244:245]
	v_pk_fma_f32 v[138:139], v[34:35], v[154:155], v[238:239]
	v_pk_fma_f32 v[198:199], v[42:43], v[214:215], v[246:247]
	v_pk_fma_f32 v[140:141], v[36:37], v[156:157], v[240:241]
	v_pk_fma_f32 v[200:201], v[44:45], v[216:217], v[248:249]
	v_pk_fma_f32 v[142:143], v[38:39], v[158:159], v[242:243]
	v_pk_fma_f32 v[202:203], v[46:47], v[218:219], v[250:251]
	v_pk_fma_f32 v[136:137], v[48:49], v[160:161], v[136:137]
	v_pk_fma_f32 v[196:197], v[56:57], v[220:221], v[196:197]
	v_pk_fma_f32 v[138:139], v[50:51], v[162:163], v[138:139]
	v_pk_fma_f32 v[198:199], v[58:59], v[222:223], v[198:199]
	v_pk_fma_f32 v[140:141], v[52:53], v[164:165], v[140:141]
	v_pk_fma_f32 v[200:201], v[60:61], v[224:225], v[200:201]
	v_pk_fma_f32 v[142:143], v[54:55], v[166:167], v[142:143]
	v_pk_fma_f32 v[202:203], v[62:63], v[226:227], v[202:203]
	v_pk_fma_f32 v[136:137], v[16:17], v[168:169], v[136:137]
	v_pk_fma_f32 v[196:197], v[24:25], v[228:229], v[196:197]
	v_pk_fma_f32 v[138:139], v[18:19], v[170:171], v[138:139]
	v_pk_fma_f32 v[198:199], v[26:27], v[230:231], v[198:199]
	v_pk_fma_f32 v[140:141], v[20:21], v[172:173], v[140:141]
	v_pk_fma_f32 v[200:201], v[28:29], v[232:233], v[200:201]
	v_pk_fma_f32 v[142:143], v[22:23], v[174:175], v[142:143]
	v_pk_fma_f32 v[202:203], v[30:31], v[234:235], v[202:203]
	v_pk_mul_f32 v[184:185], v[136:137], v[180:181]
	v_pk_mul_f32 v[186:187], v[138:139], v[180:181]
	v_pk_mul_f32 v[188:189], v[140:141], v[180:181]
	v_pk_mul_f32 v[190:191], v[142:143], v[180:181]
	v_exp_f32_e32 v184, v184
	v_exp_f32_e32 v185, v185
	v_exp_f32_e32 v186, v186
	v_exp_f32_e32 v187, v187
	v_exp_f32_e32 v188, v188
	v_exp_f32_e32 v189, v189
	v_exp_f32_e32 v190, v190
	v_exp_f32_e32 v191, v191
	s_nop 0
	v_pk_add_f32 v[184:185], v[184:185], v[144:145]
	v_pk_add_f32 v[186:187], v[186:187], v[144:145]
	v_pk_add_f32 v[188:189], v[188:189], v[144:145]
	v_pk_add_f32 v[190:191], v[190:191], v[144:145]
	v_rcp_f32_e32 v184, v184
	v_rcp_f32_e32 v185, v185
	v_rcp_f32_e32 v186, v186
	v_rcp_f32_e32 v187, v187
	v_rcp_f32_e32 v188, v188
	v_rcp_f32_e32 v189, v189
	v_rcp_f32_e32 v190, v190
	v_rcp_f32_e32 v191, v191
	s_nop 0
	v_pk_mul_f32 v[136:137], v[136:137], v[184:185]
	v_pk_mul_f32 v[138:139], v[138:139], v[186:187]
	v_pk_mul_f32 v[140:141], v[140:141], v[188:189]
	v_pk_mul_f32 v[142:143], v[142:143], v[190:191]
	v_pk_mul_f32 v[136:137], v[136:137], v[196:197]
	v_pk_mul_f32 v[138:139], v[138:139], v[198:199]
	v_pk_mul_f32 v[140:141], v[140:141], v[200:201]
	v_pk_mul_f32 v[142:143], v[142:143], v[202:203]
	v_cvt_pk_bf16_f32 v12, v136, v137
	v_cvt_pk_bf16_f32 v13, v138, v139
	v_cvt_pk_bf16_f32 v14, v140, v141
	v_cvt_pk_bf16_f32 v15, v142, v143
	global_store_dwordx4 v6, v[12:15], s[30:31]
	v_add_u32_e32 v6, 5632, v6
	s_waitcnt vmcnt(25)
	v_lshlrev_b32_e32 v32, 16, v120
	v_and_b32_e32 v33, s99, v120
	v_lshlrev_b32_e32 v34, 16, v121
	v_and_b32_e32 v35, s99, v121
	v_lshlrev_b32_e32 v36, 16, v122
	v_and_b32_e32 v37, s99, v122
	v_lshlrev_b32_e32 v38, 16, v123
	v_and_b32_e32 v39, s99, v123
	v_lshlrev_b32_e32 v40, 16, v124
	v_and_b32_e32 v41, s99, v124
	v_lshlrev_b32_e32 v42, 16, v125
	v_and_b32_e32 v43, s99, v125
	v_lshlrev_b32_e32 v44, 16, v126
	v_and_b32_e32 v45, s99, v126
	v_lshlrev_b32_e32 v46, 16, v127
	v_and_b32_e32 v47, s99, v127
	v_add_u32_e32 v11, 67130112, v5
	global_load_dwordx4 v[120:123], v11, s[2:3] offset:-2816
	global_load_dwordx4 v[124:127], v11, s[2:3] offset:2816
	v_pk_fma_f32 v[136:137], v[48:49], v[152:153], v[236:237]
	v_pk_fma_f32 v[196:197], v[56:57], v[212:213], v[244:245]
	v_pk_fma_f32 v[138:139], v[50:51], v[154:155], v[238:239]
	v_pk_fma_f32 v[198:199], v[58:59], v[214:215], v[246:247]
	v_pk_fma_f32 v[140:141], v[52:53], v[156:157], v[240:241]
	v_pk_fma_f32 v[200:201], v[60:61], v[216:217], v[248:249]
	v_pk_fma_f32 v[142:143], v[54:55], v[158:159], v[242:243]
	v_pk_fma_f32 v[202:203], v[62:63], v[218:219], v[250:251]
	v_pk_fma_f32 v[136:137], v[16:17], v[160:161], v[136:137]
	v_pk_fma_f32 v[196:197], v[24:25], v[220:221], v[196:197]
	v_pk_fma_f32 v[138:139], v[18:19], v[162:163], v[138:139]
	v_pk_fma_f32 v[198:199], v[26:27], v[222:223], v[198:199]
	v_pk_fma_f32 v[140:141], v[20:21], v[164:165], v[140:141]
	v_pk_fma_f32 v[200:201], v[28:29], v[224:225], v[200:201]
	v_pk_fma_f32 v[142:143], v[22:23], v[166:167], v[142:143]
	v_pk_fma_f32 v[202:203], v[30:31], v[226:227], v[202:203]
	v_pk_fma_f32 v[136:137], v[32:33], v[168:169], v[136:137]
	v_pk_fma_f32 v[196:197], v[40:41], v[228:229], v[196:197]
	v_pk_fma_f32 v[138:139], v[34:35], v[170:171], v[138:139]
	v_pk_fma_f32 v[198:199], v[42:43], v[230:231], v[198:199]
	v_pk_fma_f32 v[140:141], v[36:37], v[172:173], v[140:141]
	v_pk_fma_f32 v[200:201], v[44:45], v[232:233], v[200:201]
	v_pk_fma_f32 v[142:143], v[38:39], v[174:175], v[142:143]
	v_pk_fma_f32 v[202:203], v[46:47], v[234:235], v[202:203]
	v_pk_mul_f32 v[184:185], v[136:137], v[180:181]
	v_pk_mul_f32 v[186:187], v[138:139], v[180:181]
	v_pk_mul_f32 v[188:189], v[140:141], v[180:181]
	v_pk_mul_f32 v[190:191], v[142:143], v[180:181]
	v_exp_f32_e32 v184, v184
	v_exp_f32_e32 v185, v185
	v_exp_f32_e32 v186, v186
	v_exp_f32_e32 v187, v187
	v_exp_f32_e32 v188, v188
	v_exp_f32_e32 v189, v189
	v_exp_f32_e32 v190, v190
	v_exp_f32_e32 v191, v191
	s_nop 0
	v_pk_add_f32 v[184:185], v[184:185], v[144:145]
	v_pk_add_f32 v[186:187], v[186:187], v[144:145]
	v_pk_add_f32 v[188:189], v[188:189], v[144:145]
	v_pk_add_f32 v[190:191], v[190:191], v[144:145]
	v_rcp_f32_e32 v184, v184
	v_rcp_f32_e32 v185, v185
	v_rcp_f32_e32 v186, v186
	v_rcp_f32_e32 v187, v187
	v_rcp_f32_e32 v188, v188
	v_rcp_f32_e32 v189, v189
	v_rcp_f32_e32 v190, v190
	v_rcp_f32_e32 v191, v191
	s_nop 0
	v_pk_mul_f32 v[136:137], v[136:137], v[184:185]
	v_pk_mul_f32 v[138:139], v[138:139], v[186:187]
	v_pk_mul_f32 v[140:141], v[140:141], v[188:189]
	v_pk_mul_f32 v[142:143], v[142:143], v[190:191]
	v_pk_mul_f32 v[136:137], v[136:137], v[196:197]
	v_pk_mul_f32 v[138:139], v[138:139], v[198:199]
	v_pk_mul_f32 v[140:141], v[140:141], v[200:201]
	v_pk_mul_f32 v[142:143], v[142:143], v[202:203]
	v_cvt_pk_bf16_f32 v12, v136, v137
	v_cvt_pk_bf16_f32 v13, v138, v139
	v_cvt_pk_bf16_f32 v14, v140, v141
	v_cvt_pk_bf16_f32 v15, v142, v143
	global_store_dwordx4 v6, v[12:15], s[30:31]
	v_add_u32_e32 v6, 5632, v6
	s_waitcnt vmcnt(25)
; __device__ __forceinline__ unsigned cvt_pk_bf16(float lo, float hi) { unsigned r; asm volatile("v_cvt_pk_bf16_f32 %0, %1, %2" : "=v"(r) : "v"(lo), "v"(hi)); return r; }
; __device__ __forceinline__ float silu_f(float x) { return x * __builtin_amdgcn_rcpf(1.0f + __builtin_amdgcn_exp2f(-LOG2E * x)); }
; __device__ __forceinline__ float bflo(unsigned w) { return __uint_as_float(w << 16); }
; __device__ __forceinline__ float bfhi(unsigned w) { return __uint_as_float(w & 0xffff0000u); }
; __device__ __forceinline__ void conv_phase(const bf16_t* Z, bf16_t* UA, const float* cw, const float* cb, int nrows, int rowoff) {
;     ...
;         for (int rr = 0; rr < 16; ++rr) {
;             u32x4 na = zero, ng = zero; if (rr < 15 || has_right) { na = *(const u32x4*)(zp + (size_t)(rr + 1) * FFN2); ng = *(const u32x4*)(zp + (size_t)(rr + 1) * FFN2 + FFN); }
;             u32x4 o;
; #pragma unroll
;             for (int e2 = 0; e2 < 4; ++e2) {
;                 const float a0 = bflo(pa[e2]) * wa[0][2 * e2] + bflo(ca[e2]) * wa[1][2 * e2] + bflo(na[e2]) * wa[2][2 * e2] + ba[2 * e2];
;                 const float a1 = bfhi(pa[e2]) * wa[0][2 * e2 + 1] + bfhi(ca[e2]) * wa[1][2 * e2 + 1] + bfhi(na[e2]) * wa[2][2 * e2 + 1] + ba[2 * e2 + 1];
;                 const float g0 = bflo(pg[e2]) * wg[0][2 * e2] + bflo(cgv[e2]) * wg[1][2 * e2] + bflo(ng[e2]) * wg[2][2 * e2] + bg[2 * e2];
;                 const float g1 = bfhi(pg[e2]) * wg[0][2 * e2 + 1] + bfhi(cgv[e2]) * wg[1][2 * e2 + 1] + bfhi(ng[e2]) * wg[2][2 * e2 + 1] + bg[2 * e2 + 1];
;                 o[e2] = cvt_pk_bf16(silu_f(a0) * g0, silu_f(a1) * g1); }
;             *(u32x4*)(UA + (size_t)(r0 + rr) * FFN + c0) = o;
;             pa = ca; pg = cgv; ca = na; cgv = ng;
; __device__ __forceinline__ void xcd_barrier(const XcdBarrier& b) {
;     asm volatile("s_waitcnt vmcnt(0)" ::: "memory");
;     __syncthreads();
;     if (threadIdx.x == 0) {
;         unsigned* bar = b.bar;
;         __builtin_amdgcn_s_waitcnt(0);
;         unsigned nloc = b.st[0], nx = b.st[1];
;         if (nloc == 0u) { xcd_barrier_complete(bar, b.x, nloc, nx); b.st[0] = nloc; b.st[1] = nx; }
	v_cndmask_b32_e64 v128, 0, v128, s[100:101]
	v_cndmask_b32_e64 v129, 0, v129, s[100:101]
	v_cndmask_b32_e64 v130, 0, v130, s[100:101]
	v_cndmask_b32_e64 v131, 0, v131, s[100:101]
	v_cndmask_b32_e64 v132, 0, v132, s[100:101]
	v_cndmask_b32_e64 v133, 0, v133, s[100:101]
	v_cndmask_b32_e64 v134, 0, v134, s[100:101]
	v_cndmask_b32_e64 v135, 0, v135, s[100:101]
	v_lshlrev_b32_e32 v48, 16, v128
	v_and_b32_e32 v49, s99, v128
	v_lshlrev_b32_e32 v50, 16, v129
	v_and_b32_e32 v51, s99, v129
	v_lshlrev_b32_e32 v52, 16, v130
	v_and_b32_e32 v53, s99, v130
	v_lshlrev_b32_e32 v54, 16, v131
	v_and_b32_e32 v55, s99, v131
	v_lshlrev_b32_e32 v56, 16, v132
	v_and_b32_e32 v57, s99, v132
	v_lshlrev_b32_e32 v58, 16, v133
	v_and_b32_e32 v59, s99, v133
	v_lshlrev_b32_e32 v60, 16, v134
	v_and_b32_e32 v61, s99, v134
	v_lshlrev_b32_e32 v62, 16, v135
	v_and_b32_e32 v63, s99, v135
	v_add_u32_e32 v10, 67141376, v5
	global_load_dwordx4 v[128:131], v10, s[2:3] offset:-2816
	global_load_dwordx4 v[132:135], v10, s[2:3] offset:2816
	v_pk_fma_f32 v[136:137], v[16:17], v[152:153], v[236:237]
	v_pk_fma_f32 v[196:197], v[24:25], v[212:213], v[244:245]
	v_pk_fma_f32 v[138:139], v[18:19], v[154:155], v[238:239]
	v_pk_fma_f32 v[198:199], v[26:27], v[214:215], v[246:247]
	v_pk_fma_f32 v[140:141], v[20:21], v[156:157], v[240:241]
	v_pk_fma_f32 v[200:201], v[28:29], v[216:217], v[248:249]
	v_pk_fma_f32 v[142:143], v[22:23], v[158:159], v[242:243]
	v_pk_fma_f32 v[202:203], v[30:31], v[218:219], v[250:251]
	v_pk_fma_f32 v[136:137], v[32:33], v[160:161], v[136:137]
	v_pk_fma_f32 v[196:197], v[40:41], v[220:221], v[196:197]
	v_pk_fma_f32 v[138:139], v[34:35], v[162:163], v[138:139]
	v_pk_fma_f32 v[198:199], v[42:43], v[222:223], v[198:199]
	v_pk_fma_f32 v[140:141], v[36:37], v[164:165], v[140:141]
	v_pk_fma_f32 v[200:201], v[44:45], v[224:225], v[200:201]
	v_pk_fma_f32 v[142:143], v[38:39], v[166:167], v[142:143]
	v_pk_fma_f32 v[202:203], v[46:47], v[226:227], v[202:203]
	v_pk_fma_f32 v[136:137], v[48:49], v[168:169], v[136:137]
	v_pk_fma_f32 v[196:197], v[56:57], v[228:229], v[196:197]
	v_pk_fma_f32 v[138:139], v[50:51], v[170:171], v[138:139]
	v_pk_fma_f32 v[198:199], v[58:59], v[230:231], v[198:199]
	v_pk_fma_f32 v[140:141], v[52:53], v[172:173], v[140:141]
	v_pk_fma_f32 v[200:201], v[60:61], v[232:233], v[200:201]
	v_pk_fma_f32 v[142:143], v[54:55], v[174:175], v[142:143]
	v_pk_fma_f32 v[202:203], v[62:63], v[234:235], v[202:203]
	v_pk_mul_f32 v[184:185], v[136:137], v[180:181]
	v_pk_mul_f32 v[186:187], v[138:139], v[180:181]
	v_pk_mul_f32 v[188:189], v[140:141], v[180:181]
	v_pk_mul_f32 v[190:191], v[142:143], v[180:181]
	v_exp_f32_e32 v184, v184
	v_exp_f32_e32 v185, v185
	v_exp_f32_e32 v186, v186
	v_exp_f32_e32 v187, v187
	v_exp_f32_e32 v188, v188
	v_exp_f32_e32 v189, v189
	v_exp_f32_e32 v190, v190
	v_exp_f32_e32 v191, v191
	s_nop 0
	v_pk_add_f32 v[184:185], v[184:185], v[144:145]
	v_pk_add_f32 v[186:187], v[186:187], v[144:145]
	v_pk_add_f32 v[188:189], v[188:189], v[144:145]
	v_pk_add_f32 v[190:191], v[190:191], v[144:145]
	v_rcp_f32_e32 v184, v184
	v_rcp_f32_e32 v185, v185
	v_rcp_f32_e32 v186, v186
	v_rcp_f32_e32 v187, v187
	v_rcp_f32_e32 v188, v188
	v_rcp_f32_e32 v189, v189
	v_rcp_f32_e32 v190, v190
	v_rcp_f32_e32 v191, v191
	s_nop 0
	v_pk_mul_f32 v[136:137], v[136:137], v[184:185]
	v_pk_mul_f32 v[138:139], v[138:139], v[186:187]
	v_pk_mul_f32 v[140:141], v[140:141], v[188:189]
	v_pk_mul_f32 v[142:143], v[142:143], v[190:191]
	v_pk_mul_f32 v[136:137], v[136:137], v[196:197]
	v_pk_mul_f32 v[138:139], v[138:139], v[198:199]
	v_pk_mul_f32 v[140:141], v[140:141], v[200:201]
	v_pk_mul_f32 v[142:143], v[142:143], v[202:203]
	v_cvt_pk_bf16_f32 v12, v136, v137
	v_cvt_pk_bf16_f32 v13, v138, v139
	v_cvt_pk_bf16_f32 v14, v140, v141
	v_cvt_pk_bf16_f32 v15, v142, v143
	global_store_dwordx4 v6, v[12:15], s[30:31]
	v_add_u32_e32 v5, 67043328, v5
	v_add_u32_e32 v6, 33437184, v6
	v_add_u32_e32 v7, 372, v7
	v_add_u32_e32 v2, 372, v2
	s_add_u32 s98, s98, 1
	s_cmp_lt_u32 s98, 6
	s_cbranch_scc1 .Lconv_item_l1
.Lconv_done_l1:
	s_waitcnt vmcnt(0)
	s_barrier
	s_mov_b64 s[2:3], exec
	v_readlane_b32 s12, v254, 0
	v_readlane_b32 s13, v254, 1
	s_and_b64 s[12:13], s[2:3], s[12:13]
	s_mov_b64 exec, s[12:13]
	s_cbranch_execz .LBB0_1158
	v_readlane_b32 s12, v255, 18
	s_waitcnt vmcnt(0) expcnt(0) lgkmcnt(0)
	s_nop 0
	v_mov_b32_e32 v1, s12
	ds_read_b32 v3, v1
	v_readlane_b32 s12, v255, 22
	s_waitcnt lgkmcnt(0)
	v_cmp_ne_u32_e32 vcc, 0, v3
	v_mov_b32_e32 v1, s12
	ds_read_b32 v2, v1
	s_cbranch_vccnz .LBB0_1126
	s_mov_b32 s12, 1
	s_branch .LBB0_1114
